# quadrant tail K-loops rewritten by hand: one super-phase per K-tile, 4-slot LDS staging ring (prefetch 3 K-tiles ahead), vmcnt(8)
# speedup vs baseline: 1.0812x; 1.0074x over previous
.Lq_lin_0_loop:
	s_add_u32 s74, s74, 0x100
	s_addc_u32 s75, s75, 0
	s_add_u32 s2, vcc_lo, 0x0
	s_addc_u32 s3, vcc_hi, 0
	s_waitcnt vmcnt(0)
	s_barrier
	s_barrier
	v_lshl_add_u64 v[142:143], s[74:75], 0, v[132:133]
	s_add_i32 m0, s5, 0x4000
	v_lshl_add_u64 v[160:161], s[74:75], 0, v[130:131]
	global_load_lds_dwordx4 v[142:143], off
	s_add_i32 m0, s5, 0x6000
	v_lshl_add_u64 v[178:179], s[2:3], 0, v[144:145]
	global_load_lds_dwordx4 v[160:161], off
	s_add_i32 m0, s5, 0x14000
	v_lshl_add_u64 v[238:239], s[2:3], 0, v[128:129]
	global_load_lds_dwordx4 v[178:179], off
	s_add_i32 m0, s5, 0x16000
	s_add_u32 s74, s74, 0x80
	s_addc_u32 s75, s75, 0
	global_load_lds_dwordx4 v[238:239], off
	s_add_u32 s2, s2, 0x80
	s_addc_u32 s3, s3, 0
	s_mov_b32 s8, 0
.Lq_lin_0_k:
	v_lshl_add_u64 v[142:143], s[74:75], 0, v[132:133]
	s_add_i32 m0, s5, 0xc000
	v_lshl_add_u64 v[160:161], s[74:75], 0, v[130:131]
	global_load_lds_dwordx4 v[142:143], off
	s_add_i32 m0, s5, 0xe000
	v_lshl_add_u64 v[178:179], s[2:3], 0, v[144:145]
	global_load_lds_dwordx4 v[160:161], off
	s_add_i32 m0, s5, 0x1c000
	v_lshl_add_u64 v[238:239], s[2:3], 0, v[128:129]
	global_load_lds_dwordx4 v[178:179], off
	s_add_i32 m0, s5, 0x1e000
	s_add_u32 s74, s74, 0x80
	s_addc_u32 s75, s75, 0
	global_load_lds_dwordx4 v[238:239], off
	s_add_u32 s2, s2, 0x80
	s_addc_u32 s3, s3, 0
	v_add_u32_e32 v165, 0x10000, v162
	ds_read_b128 v[206:209], v164 offset:0
	ds_read_b128 v[210:213], v164 offset:1024
	ds_read_b128 v[214:217], v164 offset:2048
	ds_read_b128 v[218:221], v164 offset:3072
	ds_read_b128 v[222:225], v164 offset:4096
	ds_read_b128 v[226:229], v164 offset:5120
	ds_read_b128 v[230:233], v164 offset:6144
	ds_read_b128 v[234:237], v164 offset:7168
	ds_read_b128 v[138:141], v165
	ds_read_b128 v[166:169], v165 offset:1024
	ds_read_b128 v[170:173], v165 offset:2048
	ds_read_b128 v[174:177], v165 offset:3072
	s_waitcnt vmcnt(8)
	s_waitcnt lgkmcnt(0)
	s_barrier
	s_setprio 1
	v_mfma_f32_16x16x32_bf16 v[124:127], v[138:141], v[206:209], v[124:127]
	v_mfma_f32_16x16x32_bf16 v[120:123], v[170:173], v[206:209], v[120:123]
	v_mfma_f32_16x16x32_bf16 v[108:111], v[138:141], v[214:217], v[108:111]
	v_mfma_f32_16x16x32_bf16 v[104:107], v[170:173], v[214:217], v[104:107]
	v_mfma_f32_16x16x32_bf16 v[92:95], v[138:141], v[222:225], v[92:95]
	v_mfma_f32_16x16x32_bf16 v[88:91], v[170:173], v[222:225], v[88:91]
	v_mfma_f32_16x16x32_bf16 v[76:79], v[138:141], v[230:233], v[76:79]
	v_mfma_f32_16x16x32_bf16 v[72:75], v[170:173], v[230:233], v[72:75]
	v_mfma_f32_16x16x32_bf16 v[124:127], v[166:169], v[210:213], v[124:127]
	v_mfma_f32_16x16x32_bf16 v[120:123], v[174:177], v[210:213], v[120:123]
	v_mfma_f32_16x16x32_bf16 v[108:111], v[166:169], v[218:221], v[108:111]
	v_mfma_f32_16x16x32_bf16 v[104:107], v[174:177], v[218:221], v[104:107]
	v_mfma_f32_16x16x32_bf16 v[92:95], v[166:169], v[226:229], v[92:95]
	v_mfma_f32_16x16x32_bf16 v[88:91], v[174:177], v[226:229], v[88:91]
	v_mfma_f32_16x16x32_bf16 v[76:79], v[166:169], v[234:237], v[76:79]
	v_mfma_f32_16x16x32_bf16 v[72:75], v[174:177], v[234:237], v[72:75]
	s_setprio 0
	s_barrier
	v_lshl_add_u64 v[142:143], s[74:75], 0, v[132:133]
	s_add_i32 m0, s5, 0x0
	v_lshl_add_u64 v[160:161], s[74:75], 0, v[130:131]
	global_load_lds_dwordx4 v[142:143], off
	s_add_i32 m0, s5, 0x2000
	v_lshl_add_u64 v[178:179], s[2:3], 0, v[144:145]
	global_load_lds_dwordx4 v[160:161], off
	s_add_i32 m0, s5, 0x10000
	v_lshl_add_u64 v[238:239], s[2:3], 0, v[128:129]
	global_load_lds_dwordx4 v[178:179], off
	s_add_i32 m0, s5, 0x12000
	s_add_u32 s74, s74, 0x80
	s_addc_u32 s75, s75, 0
	global_load_lds_dwordx4 v[238:239], off
	s_add_u32 s2, s2, 0x80
	s_addc_u32 s3, s3, 0
	v_add_u32_e32 v165, 0x18000, v162
	ds_read_b128 v[206:209], v164 offset:32768
	ds_read_b128 v[210:213], v164 offset:33792
	ds_read_b128 v[214:217], v164 offset:34816
	ds_read_b128 v[218:221], v164 offset:35840
	ds_read_b128 v[222:225], v164 offset:36864
	ds_read_b128 v[226:229], v164 offset:37888
	ds_read_b128 v[230:233], v164 offset:38912
	ds_read_b128 v[234:237], v164 offset:39936
	ds_read_b128 v[138:141], v165
	ds_read_b128 v[166:169], v165 offset:1024
	ds_read_b128 v[170:173], v165 offset:2048
	ds_read_b128 v[174:177], v165 offset:3072
	s_waitcnt vmcnt(8)
	s_waitcnt lgkmcnt(0)
	s_barrier
	s_setprio 1
	v_mfma_f32_16x16x32_bf16 v[124:127], v[138:141], v[206:209], v[124:127]
	v_mfma_f32_16x16x32_bf16 v[120:123], v[170:173], v[206:209], v[120:123]
	v_mfma_f32_16x16x32_bf16 v[108:111], v[138:141], v[214:217], v[108:111]
	v_mfma_f32_16x16x32_bf16 v[104:107], v[170:173], v[214:217], v[104:107]
	v_mfma_f32_16x16x32_bf16 v[92:95], v[138:141], v[222:225], v[92:95]
	v_mfma_f32_16x16x32_bf16 v[88:91], v[170:173], v[222:225], v[88:91]
	v_mfma_f32_16x16x32_bf16 v[76:79], v[138:141], v[230:233], v[76:79]
	v_mfma_f32_16x16x32_bf16 v[72:75], v[170:173], v[230:233], v[72:75]
	v_mfma_f32_16x16x32_bf16 v[124:127], v[166:169], v[210:213], v[124:127]
	v_mfma_f32_16x16x32_bf16 v[120:123], v[174:177], v[210:213], v[120:123]
	v_mfma_f32_16x16x32_bf16 v[108:111], v[166:169], v[218:221], v[108:111]
	v_mfma_f32_16x16x32_bf16 v[104:107], v[174:177], v[218:221], v[104:107]
	v_mfma_f32_16x16x32_bf16 v[92:95], v[166:169], v[226:229], v[92:95]
	v_mfma_f32_16x16x32_bf16 v[88:91], v[174:177], v[226:229], v[88:91]
	v_mfma_f32_16x16x32_bf16 v[76:79], v[166:169], v[234:237], v[76:79]
	v_mfma_f32_16x16x32_bf16 v[72:75], v[174:177], v[234:237], v[72:75]
	s_setprio 0
	s_barrier
	v_lshl_add_u64 v[142:143], s[74:75], 0, v[132:133]
	s_add_i32 m0, s5, 0x8000
	v_lshl_add_u64 v[160:161], s[74:75], 0, v[130:131]
	global_load_lds_dwordx4 v[142:143], off
	s_add_i32 m0, s5, 0xa000
	v_lshl_add_u64 v[178:179], s[2:3], 0, v[144:145]
	global_load_lds_dwordx4 v[160:161], off
	s_add_i32 m0, s5, 0x18000
	v_lshl_add_u64 v[238:239], s[2:3], 0, v[128:129]
	global_load_lds_dwordx4 v[178:179], off
	s_add_i32 m0, s5, 0x1a000
	s_add_u32 s74, s74, 0x80
	s_addc_u32 s75, s75, 0
	global_load_lds_dwordx4 v[238:239], off
	s_add_u32 s2, s2, 0x80
	s_addc_u32 s3, s3, 0
	v_add_u32_e32 v165, 0x14000, v162
	ds_read_b128 v[206:209], v164 offset:16384
	ds_read_b128 v[210:213], v164 offset:17408
	ds_read_b128 v[214:217], v164 offset:18432
	ds_read_b128 v[218:221], v164 offset:19456
	ds_read_b128 v[222:225], v164 offset:20480
	ds_read_b128 v[226:229], v164 offset:21504
	ds_read_b128 v[230:233], v164 offset:22528
	ds_read_b128 v[234:237], v164 offset:23552
	ds_read_b128 v[138:141], v165
	ds_read_b128 v[166:169], v165 offset:1024
	ds_read_b128 v[170:173], v165 offset:2048
	ds_read_b128 v[174:177], v165 offset:3072
	s_waitcnt vmcnt(8)
	s_waitcnt lgkmcnt(0)
	s_barrier
	s_setprio 1
	v_mfma_f32_16x16x32_bf16 v[124:127], v[138:141], v[206:209], v[124:127]
	v_mfma_f32_16x16x32_bf16 v[120:123], v[170:173], v[206:209], v[120:123]
	v_mfma_f32_16x16x32_bf16 v[108:111], v[138:141], v[214:217], v[108:111]
	v_mfma_f32_16x16x32_bf16 v[104:107], v[170:173], v[214:217], v[104:107]
	v_mfma_f32_16x16x32_bf16 v[92:95], v[138:141], v[222:225], v[92:95]
	v_mfma_f32_16x16x32_bf16 v[88:91], v[170:173], v[222:225], v[88:91]
	v_mfma_f32_16x16x32_bf16 v[76:79], v[138:141], v[230:233], v[76:79]
	v_mfma_f32_16x16x32_bf16 v[72:75], v[170:173], v[230:233], v[72:75]
	v_mfma_f32_16x16x32_bf16 v[124:127], v[166:169], v[210:213], v[124:127]
	v_mfma_f32_16x16x32_bf16 v[120:123], v[174:177], v[210:213], v[120:123]
	v_mfma_f32_16x16x32_bf16 v[108:111], v[166:169], v[218:221], v[108:111]
	v_mfma_f32_16x16x32_bf16 v[104:107], v[174:177], v[218:221], v[104:107]
	v_mfma_f32_16x16x32_bf16 v[92:95], v[166:169], v[226:229], v[92:95]
	v_mfma_f32_16x16x32_bf16 v[88:91], v[174:177], v[226:229], v[88:91]
	v_mfma_f32_16x16x32_bf16 v[76:79], v[166:169], v[234:237], v[76:79]
	v_mfma_f32_16x16x32_bf16 v[72:75], v[174:177], v[234:237], v[72:75]
	s_setprio 0
	s_barrier
	v_lshl_add_u64 v[142:143], s[74:75], 0, v[132:133]
	s_add_i32 m0, s5, 0x4000
	v_lshl_add_u64 v[160:161], s[74:75], 0, v[130:131]
	global_load_lds_dwordx4 v[142:143], off
	s_add_i32 m0, s5, 0x6000
	v_lshl_add_u64 v[178:179], s[2:3], 0, v[144:145]
	global_load_lds_dwordx4 v[160:161], off
	s_add_i32 m0, s5, 0x14000
	v_lshl_add_u64 v[238:239], s[2:3], 0, v[128:129]
	global_load_lds_dwordx4 v[178:179], off
	s_add_i32 m0, s5, 0x16000
	s_add_u32 s74, s74, 0x80
	s_addc_u32 s75, s75, 0
	global_load_lds_dwordx4 v[238:239], off
	s_add_u32 s2, s2, 0x80
	s_addc_u32 s3, s3, 0
	v_add_u32_e32 v165, 0x1c000, v162
	ds_read_b128 v[206:209], v164 offset:49152
	ds_read_b128 v[210:213], v164 offset:50176
	ds_read_b128 v[214:217], v164 offset:51200
	ds_read_b128 v[218:221], v164 offset:52224
	ds_read_b128 v[222:225], v164 offset:53248
	ds_read_b128 v[226:229], v164 offset:54272
	ds_read_b128 v[230:233], v164 offset:55296
	ds_read_b128 v[234:237], v164 offset:56320
	ds_read_b128 v[138:141], v165
	ds_read_b128 v[166:169], v165 offset:1024
	ds_read_b128 v[170:173], v165 offset:2048
	ds_read_b128 v[174:177], v165 offset:3072
	s_waitcnt vmcnt(8)
	s_waitcnt lgkmcnt(0)
	s_barrier
	s_setprio 1
	v_mfma_f32_16x16x32_bf16 v[124:127], v[138:141], v[206:209], v[124:127]
	v_mfma_f32_16x16x32_bf16 v[120:123], v[170:173], v[206:209], v[120:123]
	v_mfma_f32_16x16x32_bf16 v[108:111], v[138:141], v[214:217], v[108:111]
	v_mfma_f32_16x16x32_bf16 v[104:107], v[170:173], v[214:217], v[104:107]
	v_mfma_f32_16x16x32_bf16 v[92:95], v[138:141], v[222:225], v[92:95]
	v_mfma_f32_16x16x32_bf16 v[88:91], v[170:173], v[222:225], v[88:91]
	v_mfma_f32_16x16x32_bf16 v[76:79], v[138:141], v[230:233], v[76:79]
	v_mfma_f32_16x16x32_bf16 v[72:75], v[170:173], v[230:233], v[72:75]
	v_mfma_f32_16x16x32_bf16 v[124:127], v[166:169], v[210:213], v[124:127]
	v_mfma_f32_16x16x32_bf16 v[120:123], v[174:177], v[210:213], v[120:123]
	v_mfma_f32_16x16x32_bf16 v[108:111], v[166:169], v[218:221], v[108:111]
	v_mfma_f32_16x16x32_bf16 v[104:107], v[174:177], v[218:221], v[104:107]
	v_mfma_f32_16x16x32_bf16 v[92:95], v[166:169], v[226:229], v[92:95]
	v_mfma_f32_16x16x32_bf16 v[88:91], v[174:177], v[226:229], v[88:91]
	v_mfma_f32_16x16x32_bf16 v[76:79], v[166:169], v[234:237], v[76:79]
	v_mfma_f32_16x16x32_bf16 v[72:75], v[174:177], v[234:237], v[72:75]
	s_setprio 0
	s_barrier
	s_add_i32 s8, s8, 1
	s_cmp_lt_u32 s8, 7
	s_cbranch_scc1 .Lq_lin_0_k
	v_lshl_add_u64 v[142:143], s[74:75], 0, v[132:133]
	s_add_i32 m0, s5, 0xc000
	v_lshl_add_u64 v[160:161], s[74:75], 0, v[130:131]
	global_load_lds_dwordx4 v[142:143], off
	s_add_i32 m0, s5, 0xe000
	v_lshl_add_u64 v[178:179], s[2:3], 0, v[144:145]
	global_load_lds_dwordx4 v[160:161], off
	s_add_i32 m0, s5, 0x1c000
	v_lshl_add_u64 v[238:239], s[2:3], 0, v[128:129]
	global_load_lds_dwordx4 v[178:179], off
	s_add_i32 m0, s5, 0x1e000
	s_add_u32 s74, s74, 0x80
	s_addc_u32 s75, s75, 0
	global_load_lds_dwordx4 v[238:239], off
	s_add_u32 s2, s2, 0x80
	s_addc_u32 s3, s3, 0
	v_add_u32_e32 v165, 0x10000, v162
	ds_read_b128 v[206:209], v164 offset:0
	ds_read_b128 v[210:213], v164 offset:1024
	ds_read_b128 v[214:217], v164 offset:2048
	ds_read_b128 v[218:221], v164 offset:3072
	ds_read_b128 v[222:225], v164 offset:4096
	ds_read_b128 v[226:229], v164 offset:5120
	ds_read_b128 v[230:233], v164 offset:6144
	ds_read_b128 v[234:237], v164 offset:7168
	ds_read_b128 v[138:141], v165
	ds_read_b128 v[166:169], v165 offset:1024
	ds_read_b128 v[170:173], v165 offset:2048
	ds_read_b128 v[174:177], v165 offset:3072
	s_waitcnt vmcnt(8)
	s_waitcnt lgkmcnt(0)
	s_barrier
	s_setprio 1
	v_mfma_f32_16x16x32_bf16 v[124:127], v[138:141], v[206:209], v[124:127]
	v_mfma_f32_16x16x32_bf16 v[120:123], v[170:173], v[206:209], v[120:123]
	v_mfma_f32_16x16x32_bf16 v[108:111], v[138:141], v[214:217], v[108:111]
	v_mfma_f32_16x16x32_bf16 v[104:107], v[170:173], v[214:217], v[104:107]
	v_mfma_f32_16x16x32_bf16 v[92:95], v[138:141], v[222:225], v[92:95]
	v_mfma_f32_16x16x32_bf16 v[88:91], v[170:173], v[222:225], v[88:91]
	v_mfma_f32_16x16x32_bf16 v[76:79], v[138:141], v[230:233], v[76:79]
	v_mfma_f32_16x16x32_bf16 v[72:75], v[170:173], v[230:233], v[72:75]
	v_mfma_f32_16x16x32_bf16 v[124:127], v[166:169], v[210:213], v[124:127]
	v_mfma_f32_16x16x32_bf16 v[120:123], v[174:177], v[210:213], v[120:123]
	v_mfma_f32_16x16x32_bf16 v[108:111], v[166:169], v[218:221], v[108:111]
	v_mfma_f32_16x16x32_bf16 v[104:107], v[174:177], v[218:221], v[104:107]
	v_mfma_f32_16x16x32_bf16 v[92:95], v[166:169], v[226:229], v[92:95]
	v_mfma_f32_16x16x32_bf16 v[88:91], v[174:177], v[226:229], v[88:91]
	v_mfma_f32_16x16x32_bf16 v[76:79], v[166:169], v[234:237], v[76:79]
	v_mfma_f32_16x16x32_bf16 v[72:75], v[174:177], v[234:237], v[72:75]
	s_setprio 0
	s_barrier
	v_add_u32_e32 v165, 0x18000, v162
	ds_read_b128 v[206:209], v164 offset:32768
	ds_read_b128 v[210:213], v164 offset:33792
	ds_read_b128 v[214:217], v164 offset:34816
	ds_read_b128 v[218:221], v164 offset:35840
	ds_read_b128 v[222:225], v164 offset:36864
	ds_read_b128 v[226:229], v164 offset:37888
	ds_read_b128 v[230:233], v164 offset:38912
	ds_read_b128 v[234:237], v164 offset:39936
	ds_read_b128 v[138:141], v165
	ds_read_b128 v[166:169], v165 offset:1024
	ds_read_b128 v[170:173], v165 offset:2048
	ds_read_b128 v[174:177], v165 offset:3072
	s_waitcnt vmcnt(4)
	s_waitcnt lgkmcnt(0)
	s_barrier
	s_setprio 1
	v_mfma_f32_16x16x32_bf16 v[124:127], v[138:141], v[206:209], v[124:127]
	v_mfma_f32_16x16x32_bf16 v[120:123], v[170:173], v[206:209], v[120:123]
	v_mfma_f32_16x16x32_bf16 v[108:111], v[138:141], v[214:217], v[108:111]
	v_mfma_f32_16x16x32_bf16 v[104:107], v[170:173], v[214:217], v[104:107]
	v_mfma_f32_16x16x32_bf16 v[92:95], v[138:141], v[222:225], v[92:95]
	v_mfma_f32_16x16x32_bf16 v[88:91], v[170:173], v[222:225], v[88:91]
	v_mfma_f32_16x16x32_bf16 v[76:79], v[138:141], v[230:233], v[76:79]
	v_mfma_f32_16x16x32_bf16 v[72:75], v[170:173], v[230:233], v[72:75]
	v_mfma_f32_16x16x32_bf16 v[124:127], v[166:169], v[210:213], v[124:127]
	v_mfma_f32_16x16x32_bf16 v[120:123], v[174:177], v[210:213], v[120:123]
	v_mfma_f32_16x16x32_bf16 v[108:111], v[166:169], v[218:221], v[108:111]
	v_mfma_f32_16x16x32_bf16 v[104:107], v[174:177], v[218:221], v[104:107]
	v_mfma_f32_16x16x32_bf16 v[92:95], v[166:169], v[226:229], v[92:95]
	v_mfma_f32_16x16x32_bf16 v[88:91], v[174:177], v[226:229], v[88:91]
	v_mfma_f32_16x16x32_bf16 v[76:79], v[166:169], v[234:237], v[76:79]
	v_mfma_f32_16x16x32_bf16 v[72:75], v[174:177], v[234:237], v[72:75]
	s_setprio 0
	s_barrier
	v_add_u32_e32 v165, 0x14000, v162
	ds_read_b128 v[206:209], v164 offset:16384
	ds_read_b128 v[210:213], v164 offset:17408
	ds_read_b128 v[214:217], v164 offset:18432
	ds_read_b128 v[218:221], v164 offset:19456
	ds_read_b128 v[222:225], v164 offset:20480
	ds_read_b128 v[226:229], v164 offset:21504
	ds_read_b128 v[230:233], v164 offset:22528
	ds_read_b128 v[234:237], v164 offset:23552
	ds_read_b128 v[138:141], v165
	ds_read_b128 v[166:169], v165 offset:1024
	ds_read_b128 v[170:173], v165 offset:2048
	ds_read_b128 v[174:177], v165 offset:3072
	s_waitcnt vmcnt(0)
	s_waitcnt lgkmcnt(0)
	s_barrier
	s_setprio 1
	v_mfma_f32_16x16x32_bf16 v[124:127], v[138:141], v[206:209], v[124:127]
	v_mfma_f32_16x16x32_bf16 v[120:123], v[170:173], v[206:209], v[120:123]
	v_mfma_f32_16x16x32_bf16 v[108:111], v[138:141], v[214:217], v[108:111]
	v_mfma_f32_16x16x32_bf16 v[104:107], v[170:173], v[214:217], v[104:107]
	v_mfma_f32_16x16x32_bf16 v[92:95], v[138:141], v[222:225], v[92:95]
	v_mfma_f32_16x16x32_bf16 v[88:91], v[170:173], v[222:225], v[88:91]
	v_mfma_f32_16x16x32_bf16 v[76:79], v[138:141], v[230:233], v[76:79]
	v_mfma_f32_16x16x32_bf16 v[72:75], v[170:173], v[230:233], v[72:75]
	v_mfma_f32_16x16x32_bf16 v[124:127], v[166:169], v[210:213], v[124:127]
	v_mfma_f32_16x16x32_bf16 v[120:123], v[174:177], v[210:213], v[120:123]
	v_mfma_f32_16x16x32_bf16 v[108:111], v[166:169], v[218:221], v[108:111]
	v_mfma_f32_16x16x32_bf16 v[104:107], v[174:177], v[218:221], v[104:107]
	v_mfma_f32_16x16x32_bf16 v[92:95], v[166:169], v[226:229], v[92:95]
	v_mfma_f32_16x16x32_bf16 v[88:91], v[174:177], v[226:229], v[88:91]
	v_mfma_f32_16x16x32_bf16 v[76:79], v[166:169], v[234:237], v[76:79]
	v_mfma_f32_16x16x32_bf16 v[72:75], v[174:177], v[234:237], v[72:75]
	s_setprio 0
	s_barrier
	v_add_u32_e32 v165, 0x1c000, v162
	ds_read_b128 v[206:209], v164 offset:49152
	ds_read_b128 v[210:213], v164 offset:50176
	ds_read_b128 v[214:217], v164 offset:51200
	ds_read_b128 v[218:221], v164 offset:52224
	ds_read_b128 v[222:225], v164 offset:53248
	ds_read_b128 v[226:229], v164 offset:54272
	ds_read_b128 v[230:233], v164 offset:55296
	ds_read_b128 v[234:237], v164 offset:56320
	ds_read_b128 v[138:141], v165
	ds_read_b128 v[166:169], v165 offset:1024
	ds_read_b128 v[170:173], v165 offset:2048
	ds_read_b128 v[174:177], v165 offset:3072
	s_waitcnt lgkmcnt(0)
	s_barrier
	s_setprio 1
	v_mfma_f32_16x16x32_bf16 v[124:127], v[138:141], v[206:209], v[124:127]
	v_mfma_f32_16x16x32_bf16 v[120:123], v[170:173], v[206:209], v[120:123]
	v_mfma_f32_16x16x32_bf16 v[108:111], v[138:141], v[214:217], v[108:111]
	v_mfma_f32_16x16x32_bf16 v[104:107], v[170:173], v[214:217], v[104:107]
	v_mfma_f32_16x16x32_bf16 v[92:95], v[138:141], v[222:225], v[92:95]
	v_mfma_f32_16x16x32_bf16 v[88:91], v[170:173], v[222:225], v[88:91]
	v_mfma_f32_16x16x32_bf16 v[76:79], v[138:141], v[230:233], v[76:79]
	v_mfma_f32_16x16x32_bf16 v[72:75], v[170:173], v[230:233], v[72:75]
	v_mfma_f32_16x16x32_bf16 v[124:127], v[166:169], v[210:213], v[124:127]
	v_mfma_f32_16x16x32_bf16 v[120:123], v[174:177], v[210:213], v[120:123]
	v_mfma_f32_16x16x32_bf16 v[108:111], v[166:169], v[218:221], v[108:111]
	v_mfma_f32_16x16x32_bf16 v[104:107], v[174:177], v[218:221], v[104:107]
	v_mfma_f32_16x16x32_bf16 v[92:95], v[166:169], v[226:229], v[92:95]
	v_mfma_f32_16x16x32_bf16 v[88:91], v[174:177], v[226:229], v[88:91]
	v_mfma_f32_16x16x32_bf16 v[76:79], v[166:169], v[234:237], v[76:79]
	v_mfma_f32_16x16x32_bf16 v[72:75], v[174:177], v[234:237], v[72:75]
	s_setprio 0
	s_barrier
	s_branch .Lq_lin_exit
.Lq_lin_1_loop:
	s_add_u32 s74, s74, 0x100
	s_addc_u32 s75, s75, 0
	s_add_u32 s2, vcc_lo, 0x80000
	s_addc_u32 s3, vcc_hi, 0
	s_waitcnt vmcnt(0)
	s_barrier
	s_barrier
	v_lshl_add_u64 v[142:143], s[74:75], 0, v[132:133]
	s_add_i32 m0, s5, 0x4000
	v_lshl_add_u64 v[160:161], s[74:75], 0, v[130:131]
	global_load_lds_dwordx4 v[142:143], off
	s_add_i32 m0, s5, 0x6000
	v_lshl_add_u64 v[178:179], s[2:3], 0, v[144:145]
	global_load_lds_dwordx4 v[160:161], off
	s_add_i32 m0, s5, 0x10000
	v_lshl_add_u64 v[238:239], s[2:3], 0, v[128:129]
	global_load_lds_dwordx4 v[178:179], off
	s_add_i32 m0, s5, 0x12000
	s_add_u32 s74, s74, 0x80
	s_addc_u32 s75, s75, 0
	global_load_lds_dwordx4 v[238:239], off
	s_add_u32 s2, s2, 0x80
	s_addc_u32 s3, s3, 0
	s_mov_b32 s8, 0
.Lq_lin_1_k:
	v_lshl_add_u64 v[142:143], s[74:75], 0, v[132:133]
	s_add_i32 m0, s5, 0xc000
	v_lshl_add_u64 v[160:161], s[74:75], 0, v[130:131]
	global_load_lds_dwordx4 v[142:143], off
	s_add_i32 m0, s5, 0xe000
	v_lshl_add_u64 v[178:179], s[2:3], 0, v[144:145]
	global_load_lds_dwordx4 v[160:161], off
	s_add_i32 m0, s5, 0x18000
	v_lshl_add_u64 v[238:239], s[2:3], 0, v[128:129]
	global_load_lds_dwordx4 v[178:179], off
	s_add_i32 m0, s5, 0x1a000
	s_add_u32 s74, s74, 0x80
	s_addc_u32 s75, s75, 0
	global_load_lds_dwordx4 v[238:239], off
	s_add_u32 s2, s2, 0x80
	s_addc_u32 s3, s3, 0
	v_add_u32_e32 v165, 0x14000, v162
	ds_read_b128 v[206:209], v164 offset:0
	ds_read_b128 v[210:213], v164 offset:1024
	ds_read_b128 v[214:217], v164 offset:2048
	ds_read_b128 v[218:221], v164 offset:3072
	ds_read_b128 v[222:225], v164 offset:4096
	ds_read_b128 v[226:229], v164 offset:5120
	ds_read_b128 v[230:233], v164 offset:6144
	ds_read_b128 v[234:237], v164 offset:7168
	ds_read_b128 v[190:193], v165
	ds_read_b128 v[194:197], v165 offset:1024
	ds_read_b128 v[198:201], v165 offset:2048
	ds_read_b128 v[202:205], v165 offset:3072
	s_waitcnt vmcnt(8)
	s_waitcnt lgkmcnt(0)
	s_barrier
	s_setprio 1
	v_mfma_f32_16x16x32_bf16 v[116:119], v[190:193], v[206:209], v[116:119]
	v_mfma_f32_16x16x32_bf16 v[112:115], v[198:201], v[206:209], v[112:115]
	v_mfma_f32_16x16x32_bf16 v[100:103], v[190:193], v[214:217], v[100:103]
	v_mfma_f32_16x16x32_bf16 v[96:99], v[198:201], v[214:217], v[96:99]
	v_mfma_f32_16x16x32_bf16 v[84:87], v[190:193], v[222:225], v[84:87]
	v_mfma_f32_16x16x32_bf16 v[80:83], v[198:201], v[222:225], v[80:83]
	v_mfma_f32_16x16x32_bf16 v[68:71], v[190:193], v[230:233], v[68:71]
	v_mfma_f32_16x16x32_bf16 v[64:67], v[198:201], v[230:233], v[64:67]
	v_mfma_f32_16x16x32_bf16 v[116:119], v[194:197], v[210:213], v[116:119]
	v_mfma_f32_16x16x32_bf16 v[112:115], v[202:205], v[210:213], v[112:115]
	v_mfma_f32_16x16x32_bf16 v[100:103], v[194:197], v[218:221], v[100:103]
	v_mfma_f32_16x16x32_bf16 v[96:99], v[202:205], v[218:221], v[96:99]
	v_mfma_f32_16x16x32_bf16 v[84:87], v[194:197], v[226:229], v[84:87]
	v_mfma_f32_16x16x32_bf16 v[80:83], v[202:205], v[226:229], v[80:83]
	v_mfma_f32_16x16x32_bf16 v[68:71], v[194:197], v[234:237], v[68:71]
	v_mfma_f32_16x16x32_bf16 v[64:67], v[202:205], v[234:237], v[64:67]
	s_setprio 0
	s_barrier
	v_lshl_add_u64 v[142:143], s[74:75], 0, v[132:133]
	s_add_i32 m0, s5, 0x0
	v_lshl_add_u64 v[160:161], s[74:75], 0, v[130:131]
	global_load_lds_dwordx4 v[142:143], off
	s_add_i32 m0, s5, 0x2000
	v_lshl_add_u64 v[178:179], s[2:3], 0, v[144:145]
	global_load_lds_dwordx4 v[160:161], off
	s_add_i32 m0, s5, 0x14000
	v_lshl_add_u64 v[238:239], s[2:3], 0, v[128:129]
	global_load_lds_dwordx4 v[178:179], off
	s_add_i32 m0, s5, 0x16000
	s_add_u32 s74, s74, 0x80
	s_addc_u32 s75, s75, 0
	global_load_lds_dwordx4 v[238:239], off
	s_add_u32 s2, s2, 0x80
	s_addc_u32 s3, s3, 0
	v_add_u32_e32 v165, 0x1c000, v162
	ds_read_b128 v[206:209], v164 offset:32768
	ds_read_b128 v[210:213], v164 offset:33792
	ds_read_b128 v[214:217], v164 offset:34816
	ds_read_b128 v[218:221], v164 offset:35840
	ds_read_b128 v[222:225], v164 offset:36864
	ds_read_b128 v[226:229], v164 offset:37888
	ds_read_b128 v[230:233], v164 offset:38912
	ds_read_b128 v[234:237], v164 offset:39936
	ds_read_b128 v[190:193], v165
	ds_read_b128 v[194:197], v165 offset:1024
	ds_read_b128 v[198:201], v165 offset:2048
	ds_read_b128 v[202:205], v165 offset:3072
	s_waitcnt vmcnt(8)
	s_waitcnt lgkmcnt(0)
	s_barrier
	s_setprio 1
	v_mfma_f32_16x16x32_bf16 v[116:119], v[190:193], v[206:209], v[116:119]
	v_mfma_f32_16x16x32_bf16 v[112:115], v[198:201], v[206:209], v[112:115]
	v_mfma_f32_16x16x32_bf16 v[100:103], v[190:193], v[214:217], v[100:103]
	v_mfma_f32_16x16x32_bf16 v[96:99], v[198:201], v[214:217], v[96:99]
	v_mfma_f32_16x16x32_bf16 v[84:87], v[190:193], v[222:225], v[84:87]
	v_mfma_f32_16x16x32_bf16 v[80:83], v[198:201], v[222:225], v[80:83]
	v_mfma_f32_16x16x32_bf16 v[68:71], v[190:193], v[230:233], v[68:71]
	v_mfma_f32_16x16x32_bf16 v[64:67], v[198:201], v[230:233], v[64:67]
	v_mfma_f32_16x16x32_bf16 v[116:119], v[194:197], v[210:213], v[116:119]
	v_mfma_f32_16x16x32_bf16 v[112:115], v[202:205], v[210:213], v[112:115]
	v_mfma_f32_16x16x32_bf16 v[100:103], v[194:197], v[218:221], v[100:103]
	v_mfma_f32_16x16x32_bf16 v[96:99], v[202:205], v[218:221], v[96:99]
	v_mfma_f32_16x16x32_bf16 v[84:87], v[194:197], v[226:229], v[84:87]
	v_mfma_f32_16x16x32_bf16 v[80:83], v[202:205], v[226:229], v[80:83]
	v_mfma_f32_16x16x32_bf16 v[68:71], v[194:197], v[234:237], v[68:71]
	v_mfma_f32_16x16x32_bf16 v[64:67], v[202:205], v[234:237], v[64:67]
	s_setprio 0
	s_barrier
	v_lshl_add_u64 v[142:143], s[74:75], 0, v[132:133]
	s_add_i32 m0, s5, 0x8000
	v_lshl_add_u64 v[160:161], s[74:75], 0, v[130:131]
	global_load_lds_dwordx4 v[142:143], off
	s_add_i32 m0, s5, 0xa000
	v_lshl_add_u64 v[178:179], s[2:3], 0, v[144:145]
	global_load_lds_dwordx4 v[160:161], off
	s_add_i32 m0, s5, 0x1c000
	v_lshl_add_u64 v[238:239], s[2:3], 0, v[128:129]
	global_load_lds_dwordx4 v[178:179], off
	s_add_i32 m0, s5, 0x1e000
	s_add_u32 s74, s74, 0x80
	s_addc_u32 s75, s75, 0
	global_load_lds_dwordx4 v[238:239], off
	s_add_u32 s2, s2, 0x80
	s_addc_u32 s3, s3, 0
	v_add_u32_e32 v165, 0x10000, v162
	ds_read_b128 v[206:209], v164 offset:16384
	ds_read_b128 v[210:213], v164 offset:17408
	ds_read_b128 v[214:217], v164 offset:18432
	ds_read_b128 v[218:221], v164 offset:19456
	ds_read_b128 v[222:225], v164 offset:20480
	ds_read_b128 v[226:229], v164 offset:21504
	ds_read_b128 v[230:233], v164 offset:22528
	ds_read_b128 v[234:237], v164 offset:23552
	ds_read_b128 v[190:193], v165
	ds_read_b128 v[194:197], v165 offset:1024
	ds_read_b128 v[198:201], v165 offset:2048
	ds_read_b128 v[202:205], v165 offset:3072
	s_waitcnt vmcnt(8)
	s_waitcnt lgkmcnt(0)
	s_barrier
	s_setprio 1
	v_mfma_f32_16x16x32_bf16 v[116:119], v[190:193], v[206:209], v[116:119]
	v_mfma_f32_16x16x32_bf16 v[112:115], v[198:201], v[206:209], v[112:115]
	v_mfma_f32_16x16x32_bf16 v[100:103], v[190:193], v[214:217], v[100:103]
	v_mfma_f32_16x16x32_bf16 v[96:99], v[198:201], v[214:217], v[96:99]
	v_mfma_f32_16x16x32_bf16 v[84:87], v[190:193], v[222:225], v[84:87]
	v_mfma_f32_16x16x32_bf16 v[80:83], v[198:201], v[222:225], v[80:83]
	v_mfma_f32_16x16x32_bf16 v[68:71], v[190:193], v[230:233], v[68:71]
	v_mfma_f32_16x16x32_bf16 v[64:67], v[198:201], v[230:233], v[64:67]
	v_mfma_f32_16x16x32_bf16 v[116:119], v[194:197], v[210:213], v[116:119]
	v_mfma_f32_16x16x32_bf16 v[112:115], v[202:205], v[210:213], v[112:115]
	v_mfma_f32_16x16x32_bf16 v[100:103], v[194:197], v[218:221], v[100:103]
	v_mfma_f32_16x16x32_bf16 v[96:99], v[202:205], v[218:221], v[96:99]
	v_mfma_f32_16x16x32_bf16 v[84:87], v[194:197], v[226:229], v[84:87]
	v_mfma_f32_16x16x32_bf16 v[80:83], v[202:205], v[226:229], v[80:83]
	v_mfma_f32_16x16x32_bf16 v[68:71], v[194:197], v[234:237], v[68:71]
	v_mfma_f32_16x16x32_bf16 v[64:67], v[202:205], v[234:237], v[64:67]
	s_setprio 0
	s_barrier
	v_lshl_add_u64 v[142:143], s[74:75], 0, v[132:133]
	s_add_i32 m0, s5, 0x4000
	v_lshl_add_u64 v[160:161], s[74:75], 0, v[130:131]
	global_load_lds_dwordx4 v[142:143], off
	s_add_i32 m0, s5, 0x6000
	v_lshl_add_u64 v[178:179], s[2:3], 0, v[144:145]
	global_load_lds_dwordx4 v[160:161], off
	s_add_i32 m0, s5, 0x10000
	v_lshl_add_u64 v[238:239], s[2:3], 0, v[128:129]
	global_load_lds_dwordx4 v[178:179], off
	s_add_i32 m0, s5, 0x12000
	s_add_u32 s74, s74, 0x80
	s_addc_u32 s75, s75, 0
	global_load_lds_dwordx4 v[238:239], off
	s_add_u32 s2, s2, 0x80
	s_addc_u32 s3, s3, 0
	v_add_u32_e32 v165, 0x18000, v162
	ds_read_b128 v[206:209], v164 offset:49152
	ds_read_b128 v[210:213], v164 offset:50176
	ds_read_b128 v[214:217], v164 offset:51200
	ds_read_b128 v[218:221], v164 offset:52224
	ds_read_b128 v[222:225], v164 offset:53248
	ds_read_b128 v[226:229], v164 offset:54272
	ds_read_b128 v[230:233], v164 offset:55296
	ds_read_b128 v[234:237], v164 offset:56320
	ds_read_b128 v[190:193], v165
	ds_read_b128 v[194:197], v165 offset:1024
	ds_read_b128 v[198:201], v165 offset:2048
	ds_read_b128 v[202:205], v165 offset:3072
	s_waitcnt vmcnt(8)
	s_waitcnt lgkmcnt(0)
	s_barrier
	s_setprio 1
	v_mfma_f32_16x16x32_bf16 v[116:119], v[190:193], v[206:209], v[116:119]
	v_mfma_f32_16x16x32_bf16 v[112:115], v[198:201], v[206:209], v[112:115]
	v_mfma_f32_16x16x32_bf16 v[100:103], v[190:193], v[214:217], v[100:103]
	v_mfma_f32_16x16x32_bf16 v[96:99], v[198:201], v[214:217], v[96:99]
	v_mfma_f32_16x16x32_bf16 v[84:87], v[190:193], v[222:225], v[84:87]
	v_mfma_f32_16x16x32_bf16 v[80:83], v[198:201], v[222:225], v[80:83]
	v_mfma_f32_16x16x32_bf16 v[68:71], v[190:193], v[230:233], v[68:71]
	v_mfma_f32_16x16x32_bf16 v[64:67], v[198:201], v[230:233], v[64:67]
	v_mfma_f32_16x16x32_bf16 v[116:119], v[194:197], v[210:213], v[116:119]
	v_mfma_f32_16x16x32_bf16 v[112:115], v[202:205], v[210:213], v[112:115]
	v_mfma_f32_16x16x32_bf16 v[100:103], v[194:197], v[218:221], v[100:103]
	v_mfma_f32_16x16x32_bf16 v[96:99], v[202:205], v[218:221], v[96:99]
	v_mfma_f32_16x16x32_bf16 v[84:87], v[194:197], v[226:229], v[84:87]
	v_mfma_f32_16x16x32_bf16 v[80:83], v[202:205], v[226:229], v[80:83]
	v_mfma_f32_16x16x32_bf16 v[68:71], v[194:197], v[234:237], v[68:71]
	v_mfma_f32_16x16x32_bf16 v[64:67], v[202:205], v[234:237], v[64:67]
	s_setprio 0
	s_barrier
	s_add_i32 s8, s8, 1
	s_cmp_lt_u32 s8, 7
	s_cbranch_scc1 .Lq_lin_1_k
	v_lshl_add_u64 v[142:143], s[74:75], 0, v[132:133]
	s_add_i32 m0, s5, 0xc000
	v_lshl_add_u64 v[160:161], s[74:75], 0, v[130:131]
	global_load_lds_dwordx4 v[142:143], off
	s_add_i32 m0, s5, 0xe000
	v_lshl_add_u64 v[178:179], s[2:3], 0, v[144:145]
	global_load_lds_dwordx4 v[160:161], off
	s_add_i32 m0, s5, 0x18000
	v_lshl_add_u64 v[238:239], s[2:3], 0, v[128:129]
	global_load_lds_dwordx4 v[178:179], off
	s_add_i32 m0, s5, 0x1a000
	s_add_u32 s74, s74, 0x80
	s_addc_u32 s75, s75, 0
	global_load_lds_dwordx4 v[238:239], off
	s_add_u32 s2, s2, 0x80
	s_addc_u32 s3, s3, 0
	v_add_u32_e32 v165, 0x14000, v162
	ds_read_b128 v[206:209], v164 offset:0
	ds_read_b128 v[210:213], v164 offset:1024
	ds_read_b128 v[214:217], v164 offset:2048
	ds_read_b128 v[218:221], v164 offset:3072
	ds_read_b128 v[222:225], v164 offset:4096
	ds_read_b128 v[226:229], v164 offset:5120
	ds_read_b128 v[230:233], v164 offset:6144
	ds_read_b128 v[234:237], v164 offset:7168
	ds_read_b128 v[190:193], v165
	ds_read_b128 v[194:197], v165 offset:1024
	ds_read_b128 v[198:201], v165 offset:2048
	ds_read_b128 v[202:205], v165 offset:3072
	s_waitcnt vmcnt(8)
	s_waitcnt lgkmcnt(0)
	s_barrier
	s_setprio 1
	v_mfma_f32_16x16x32_bf16 v[116:119], v[190:193], v[206:209], v[116:119]
	v_mfma_f32_16x16x32_bf16 v[112:115], v[198:201], v[206:209], v[112:115]
	v_mfma_f32_16x16x32_bf16 v[100:103], v[190:193], v[214:217], v[100:103]
	v_mfma_f32_16x16x32_bf16 v[96:99], v[198:201], v[214:217], v[96:99]
	v_mfma_f32_16x16x32_bf16 v[84:87], v[190:193], v[222:225], v[84:87]
	v_mfma_f32_16x16x32_bf16 v[80:83], v[198:201], v[222:225], v[80:83]
	v_mfma_f32_16x16x32_bf16 v[68:71], v[190:193], v[230:233], v[68:71]
	v_mfma_f32_16x16x32_bf16 v[64:67], v[198:201], v[230:233], v[64:67]
	v_mfma_f32_16x16x32_bf16 v[116:119], v[194:197], v[210:213], v[116:119]
	v_mfma_f32_16x16x32_bf16 v[112:115], v[202:205], v[210:213], v[112:115]
	v_mfma_f32_16x16x32_bf16 v[100:103], v[194:197], v[218:221], v[100:103]
	v_mfma_f32_16x16x32_bf16 v[96:99], v[202:205], v[218:221], v[96:99]
	v_mfma_f32_16x16x32_bf16 v[84:87], v[194:197], v[226:229], v[84:87]
	v_mfma_f32_16x16x32_bf16 v[80:83], v[202:205], v[226:229], v[80:83]
	v_mfma_f32_16x16x32_bf16 v[68:71], v[194:197], v[234:237], v[68:71]
	v_mfma_f32_16x16x32_bf16 v[64:67], v[202:205], v[234:237], v[64:67]
	s_setprio 0
	s_barrier
	v_add_u32_e32 v165, 0x1c000, v162
	ds_read_b128 v[206:209], v164 offset:32768
	ds_read_b128 v[210:213], v164 offset:33792
	ds_read_b128 v[214:217], v164 offset:34816
	ds_read_b128 v[218:221], v164 offset:35840
	ds_read_b128 v[222:225], v164 offset:36864
	ds_read_b128 v[226:229], v164 offset:37888
	ds_read_b128 v[230:233], v164 offset:38912
	ds_read_b128 v[234:237], v164 offset:39936
	ds_read_b128 v[190:193], v165
	ds_read_b128 v[194:197], v165 offset:1024
	ds_read_b128 v[198:201], v165 offset:2048
	ds_read_b128 v[202:205], v165 offset:3072
	s_waitcnt vmcnt(4)
	s_waitcnt lgkmcnt(0)
	s_barrier
	s_setprio 1
	v_mfma_f32_16x16x32_bf16 v[116:119], v[190:193], v[206:209], v[116:119]
	v_mfma_f32_16x16x32_bf16 v[112:115], v[198:201], v[206:209], v[112:115]
	v_mfma_f32_16x16x32_bf16 v[100:103], v[190:193], v[214:217], v[100:103]
	v_mfma_f32_16x16x32_bf16 v[96:99], v[198:201], v[214:217], v[96:99]
	v_mfma_f32_16x16x32_bf16 v[84:87], v[190:193], v[222:225], v[84:87]
	v_mfma_f32_16x16x32_bf16 v[80:83], v[198:201], v[222:225], v[80:83]
	v_mfma_f32_16x16x32_bf16 v[68:71], v[190:193], v[230:233], v[68:71]
	v_mfma_f32_16x16x32_bf16 v[64:67], v[198:201], v[230:233], v[64:67]
	v_mfma_f32_16x16x32_bf16 v[116:119], v[194:197], v[210:213], v[116:119]
	v_mfma_f32_16x16x32_bf16 v[112:115], v[202:205], v[210:213], v[112:115]
	v_mfma_f32_16x16x32_bf16 v[100:103], v[194:197], v[218:221], v[100:103]
	v_mfma_f32_16x16x32_bf16 v[96:99], v[202:205], v[218:221], v[96:99]
	v_mfma_f32_16x16x32_bf16 v[84:87], v[194:197], v[226:229], v[84:87]
	v_mfma_f32_16x16x32_bf16 v[80:83], v[202:205], v[226:229], v[80:83]
	v_mfma_f32_16x16x32_bf16 v[68:71], v[194:197], v[234:237], v[68:71]
	v_mfma_f32_16x16x32_bf16 v[64:67], v[202:205], v[234:237], v[64:67]
	s_setprio 0
	s_barrier
	v_add_u32_e32 v165, 0x10000, v162
	ds_read_b128 v[206:209], v164 offset:16384
	ds_read_b128 v[210:213], v164 offset:17408
	ds_read_b128 v[214:217], v164 offset:18432
	ds_read_b128 v[218:221], v164 offset:19456
	ds_read_b128 v[222:225], v164 offset:20480
	ds_read_b128 v[226:229], v164 offset:21504
	ds_read_b128 v[230:233], v164 offset:22528
	ds_read_b128 v[234:237], v164 offset:23552
	ds_read_b128 v[190:193], v165
	ds_read_b128 v[194:197], v165 offset:1024
	ds_read_b128 v[198:201], v165 offset:2048
	ds_read_b128 v[202:205], v165 offset:3072
	s_waitcnt vmcnt(0)
	s_waitcnt lgkmcnt(0)
	s_barrier
	s_setprio 1
	v_mfma_f32_16x16x32_bf16 v[116:119], v[190:193], v[206:209], v[116:119]
	v_mfma_f32_16x16x32_bf16 v[112:115], v[198:201], v[206:209], v[112:115]
	v_mfma_f32_16x16x32_bf16 v[100:103], v[190:193], v[214:217], v[100:103]
	v_mfma_f32_16x16x32_bf16 v[96:99], v[198:201], v[214:217], v[96:99]
	v_mfma_f32_16x16x32_bf16 v[84:87], v[190:193], v[222:225], v[84:87]
	v_mfma_f32_16x16x32_bf16 v[80:83], v[198:201], v[222:225], v[80:83]
	v_mfma_f32_16x16x32_bf16 v[68:71], v[190:193], v[230:233], v[68:71]
	v_mfma_f32_16x16x32_bf16 v[64:67], v[198:201], v[230:233], v[64:67]
	v_mfma_f32_16x16x32_bf16 v[116:119], v[194:197], v[210:213], v[116:119]
	v_mfma_f32_16x16x32_bf16 v[112:115], v[202:205], v[210:213], v[112:115]
	v_mfma_f32_16x16x32_bf16 v[100:103], v[194:197], v[218:221], v[100:103]
	v_mfma_f32_16x16x32_bf16 v[96:99], v[202:205], v[218:221], v[96:99]
	v_mfma_f32_16x16x32_bf16 v[84:87], v[194:197], v[226:229], v[84:87]
	v_mfma_f32_16x16x32_bf16 v[80:83], v[202:205], v[226:229], v[80:83]
	v_mfma_f32_16x16x32_bf16 v[68:71], v[194:197], v[234:237], v[68:71]
	v_mfma_f32_16x16x32_bf16 v[64:67], v[202:205], v[234:237], v[64:67]
	s_setprio 0
	s_barrier
	v_add_u32_e32 v165, 0x18000, v162
	ds_read_b128 v[206:209], v164 offset:49152
	ds_read_b128 v[210:213], v164 offset:50176
	ds_read_b128 v[214:217], v164 offset:51200
	ds_read_b128 v[218:221], v164 offset:52224
	ds_read_b128 v[222:225], v164 offset:53248
	ds_read_b128 v[226:229], v164 offset:54272
	ds_read_b128 v[230:233], v164 offset:55296
	ds_read_b128 v[234:237], v164 offset:56320
	ds_read_b128 v[190:193], v165
	ds_read_b128 v[194:197], v165 offset:1024
	ds_read_b128 v[198:201], v165 offset:2048
	ds_read_b128 v[202:205], v165 offset:3072
	s_waitcnt lgkmcnt(0)
	s_barrier
	s_setprio 1
	v_mfma_f32_16x16x32_bf16 v[116:119], v[190:193], v[206:209], v[116:119]
	v_mfma_f32_16x16x32_bf16 v[112:115], v[198:201], v[206:209], v[112:115]
	v_mfma_f32_16x16x32_bf16 v[100:103], v[190:193], v[214:217], v[100:103]
	v_mfma_f32_16x16x32_bf16 v[96:99], v[198:201], v[214:217], v[96:99]
	v_mfma_f32_16x16x32_bf16 v[84:87], v[190:193], v[222:225], v[84:87]
	v_mfma_f32_16x16x32_bf16 v[80:83], v[198:201], v[222:225], v[80:83]
	v_mfma_f32_16x16x32_bf16 v[68:71], v[190:193], v[230:233], v[68:71]
	v_mfma_f32_16x16x32_bf16 v[64:67], v[198:201], v[230:233], v[64:67]
	v_mfma_f32_16x16x32_bf16 v[116:119], v[194:197], v[210:213], v[116:119]
	v_mfma_f32_16x16x32_bf16 v[112:115], v[202:205], v[210:213], v[112:115]
	v_mfma_f32_16x16x32_bf16 v[100:103], v[194:197], v[218:221], v[100:103]
	v_mfma_f32_16x16x32_bf16 v[96:99], v[202:205], v[218:221], v[96:99]
	v_mfma_f32_16x16x32_bf16 v[84:87], v[194:197], v[226:229], v[84:87]
	v_mfma_f32_16x16x32_bf16 v[80:83], v[202:205], v[226:229], v[80:83]
	v_mfma_f32_16x16x32_bf16 v[68:71], v[194:197], v[234:237], v[68:71]
	v_mfma_f32_16x16x32_bf16 v[64:67], v[202:205], v[234:237], v[64:67]
	s_setprio 0
	s_barrier
	s_branch .Lq_lin_exit
.Lq_lin_2_loop:
	s_add_u32 s74, s74, 0x80080
	s_addc_u32 s75, s75, 0
	s_add_u32 s2, vcc_lo, 0x0
	s_addc_u32 s3, vcc_hi, 0
	s_waitcnt vmcnt(0)
	s_barrier
	s_barrier
	v_lshl_add_u64 v[142:143], s[74:75], 0, v[132:133]
	s_add_i32 m0, s5, 0xc000
	v_lshl_add_u64 v[160:161], s[74:75], 0, v[130:131]
	global_load_lds_dwordx4 v[142:143], off
	s_add_i32 m0, s5, 0xe000
	s_add_u32 s74, s74, 0x80
	s_addc_u32 s75, s75, 0
	global_load_lds_dwordx4 v[160:161], off
	v_lshl_add_u64 v[142:143], s[74:75], 0, v[132:133]
	s_add_i32 m0, s5, 0x0
	v_lshl_add_u64 v[160:161], s[74:75], 0, v[130:131]
	global_load_lds_dwordx4 v[142:143], off
	s_add_i32 m0, s5, 0x2000
	v_lshl_add_u64 v[178:179], s[2:3], 0, v[144:145]
	global_load_lds_dwordx4 v[160:161], off
	s_add_i32 m0, s5, 0x14000
	v_lshl_add_u64 v[238:239], s[2:3], 0, v[128:129]
	global_load_lds_dwordx4 v[178:179], off
	s_add_i32 m0, s5, 0x16000
	s_add_u32 s74, s74, 0x80
	s_addc_u32 s75, s75, 0
	global_load_lds_dwordx4 v[238:239], off
	s_add_u32 s2, s2, 0x80
	s_addc_u32 s3, s3, 0
	s_mov_b32 s8, 0
.Lq_lin_2_k:
	v_lshl_add_u64 v[142:143], s[74:75], 0, v[132:133]
	s_add_i32 m0, s5, 0x8000
	v_lshl_add_u64 v[160:161], s[74:75], 0, v[130:131]
	global_load_lds_dwordx4 v[142:143], off
	s_add_i32 m0, s5, 0xa000
	v_lshl_add_u64 v[178:179], s[2:3], 0, v[144:145]
	global_load_lds_dwordx4 v[160:161], off
	s_add_i32 m0, s5, 0x1c000
	v_lshl_add_u64 v[238:239], s[2:3], 0, v[128:129]
	global_load_lds_dwordx4 v[178:179], off
	s_add_i32 m0, s5, 0x1e000
	s_add_u32 s74, s74, 0x80
	s_addc_u32 s75, s75, 0
	global_load_lds_dwordx4 v[238:239], off
	s_add_u32 s2, s2, 0x80
	s_addc_u32 s3, s3, 0
	v_add_u32_e32 v165, 0x10000, v162
	ds_read_b128 v[206:209], v164 offset:16384
	ds_read_b128 v[210:213], v164 offset:17408
	ds_read_b128 v[214:217], v164 offset:18432
	ds_read_b128 v[218:221], v164 offset:19456
	ds_read_b128 v[222:225], v164 offset:20480
	ds_read_b128 v[226:229], v164 offset:21504
	ds_read_b128 v[230:233], v164 offset:22528
	ds_read_b128 v[234:237], v164 offset:23552
	ds_read_b128 v[138:141], v165
	ds_read_b128 v[166:169], v165 offset:1024
	ds_read_b128 v[170:173], v165 offset:2048
	ds_read_b128 v[174:177], v165 offset:3072
	s_waitcnt vmcnt(8)
	s_waitcnt lgkmcnt(0)
	s_barrier
	s_setprio 1
	v_mfma_f32_16x16x32_bf16 v[60:63], v[138:141], v[206:209], v[60:63]
	v_mfma_f32_16x16x32_bf16 v[56:59], v[170:173], v[206:209], v[56:59]
	v_mfma_f32_16x16x32_bf16 v[44:47], v[138:141], v[214:217], v[44:47]
	v_mfma_f32_16x16x32_bf16 v[40:43], v[170:173], v[214:217], v[40:43]
	v_mfma_f32_16x16x32_bf16 v[28:31], v[138:141], v[222:225], v[28:31]
	v_mfma_f32_16x16x32_bf16 v[24:27], v[170:173], v[222:225], v[24:27]
	v_mfma_f32_16x16x32_bf16 v[12:15], v[138:141], v[230:233], v[12:15]
	v_mfma_f32_16x16x32_bf16 v[8:11], v[170:173], v[230:233], v[8:11]
	v_mfma_f32_16x16x32_bf16 v[60:63], v[166:169], v[210:213], v[60:63]
	v_mfma_f32_16x16x32_bf16 v[56:59], v[174:177], v[210:213], v[56:59]
	v_mfma_f32_16x16x32_bf16 v[44:47], v[166:169], v[218:221], v[44:47]
	v_mfma_f32_16x16x32_bf16 v[40:43], v[174:177], v[218:221], v[40:43]
	v_mfma_f32_16x16x32_bf16 v[28:31], v[166:169], v[226:229], v[28:31]
	v_mfma_f32_16x16x32_bf16 v[24:27], v[174:177], v[226:229], v[24:27]
	v_mfma_f32_16x16x32_bf16 v[12:15], v[166:169], v[234:237], v[12:15]
	v_mfma_f32_16x16x32_bf16 v[8:11], v[174:177], v[234:237], v[8:11]
	s_setprio 0
	s_barrier
	v_lshl_add_u64 v[142:143], s[74:75], 0, v[132:133]
	s_add_i32 m0, s5, 0x4000
	v_lshl_add_u64 v[160:161], s[74:75], 0, v[130:131]
	global_load_lds_dwordx4 v[142:143], off
	s_add_i32 m0, s5, 0x6000
	v_lshl_add_u64 v[178:179], s[2:3], 0, v[144:145]
	global_load_lds_dwordx4 v[160:161], off
	s_add_i32 m0, s5, 0x10000
	v_lshl_add_u64 v[238:239], s[2:3], 0, v[128:129]
	global_load_lds_dwordx4 v[178:179], off
	s_add_i32 m0, s5, 0x12000
	s_add_u32 s74, s74, 0x80
	s_addc_u32 s75, s75, 0
	global_load_lds_dwordx4 v[238:239], off
	s_add_u32 s2, s2, 0x80
	s_addc_u32 s3, s3, 0
	v_add_u32_e32 v165, 0x18000, v162
	ds_read_b128 v[206:209], v164 offset:49152
	ds_read_b128 v[210:213], v164 offset:50176
	ds_read_b128 v[214:217], v164 offset:51200
	ds_read_b128 v[218:221], v164 offset:52224
	ds_read_b128 v[222:225], v164 offset:53248
	ds_read_b128 v[226:229], v164 offset:54272
	ds_read_b128 v[230:233], v164 offset:55296
	ds_read_b128 v[234:237], v164 offset:56320
	ds_read_b128 v[138:141], v165
	ds_read_b128 v[166:169], v165 offset:1024
	ds_read_b128 v[170:173], v165 offset:2048
	ds_read_b128 v[174:177], v165 offset:3072
	s_waitcnt vmcnt(8)
	s_waitcnt lgkmcnt(0)
	s_barrier
	s_setprio 1
	v_mfma_f32_16x16x32_bf16 v[60:63], v[138:141], v[206:209], v[60:63]
	v_mfma_f32_16x16x32_bf16 v[56:59], v[170:173], v[206:209], v[56:59]
	v_mfma_f32_16x16x32_bf16 v[44:47], v[138:141], v[214:217], v[44:47]
	v_mfma_f32_16x16x32_bf16 v[40:43], v[170:173], v[214:217], v[40:43]
	v_mfma_f32_16x16x32_bf16 v[28:31], v[138:141], v[222:225], v[28:31]
	v_mfma_f32_16x16x32_bf16 v[24:27], v[170:173], v[222:225], v[24:27]
	v_mfma_f32_16x16x32_bf16 v[12:15], v[138:141], v[230:233], v[12:15]
	v_mfma_f32_16x16x32_bf16 v[8:11], v[170:173], v[230:233], v[8:11]
	v_mfma_f32_16x16x32_bf16 v[60:63], v[166:169], v[210:213], v[60:63]
	v_mfma_f32_16x16x32_bf16 v[56:59], v[174:177], v[210:213], v[56:59]
	v_mfma_f32_16x16x32_bf16 v[44:47], v[166:169], v[218:221], v[44:47]
	v_mfma_f32_16x16x32_bf16 v[40:43], v[174:177], v[218:221], v[40:43]
	v_mfma_f32_16x16x32_bf16 v[28:31], v[166:169], v[226:229], v[28:31]
	v_mfma_f32_16x16x32_bf16 v[24:27], v[174:177], v[226:229], v[24:27]
	v_mfma_f32_16x16x32_bf16 v[12:15], v[166:169], v[234:237], v[12:15]
	v_mfma_f32_16x16x32_bf16 v[8:11], v[174:177], v[234:237], v[8:11]
	s_setprio 0
	s_barrier
	v_lshl_add_u64 v[142:143], s[74:75], 0, v[132:133]
	s_add_i32 m0, s5, 0xc000
	v_lshl_add_u64 v[160:161], s[74:75], 0, v[130:131]
	global_load_lds_dwordx4 v[142:143], off
	s_add_i32 m0, s5, 0xe000
	v_lshl_add_u64 v[178:179], s[2:3], 0, v[144:145]
	global_load_lds_dwordx4 v[160:161], off
	s_add_i32 m0, s5, 0x18000
	v_lshl_add_u64 v[238:239], s[2:3], 0, v[128:129]
	global_load_lds_dwordx4 v[178:179], off
	s_add_i32 m0, s5, 0x1a000
	s_add_u32 s74, s74, 0x80
	s_addc_u32 s75, s75, 0
	global_load_lds_dwordx4 v[238:239], off
	s_add_u32 s2, s2, 0x80
	s_addc_u32 s3, s3, 0
	v_add_u32_e32 v165, 0x14000, v162
	ds_read_b128 v[206:209], v164 offset:0
	ds_read_b128 v[210:213], v164 offset:1024
	ds_read_b128 v[214:217], v164 offset:2048
	ds_read_b128 v[218:221], v164 offset:3072
	ds_read_b128 v[222:225], v164 offset:4096
	ds_read_b128 v[226:229], v164 offset:5120
	ds_read_b128 v[230:233], v164 offset:6144
	ds_read_b128 v[234:237], v164 offset:7168
	ds_read_b128 v[138:141], v165
	ds_read_b128 v[166:169], v165 offset:1024
	ds_read_b128 v[170:173], v165 offset:2048
	ds_read_b128 v[174:177], v165 offset:3072
	s_waitcnt vmcnt(8)
	s_waitcnt lgkmcnt(0)
	s_barrier
	s_setprio 1
	v_mfma_f32_16x16x32_bf16 v[60:63], v[138:141], v[206:209], v[60:63]
	v_mfma_f32_16x16x32_bf16 v[56:59], v[170:173], v[206:209], v[56:59]
	v_mfma_f32_16x16x32_bf16 v[44:47], v[138:141], v[214:217], v[44:47]
	v_mfma_f32_16x16x32_bf16 v[40:43], v[170:173], v[214:217], v[40:43]
	v_mfma_f32_16x16x32_bf16 v[28:31], v[138:141], v[222:225], v[28:31]
	v_mfma_f32_16x16x32_bf16 v[24:27], v[170:173], v[222:225], v[24:27]
	v_mfma_f32_16x16x32_bf16 v[12:15], v[138:141], v[230:233], v[12:15]
	v_mfma_f32_16x16x32_bf16 v[8:11], v[170:173], v[230:233], v[8:11]
	v_mfma_f32_16x16x32_bf16 v[60:63], v[166:169], v[210:213], v[60:63]
	v_mfma_f32_16x16x32_bf16 v[56:59], v[174:177], v[210:213], v[56:59]
	v_mfma_f32_16x16x32_bf16 v[44:47], v[166:169], v[218:221], v[44:47]
	v_mfma_f32_16x16x32_bf16 v[40:43], v[174:177], v[218:221], v[40:43]
	v_mfma_f32_16x16x32_bf16 v[28:31], v[166:169], v[226:229], v[28:31]
	v_mfma_f32_16x16x32_bf16 v[24:27], v[174:177], v[226:229], v[24:27]
	v_mfma_f32_16x16x32_bf16 v[12:15], v[166:169], v[234:237], v[12:15]
	v_mfma_f32_16x16x32_bf16 v[8:11], v[174:177], v[234:237], v[8:11]
	s_setprio 0
	s_barrier
	v_lshl_add_u64 v[142:143], s[74:75], 0, v[132:133]
	s_add_i32 m0, s5, 0x0
	v_lshl_add_u64 v[160:161], s[74:75], 0, v[130:131]
	global_load_lds_dwordx4 v[142:143], off
	s_add_i32 m0, s5, 0x2000
	v_lshl_add_u64 v[178:179], s[2:3], 0, v[144:145]
	global_load_lds_dwordx4 v[160:161], off
	s_add_i32 m0, s5, 0x14000
	v_lshl_add_u64 v[238:239], s[2:3], 0, v[128:129]
	global_load_lds_dwordx4 v[178:179], off
	s_add_i32 m0, s5, 0x16000
	s_add_u32 s74, s74, 0x80
	s_addc_u32 s75, s75, 0
	global_load_lds_dwordx4 v[238:239], off
	s_add_u32 s2, s2, 0x80
	s_addc_u32 s3, s3, 0
	v_add_u32_e32 v165, 0x1c000, v162
	ds_read_b128 v[206:209], v164 offset:32768
	ds_read_b128 v[210:213], v164 offset:33792
	ds_read_b128 v[214:217], v164 offset:34816
	ds_read_b128 v[218:221], v164 offset:35840
	ds_read_b128 v[222:225], v164 offset:36864
	ds_read_b128 v[226:229], v164 offset:37888
	ds_read_b128 v[230:233], v164 offset:38912
	ds_read_b128 v[234:237], v164 offset:39936
	ds_read_b128 v[138:141], v165
	ds_read_b128 v[166:169], v165 offset:1024
	ds_read_b128 v[170:173], v165 offset:2048
	ds_read_b128 v[174:177], v165 offset:3072
	s_waitcnt vmcnt(8)
	s_waitcnt lgkmcnt(0)
	s_barrier
	s_setprio 1
	v_mfma_f32_16x16x32_bf16 v[60:63], v[138:141], v[206:209], v[60:63]
	v_mfma_f32_16x16x32_bf16 v[56:59], v[170:173], v[206:209], v[56:59]
	v_mfma_f32_16x16x32_bf16 v[44:47], v[138:141], v[214:217], v[44:47]
	v_mfma_f32_16x16x32_bf16 v[40:43], v[170:173], v[214:217], v[40:43]
	v_mfma_f32_16x16x32_bf16 v[28:31], v[138:141], v[222:225], v[28:31]
	v_mfma_f32_16x16x32_bf16 v[24:27], v[170:173], v[222:225], v[24:27]
	v_mfma_f32_16x16x32_bf16 v[12:15], v[138:141], v[230:233], v[12:15]
	v_mfma_f32_16x16x32_bf16 v[8:11], v[170:173], v[230:233], v[8:11]
	v_mfma_f32_16x16x32_bf16 v[60:63], v[166:169], v[210:213], v[60:63]
	v_mfma_f32_16x16x32_bf16 v[56:59], v[174:177], v[210:213], v[56:59]
	v_mfma_f32_16x16x32_bf16 v[44:47], v[166:169], v[218:221], v[44:47]
	v_mfma_f32_16x16x32_bf16 v[40:43], v[174:177], v[218:221], v[40:43]
	v_mfma_f32_16x16x32_bf16 v[28:31], v[166:169], v[226:229], v[28:31]
	v_mfma_f32_16x16x32_bf16 v[24:27], v[174:177], v[226:229], v[24:27]
	v_mfma_f32_16x16x32_bf16 v[12:15], v[166:169], v[234:237], v[12:15]
	v_mfma_f32_16x16x32_bf16 v[8:11], v[174:177], v[234:237], v[8:11]
	s_setprio 0
	s_barrier
	s_add_i32 s8, s8, 1
	s_cmp_lt_u32 s8, 7
	s_cbranch_scc1 .Lq_lin_2_k
	v_lshl_add_u64 v[142:143], s[74:75], 0, v[132:133]
	s_add_i32 m0, s5, 0x8000
	v_lshl_add_u64 v[160:161], s[74:75], 0, v[130:131]
	global_load_lds_dwordx4 v[142:143], off
	s_add_i32 m0, s5, 0xa000
	v_lshl_add_u64 v[178:179], s[2:3], 0, v[144:145]
	global_load_lds_dwordx4 v[160:161], off
	s_add_i32 m0, s5, 0x1c000
	v_lshl_add_u64 v[238:239], s[2:3], 0, v[128:129]
	global_load_lds_dwordx4 v[178:179], off
	s_add_i32 m0, s5, 0x1e000
	s_add_u32 s74, s74, 0x80
	s_addc_u32 s75, s75, 0
	global_load_lds_dwordx4 v[238:239], off
	s_add_u32 s2, s2, 0x80
	s_addc_u32 s3, s3, 0
	v_add_u32_e32 v165, 0x10000, v162
	ds_read_b128 v[206:209], v164 offset:16384
	ds_read_b128 v[210:213], v164 offset:17408
	ds_read_b128 v[214:217], v164 offset:18432
	ds_read_b128 v[218:221], v164 offset:19456
	ds_read_b128 v[222:225], v164 offset:20480
	ds_read_b128 v[226:229], v164 offset:21504
	ds_read_b128 v[230:233], v164 offset:22528
	ds_read_b128 v[234:237], v164 offset:23552
	ds_read_b128 v[138:141], v165
	ds_read_b128 v[166:169], v165 offset:1024
	ds_read_b128 v[170:173], v165 offset:2048
	ds_read_b128 v[174:177], v165 offset:3072
	s_waitcnt vmcnt(8)
	s_waitcnt lgkmcnt(0)
	s_barrier
	s_setprio 1
	v_mfma_f32_16x16x32_bf16 v[60:63], v[138:141], v[206:209], v[60:63]
	v_mfma_f32_16x16x32_bf16 v[56:59], v[170:173], v[206:209], v[56:59]
	v_mfma_f32_16x16x32_bf16 v[44:47], v[138:141], v[214:217], v[44:47]
	v_mfma_f32_16x16x32_bf16 v[40:43], v[170:173], v[214:217], v[40:43]
	v_mfma_f32_16x16x32_bf16 v[28:31], v[138:141], v[222:225], v[28:31]
	v_mfma_f32_16x16x32_bf16 v[24:27], v[170:173], v[222:225], v[24:27]
	v_mfma_f32_16x16x32_bf16 v[12:15], v[138:141], v[230:233], v[12:15]
	v_mfma_f32_16x16x32_bf16 v[8:11], v[170:173], v[230:233], v[8:11]
	v_mfma_f32_16x16x32_bf16 v[60:63], v[166:169], v[210:213], v[60:63]
	v_mfma_f32_16x16x32_bf16 v[56:59], v[174:177], v[210:213], v[56:59]
	v_mfma_f32_16x16x32_bf16 v[44:47], v[166:169], v[218:221], v[44:47]
	v_mfma_f32_16x16x32_bf16 v[40:43], v[174:177], v[218:221], v[40:43]
	v_mfma_f32_16x16x32_bf16 v[28:31], v[166:169], v[226:229], v[28:31]
	v_mfma_f32_16x16x32_bf16 v[24:27], v[174:177], v[226:229], v[24:27]
	v_mfma_f32_16x16x32_bf16 v[12:15], v[166:169], v[234:237], v[12:15]
	v_mfma_f32_16x16x32_bf16 v[8:11], v[174:177], v[234:237], v[8:11]
	s_setprio 0
	s_barrier
	v_add_u32_e32 v165, 0x18000, v162
	ds_read_b128 v[206:209], v164 offset:49152
	ds_read_b128 v[210:213], v164 offset:50176
	ds_read_b128 v[214:217], v164 offset:51200
	ds_read_b128 v[218:221], v164 offset:52224
	ds_read_b128 v[222:225], v164 offset:53248
	ds_read_b128 v[226:229], v164 offset:54272
	ds_read_b128 v[230:233], v164 offset:55296
	ds_read_b128 v[234:237], v164 offset:56320
	ds_read_b128 v[138:141], v165
	ds_read_b128 v[166:169], v165 offset:1024
	ds_read_b128 v[170:173], v165 offset:2048
	ds_read_b128 v[174:177], v165 offset:3072
	s_waitcnt vmcnt(4)
	s_waitcnt lgkmcnt(0)
	s_barrier
	s_setprio 1
	v_mfma_f32_16x16x32_bf16 v[60:63], v[138:141], v[206:209], v[60:63]
	v_mfma_f32_16x16x32_bf16 v[56:59], v[170:173], v[206:209], v[56:59]
	v_mfma_f32_16x16x32_bf16 v[44:47], v[138:141], v[214:217], v[44:47]
	v_mfma_f32_16x16x32_bf16 v[40:43], v[170:173], v[214:217], v[40:43]
	v_mfma_f32_16x16x32_bf16 v[28:31], v[138:141], v[222:225], v[28:31]
	v_mfma_f32_16x16x32_bf16 v[24:27], v[170:173], v[222:225], v[24:27]
	v_mfma_f32_16x16x32_bf16 v[12:15], v[138:141], v[230:233], v[12:15]
	v_mfma_f32_16x16x32_bf16 v[8:11], v[170:173], v[230:233], v[8:11]
	v_mfma_f32_16x16x32_bf16 v[60:63], v[166:169], v[210:213], v[60:63]
	v_mfma_f32_16x16x32_bf16 v[56:59], v[174:177], v[210:213], v[56:59]
	v_mfma_f32_16x16x32_bf16 v[44:47], v[166:169], v[218:221], v[44:47]
	v_mfma_f32_16x16x32_bf16 v[40:43], v[174:177], v[218:221], v[40:43]
	v_mfma_f32_16x16x32_bf16 v[28:31], v[166:169], v[226:229], v[28:31]
	v_mfma_f32_16x16x32_bf16 v[24:27], v[174:177], v[226:229], v[24:27]
	v_mfma_f32_16x16x32_bf16 v[12:15], v[166:169], v[234:237], v[12:15]
	v_mfma_f32_16x16x32_bf16 v[8:11], v[174:177], v[234:237], v[8:11]
	s_setprio 0
	s_barrier
	v_add_u32_e32 v165, 0x14000, v162
	ds_read_b128 v[206:209], v164 offset:0
	ds_read_b128 v[210:213], v164 offset:1024
	ds_read_b128 v[214:217], v164 offset:2048
	ds_read_b128 v[218:221], v164 offset:3072
	ds_read_b128 v[222:225], v164 offset:4096
	ds_read_b128 v[226:229], v164 offset:5120
	ds_read_b128 v[230:233], v164 offset:6144
	ds_read_b128 v[234:237], v164 offset:7168
	ds_read_b128 v[138:141], v165
	ds_read_b128 v[166:169], v165 offset:1024
	ds_read_b128 v[170:173], v165 offset:2048
	ds_read_b128 v[174:177], v165 offset:3072
	s_waitcnt vmcnt(0)
	s_waitcnt lgkmcnt(0)
	s_barrier
	s_setprio 1
	v_mfma_f32_16x16x32_bf16 v[60:63], v[138:141], v[206:209], v[60:63]
	v_mfma_f32_16x16x32_bf16 v[56:59], v[170:173], v[206:209], v[56:59]
	v_mfma_f32_16x16x32_bf16 v[44:47], v[138:141], v[214:217], v[44:47]
	v_mfma_f32_16x16x32_bf16 v[40:43], v[170:173], v[214:217], v[40:43]
	v_mfma_f32_16x16x32_bf16 v[28:31], v[138:141], v[222:225], v[28:31]
	v_mfma_f32_16x16x32_bf16 v[24:27], v[170:173], v[222:225], v[24:27]
	v_mfma_f32_16x16x32_bf16 v[12:15], v[138:141], v[230:233], v[12:15]
	v_mfma_f32_16x16x32_bf16 v[8:11], v[170:173], v[230:233], v[8:11]
	v_mfma_f32_16x16x32_bf16 v[60:63], v[166:169], v[210:213], v[60:63]
	v_mfma_f32_16x16x32_bf16 v[56:59], v[174:177], v[210:213], v[56:59]
	v_mfma_f32_16x16x32_bf16 v[44:47], v[166:169], v[218:221], v[44:47]
	v_mfma_f32_16x16x32_bf16 v[40:43], v[174:177], v[218:221], v[40:43]
	v_mfma_f32_16x16x32_bf16 v[28:31], v[166:169], v[226:229], v[28:31]
	v_mfma_f32_16x16x32_bf16 v[24:27], v[174:177], v[226:229], v[24:27]
	v_mfma_f32_16x16x32_bf16 v[12:15], v[166:169], v[234:237], v[12:15]
	v_mfma_f32_16x16x32_bf16 v[8:11], v[174:177], v[234:237], v[8:11]
	s_setprio 0
	s_barrier
	v_add_u32_e32 v165, 0x1c000, v162
	ds_read_b128 v[206:209], v164 offset:32768
	ds_read_b128 v[210:213], v164 offset:33792
	ds_read_b128 v[214:217], v164 offset:34816
	ds_read_b128 v[218:221], v164 offset:35840
	ds_read_b128 v[222:225], v164 offset:36864
	ds_read_b128 v[226:229], v164 offset:37888
	ds_read_b128 v[230:233], v164 offset:38912
	ds_read_b128 v[234:237], v164 offset:39936
	ds_read_b128 v[138:141], v165
	ds_read_b128 v[166:169], v165 offset:1024
	ds_read_b128 v[170:173], v165 offset:2048
	ds_read_b128 v[174:177], v165 offset:3072
	s_waitcnt lgkmcnt(0)
	s_barrier
	s_setprio 1
	v_mfma_f32_16x16x32_bf16 v[60:63], v[138:141], v[206:209], v[60:63]
	v_mfma_f32_16x16x32_bf16 v[56:59], v[170:173], v[206:209], v[56:59]
	v_mfma_f32_16x16x32_bf16 v[44:47], v[138:141], v[214:217], v[44:47]
	v_mfma_f32_16x16x32_bf16 v[40:43], v[170:173], v[214:217], v[40:43]
	v_mfma_f32_16x16x32_bf16 v[28:31], v[138:141], v[222:225], v[28:31]
	v_mfma_f32_16x16x32_bf16 v[24:27], v[170:173], v[222:225], v[24:27]
	v_mfma_f32_16x16x32_bf16 v[12:15], v[138:141], v[230:233], v[12:15]
	v_mfma_f32_16x16x32_bf16 v[8:11], v[170:173], v[230:233], v[8:11]
	v_mfma_f32_16x16x32_bf16 v[60:63], v[166:169], v[210:213], v[60:63]
	v_mfma_f32_16x16x32_bf16 v[56:59], v[174:177], v[210:213], v[56:59]
	v_mfma_f32_16x16x32_bf16 v[44:47], v[166:169], v[218:221], v[44:47]
	v_mfma_f32_16x16x32_bf16 v[40:43], v[174:177], v[218:221], v[40:43]
	v_mfma_f32_16x16x32_bf16 v[28:31], v[166:169], v[226:229], v[28:31]
	v_mfma_f32_16x16x32_bf16 v[24:27], v[174:177], v[226:229], v[24:27]
	v_mfma_f32_16x16x32_bf16 v[12:15], v[166:169], v[234:237], v[12:15]
	v_mfma_f32_16x16x32_bf16 v[8:11], v[174:177], v[234:237], v[8:11]
	s_setprio 0
	s_barrier
	s_branch .Lq_lin_exit
.Lq_lin_3_loop:
	s_add_u32 s74, s74, 0x80080
	s_addc_u32 s75, s75, 0
	s_add_u32 s2, vcc_lo, 0x80000
	s_addc_u32 s3, vcc_hi, 0
	s_waitcnt vmcnt(0)
	s_barrier
	s_barrier
	v_lshl_add_u64 v[142:143], s[74:75], 0, v[132:133]
	s_add_i32 m0, s5, 0xc000
	v_lshl_add_u64 v[160:161], s[74:75], 0, v[130:131]
	global_load_lds_dwordx4 v[142:143], off
	s_add_i32 m0, s5, 0xe000
	s_add_u32 s74, s74, 0x80
	s_addc_u32 s75, s75, 0
	global_load_lds_dwordx4 v[160:161], off
	v_lshl_add_u64 v[142:143], s[74:75], 0, v[132:133]
	s_add_i32 m0, s5, 0x0
	v_lshl_add_u64 v[160:161], s[74:75], 0, v[130:131]
	global_load_lds_dwordx4 v[142:143], off
	s_add_i32 m0, s5, 0x2000
	v_lshl_add_u64 v[178:179], s[2:3], 0, v[144:145]
	global_load_lds_dwordx4 v[160:161], off
	s_add_i32 m0, s5, 0x10000
	v_lshl_add_u64 v[238:239], s[2:3], 0, v[128:129]
	global_load_lds_dwordx4 v[178:179], off
	s_add_i32 m0, s5, 0x12000
	s_add_u32 s74, s74, 0x80
	s_addc_u32 s75, s75, 0
	global_load_lds_dwordx4 v[238:239], off
	s_add_u32 s2, s2, 0x80
	s_addc_u32 s3, s3, 0
	s_mov_b32 s8, 0
.Lq_lin_3_k:
	v_lshl_add_u64 v[142:143], s[74:75], 0, v[132:133]
	s_add_i32 m0, s5, 0x8000
	v_lshl_add_u64 v[160:161], s[74:75], 0, v[130:131]
	global_load_lds_dwordx4 v[142:143], off
	s_add_i32 m0, s5, 0xa000
	v_lshl_add_u64 v[178:179], s[2:3], 0, v[144:145]
	global_load_lds_dwordx4 v[160:161], off
	s_add_i32 m0, s5, 0x18000
	v_lshl_add_u64 v[238:239], s[2:3], 0, v[128:129]
	global_load_lds_dwordx4 v[178:179], off
	s_add_i32 m0, s5, 0x1a000
	s_add_u32 s74, s74, 0x80
	s_addc_u32 s75, s75, 0
	global_load_lds_dwordx4 v[238:239], off
	s_add_u32 s2, s2, 0x80
	s_addc_u32 s3, s3, 0
	v_add_u32_e32 v165, 0x14000, v162
	ds_read_b128 v[206:209], v164 offset:16384
	ds_read_b128 v[210:213], v164 offset:17408
	ds_read_b128 v[214:217], v164 offset:18432
	ds_read_b128 v[218:221], v164 offset:19456
	ds_read_b128 v[222:225], v164 offset:20480
	ds_read_b128 v[226:229], v164 offset:21504
	ds_read_b128 v[230:233], v164 offset:22528
	ds_read_b128 v[234:237], v164 offset:23552
	ds_read_b128 v[190:193], v165
	ds_read_b128 v[194:197], v165 offset:1024
	ds_read_b128 v[198:201], v165 offset:2048
	ds_read_b128 v[202:205], v165 offset:3072
	s_waitcnt vmcnt(8)
	s_waitcnt lgkmcnt(0)
	s_barrier
	s_setprio 1
	v_mfma_f32_16x16x32_bf16 v[52:55], v[190:193], v[206:209], v[52:55]
	v_mfma_f32_16x16x32_bf16 v[48:51], v[198:201], v[206:209], v[48:51]
	v_mfma_f32_16x16x32_bf16 v[36:39], v[190:193], v[214:217], v[36:39]
	v_mfma_f32_16x16x32_bf16 v[32:35], v[198:201], v[214:217], v[32:35]
	v_mfma_f32_16x16x32_bf16 v[20:23], v[190:193], v[222:225], v[20:23]
	v_mfma_f32_16x16x32_bf16 v[16:19], v[198:201], v[222:225], v[16:19]
	v_mfma_f32_16x16x32_bf16 v[4:7], v[190:193], v[230:233], v[4:7]
	v_mfma_f32_16x16x32_bf16 v[0:3], v[198:201], v[230:233], v[0:3]
	v_mfma_f32_16x16x32_bf16 v[52:55], v[194:197], v[210:213], v[52:55]
	v_mfma_f32_16x16x32_bf16 v[48:51], v[202:205], v[210:213], v[48:51]
	v_mfma_f32_16x16x32_bf16 v[36:39], v[194:197], v[218:221], v[36:39]
	v_mfma_f32_16x16x32_bf16 v[32:35], v[202:205], v[218:221], v[32:35]
	v_mfma_f32_16x16x32_bf16 v[20:23], v[194:197], v[226:229], v[20:23]
	v_mfma_f32_16x16x32_bf16 v[16:19], v[202:205], v[226:229], v[16:19]
	v_mfma_f32_16x16x32_bf16 v[4:7], v[194:197], v[234:237], v[4:7]
	v_mfma_f32_16x16x32_bf16 v[0:3], v[202:205], v[234:237], v[0:3]
	s_setprio 0
	s_barrier
	v_lshl_add_u64 v[142:143], s[74:75], 0, v[132:133]
	s_add_i32 m0, s5, 0x4000
	v_lshl_add_u64 v[160:161], s[74:75], 0, v[130:131]
	global_load_lds_dwordx4 v[142:143], off
	s_add_i32 m0, s5, 0x6000
	v_lshl_add_u64 v[178:179], s[2:3], 0, v[144:145]
	global_load_lds_dwordx4 v[160:161], off
	s_add_i32 m0, s5, 0x14000
	v_lshl_add_u64 v[238:239], s[2:3], 0, v[128:129]
	global_load_lds_dwordx4 v[178:179], off
	s_add_i32 m0, s5, 0x16000
	s_add_u32 s74, s74, 0x80
	s_addc_u32 s75, s75, 0
	global_load_lds_dwordx4 v[238:239], off
	s_add_u32 s2, s2, 0x80
	s_addc_u32 s3, s3, 0
	v_add_u32_e32 v165, 0x1c000, v162
	ds_read_b128 v[206:209], v164 offset:49152
	ds_read_b128 v[210:213], v164 offset:50176
	ds_read_b128 v[214:217], v164 offset:51200
	ds_read_b128 v[218:221], v164 offset:52224
	ds_read_b128 v[222:225], v164 offset:53248
	ds_read_b128 v[226:229], v164 offset:54272
	ds_read_b128 v[230:233], v164 offset:55296
	ds_read_b128 v[234:237], v164 offset:56320
	ds_read_b128 v[190:193], v165
	ds_read_b128 v[194:197], v165 offset:1024
	ds_read_b128 v[198:201], v165 offset:2048
	ds_read_b128 v[202:205], v165 offset:3072
	s_waitcnt vmcnt(8)
	s_waitcnt lgkmcnt(0)
	s_barrier
	s_setprio 1
	v_mfma_f32_16x16x32_bf16 v[52:55], v[190:193], v[206:209], v[52:55]
	v_mfma_f32_16x16x32_bf16 v[48:51], v[198:201], v[206:209], v[48:51]
	v_mfma_f32_16x16x32_bf16 v[36:39], v[190:193], v[214:217], v[36:39]
	v_mfma_f32_16x16x32_bf16 v[32:35], v[198:201], v[214:217], v[32:35]
	v_mfma_f32_16x16x32_bf16 v[20:23], v[190:193], v[222:225], v[20:23]
	v_mfma_f32_16x16x32_bf16 v[16:19], v[198:201], v[222:225], v[16:19]
	v_mfma_f32_16x16x32_bf16 v[4:7], v[190:193], v[230:233], v[4:7]
	v_mfma_f32_16x16x32_bf16 v[0:3], v[198:201], v[230:233], v[0:3]
	v_mfma_f32_16x16x32_bf16 v[52:55], v[194:197], v[210:213], v[52:55]
	v_mfma_f32_16x16x32_bf16 v[48:51], v[202:205], v[210:213], v[48:51]
	v_mfma_f32_16x16x32_bf16 v[36:39], v[194:197], v[218:221], v[36:39]
	v_mfma_f32_16x16x32_bf16 v[32:35], v[202:205], v[218:221], v[32:35]
	v_mfma_f32_16x16x32_bf16 v[20:23], v[194:197], v[226:229], v[20:23]
	v_mfma_f32_16x16x32_bf16 v[16:19], v[202:205], v[226:229], v[16:19]
	v_mfma_f32_16x16x32_bf16 v[4:7], v[194:197], v[234:237], v[4:7]
	v_mfma_f32_16x16x32_bf16 v[0:3], v[202:205], v[234:237], v[0:3]
	s_setprio 0
	s_barrier
	v_lshl_add_u64 v[142:143], s[74:75], 0, v[132:133]
	s_add_i32 m0, s5, 0xc000
	v_lshl_add_u64 v[160:161], s[74:75], 0, v[130:131]
	global_load_lds_dwordx4 v[142:143], off
	s_add_i32 m0, s5, 0xe000
	v_lshl_add_u64 v[178:179], s[2:3], 0, v[144:145]
	global_load_lds_dwordx4 v[160:161], off
	s_add_i32 m0, s5, 0x1c000
	v_lshl_add_u64 v[238:239], s[2:3], 0, v[128:129]
	global_load_lds_dwordx4 v[178:179], off
	s_add_i32 m0, s5, 0x1e000
	s_add_u32 s74, s74, 0x80
	s_addc_u32 s75, s75, 0
	global_load_lds_dwordx4 v[238:239], off
	s_add_u32 s2, s2, 0x80
	s_addc_u32 s3, s3, 0
	v_add_u32_e32 v165, 0x10000, v162
	ds_read_b128 v[206:209], v164 offset:0
	ds_read_b128 v[210:213], v164 offset:1024
	ds_read_b128 v[214:217], v164 offset:2048
	ds_read_b128 v[218:221], v164 offset:3072
	ds_read_b128 v[222:225], v164 offset:4096
	ds_read_b128 v[226:229], v164 offset:5120
	ds_read_b128 v[230:233], v164 offset:6144
	ds_read_b128 v[234:237], v164 offset:7168
	ds_read_b128 v[190:193], v165
	ds_read_b128 v[194:197], v165 offset:1024
	ds_read_b128 v[198:201], v165 offset:2048
	ds_read_b128 v[202:205], v165 offset:3072
	s_waitcnt vmcnt(8)
	s_waitcnt lgkmcnt(0)
	s_barrier
	s_setprio 1
	v_mfma_f32_16x16x32_bf16 v[52:55], v[190:193], v[206:209], v[52:55]
	v_mfma_f32_16x16x32_bf16 v[48:51], v[198:201], v[206:209], v[48:51]
	v_mfma_f32_16x16x32_bf16 v[36:39], v[190:193], v[214:217], v[36:39]
	v_mfma_f32_16x16x32_bf16 v[32:35], v[198:201], v[214:217], v[32:35]
	v_mfma_f32_16x16x32_bf16 v[20:23], v[190:193], v[222:225], v[20:23]
	v_mfma_f32_16x16x32_bf16 v[16:19], v[198:201], v[222:225], v[16:19]
	v_mfma_f32_16x16x32_bf16 v[4:7], v[190:193], v[230:233], v[4:7]
	v_mfma_f32_16x16x32_bf16 v[0:3], v[198:201], v[230:233], v[0:3]
	v_mfma_f32_16x16x32_bf16 v[52:55], v[194:197], v[210:213], v[52:55]
	v_mfma_f32_16x16x32_bf16 v[48:51], v[202:205], v[210:213], v[48:51]
	v_mfma_f32_16x16x32_bf16 v[36:39], v[194:197], v[218:221], v[36:39]
	v_mfma_f32_16x16x32_bf16 v[32:35], v[202:205], v[218:221], v[32:35]
	v_mfma_f32_16x16x32_bf16 v[20:23], v[194:197], v[226:229], v[20:23]
	v_mfma_f32_16x16x32_bf16 v[16:19], v[202:205], v[226:229], v[16:19]
	v_mfma_f32_16x16x32_bf16 v[4:7], v[194:197], v[234:237], v[4:7]
	v_mfma_f32_16x16x32_bf16 v[0:3], v[202:205], v[234:237], v[0:3]
	s_setprio 0
	s_barrier
	v_lshl_add_u64 v[142:143], s[74:75], 0, v[132:133]
	s_add_i32 m0, s5, 0x0
	v_lshl_add_u64 v[160:161], s[74:75], 0, v[130:131]
	global_load_lds_dwordx4 v[142:143], off
	s_add_i32 m0, s5, 0x2000
	v_lshl_add_u64 v[178:179], s[2:3], 0, v[144:145]
	global_load_lds_dwordx4 v[160:161], off
	s_add_i32 m0, s5, 0x10000
	v_lshl_add_u64 v[238:239], s[2:3], 0, v[128:129]
	global_load_lds_dwordx4 v[178:179], off
	s_add_i32 m0, s5, 0x12000
	s_add_u32 s74, s74, 0x80
	s_addc_u32 s75, s75, 0
	global_load_lds_dwordx4 v[238:239], off
	s_add_u32 s2, s2, 0x80
	s_addc_u32 s3, s3, 0
	v_add_u32_e32 v165, 0x18000, v162
	ds_read_b128 v[206:209], v164 offset:32768
	ds_read_b128 v[210:213], v164 offset:33792
	ds_read_b128 v[214:217], v164 offset:34816
	ds_read_b128 v[218:221], v164 offset:35840
	ds_read_b128 v[222:225], v164 offset:36864
	ds_read_b128 v[226:229], v164 offset:37888
	ds_read_b128 v[230:233], v164 offset:38912
	ds_read_b128 v[234:237], v164 offset:39936
	ds_read_b128 v[190:193], v165
	ds_read_b128 v[194:197], v165 offset:1024
	ds_read_b128 v[198:201], v165 offset:2048
	ds_read_b128 v[202:205], v165 offset:3072
	s_waitcnt vmcnt(8)
	s_waitcnt lgkmcnt(0)
	s_barrier
	s_setprio 1
	v_mfma_f32_16x16x32_bf16 v[52:55], v[190:193], v[206:209], v[52:55]
	v_mfma_f32_16x16x32_bf16 v[48:51], v[198:201], v[206:209], v[48:51]
	v_mfma_f32_16x16x32_bf16 v[36:39], v[190:193], v[214:217], v[36:39]
	v_mfma_f32_16x16x32_bf16 v[32:35], v[198:201], v[214:217], v[32:35]
	v_mfma_f32_16x16x32_bf16 v[20:23], v[190:193], v[222:225], v[20:23]
	v_mfma_f32_16x16x32_bf16 v[16:19], v[198:201], v[222:225], v[16:19]
	v_mfma_f32_16x16x32_bf16 v[4:7], v[190:193], v[230:233], v[4:7]
	v_mfma_f32_16x16x32_bf16 v[0:3], v[198:201], v[230:233], v[0:3]
	v_mfma_f32_16x16x32_bf16 v[52:55], v[194:197], v[210:213], v[52:55]
	v_mfma_f32_16x16x32_bf16 v[48:51], v[202:205], v[210:213], v[48:51]
	v_mfma_f32_16x16x32_bf16 v[36:39], v[194:197], v[218:221], v[36:39]
	v_mfma_f32_16x16x32_bf16 v[32:35], v[202:205], v[218:221], v[32:35]
	v_mfma_f32_16x16x32_bf16 v[20:23], v[194:197], v[226:229], v[20:23]
	v_mfma_f32_16x16x32_bf16 v[16:19], v[202:205], v[226:229], v[16:19]
	v_mfma_f32_16x16x32_bf16 v[4:7], v[194:197], v[234:237], v[4:7]
	v_mfma_f32_16x16x32_bf16 v[0:3], v[202:205], v[234:237], v[0:3]
	s_setprio 0
	s_barrier
	s_add_i32 s8, s8, 1
	s_cmp_lt_u32 s8, 7
	s_cbranch_scc1 .Lq_lin_3_k
	v_lshl_add_u64 v[142:143], s[74:75], 0, v[132:133]
	s_add_i32 m0, s5, 0x8000
	v_lshl_add_u64 v[160:161], s[74:75], 0, v[130:131]
	global_load_lds_dwordx4 v[142:143], off
	s_add_i32 m0, s5, 0xa000
	v_lshl_add_u64 v[178:179], s[2:3], 0, v[144:145]
	global_load_lds_dwordx4 v[160:161], off
	s_add_i32 m0, s5, 0x18000
	v_lshl_add_u64 v[238:239], s[2:3], 0, v[128:129]
	global_load_lds_dwordx4 v[178:179], off
	s_add_i32 m0, s5, 0x1a000
	s_add_u32 s74, s74, 0x80
	s_addc_u32 s75, s75, 0
	global_load_lds_dwordx4 v[238:239], off
	s_add_u32 s2, s2, 0x80
	s_addc_u32 s3, s3, 0
	v_add_u32_e32 v165, 0x14000, v162
	ds_read_b128 v[206:209], v164 offset:16384
	ds_read_b128 v[210:213], v164 offset:17408
	ds_read_b128 v[214:217], v164 offset:18432
	ds_read_b128 v[218:221], v164 offset:19456
	ds_read_b128 v[222:225], v164 offset:20480
	ds_read_b128 v[226:229], v164 offset:21504
	ds_read_b128 v[230:233], v164 offset:22528
	ds_read_b128 v[234:237], v164 offset:23552
	ds_read_b128 v[190:193], v165
	ds_read_b128 v[194:197], v165 offset:1024
	ds_read_b128 v[198:201], v165 offset:2048
	ds_read_b128 v[202:205], v165 offset:3072
	s_waitcnt vmcnt(8)
	s_waitcnt lgkmcnt(0)
	s_barrier
	s_setprio 1
	v_mfma_f32_16x16x32_bf16 v[52:55], v[190:193], v[206:209], v[52:55]
	v_mfma_f32_16x16x32_bf16 v[48:51], v[198:201], v[206:209], v[48:51]
	v_mfma_f32_16x16x32_bf16 v[36:39], v[190:193], v[214:217], v[36:39]
	v_mfma_f32_16x16x32_bf16 v[32:35], v[198:201], v[214:217], v[32:35]
	v_mfma_f32_16x16x32_bf16 v[20:23], v[190:193], v[222:225], v[20:23]
	v_mfma_f32_16x16x32_bf16 v[16:19], v[198:201], v[222:225], v[16:19]
	v_mfma_f32_16x16x32_bf16 v[4:7], v[190:193], v[230:233], v[4:7]
	v_mfma_f32_16x16x32_bf16 v[0:3], v[198:201], v[230:233], v[0:3]
	v_mfma_f32_16x16x32_bf16 v[52:55], v[194:197], v[210:213], v[52:55]
	v_mfma_f32_16x16x32_bf16 v[48:51], v[202:205], v[210:213], v[48:51]
	v_mfma_f32_16x16x32_bf16 v[36:39], v[194:197], v[218:221], v[36:39]
	v_mfma_f32_16x16x32_bf16 v[32:35], v[202:205], v[218:221], v[32:35]
	v_mfma_f32_16x16x32_bf16 v[20:23], v[194:197], v[226:229], v[20:23]
	v_mfma_f32_16x16x32_bf16 v[16:19], v[202:205], v[226:229], v[16:19]
	v_mfma_f32_16x16x32_bf16 v[4:7], v[194:197], v[234:237], v[4:7]
	v_mfma_f32_16x16x32_bf16 v[0:3], v[202:205], v[234:237], v[0:3]
	s_setprio 0
	s_barrier
	v_add_u32_e32 v165, 0x1c000, v162
	ds_read_b128 v[206:209], v164 offset:49152
	ds_read_b128 v[210:213], v164 offset:50176
	ds_read_b128 v[214:217], v164 offset:51200
	ds_read_b128 v[218:221], v164 offset:52224
	ds_read_b128 v[222:225], v164 offset:53248
	ds_read_b128 v[226:229], v164 offset:54272
	ds_read_b128 v[230:233], v164 offset:55296
	ds_read_b128 v[234:237], v164 offset:56320
	ds_read_b128 v[190:193], v165
	ds_read_b128 v[194:197], v165 offset:1024
	ds_read_b128 v[198:201], v165 offset:2048
	ds_read_b128 v[202:205], v165 offset:3072
	s_waitcnt vmcnt(4)
	s_waitcnt lgkmcnt(0)
	s_barrier
	s_setprio 1
	v_mfma_f32_16x16x32_bf16 v[52:55], v[190:193], v[206:209], v[52:55]
	v_mfma_f32_16x16x32_bf16 v[48:51], v[198:201], v[206:209], v[48:51]
	v_mfma_f32_16x16x32_bf16 v[36:39], v[190:193], v[214:217], v[36:39]
	v_mfma_f32_16x16x32_bf16 v[32:35], v[198:201], v[214:217], v[32:35]
	v_mfma_f32_16x16x32_bf16 v[20:23], v[190:193], v[222:225], v[20:23]
	v_mfma_f32_16x16x32_bf16 v[16:19], v[198:201], v[222:225], v[16:19]
	v_mfma_f32_16x16x32_bf16 v[4:7], v[190:193], v[230:233], v[4:7]
	v_mfma_f32_16x16x32_bf16 v[0:3], v[198:201], v[230:233], v[0:3]
	v_mfma_f32_16x16x32_bf16 v[52:55], v[194:197], v[210:213], v[52:55]
	v_mfma_f32_16x16x32_bf16 v[48:51], v[202:205], v[210:213], v[48:51]
	v_mfma_f32_16x16x32_bf16 v[36:39], v[194:197], v[218:221], v[36:39]
	v_mfma_f32_16x16x32_bf16 v[32:35], v[202:205], v[218:221], v[32:35]
	v_mfma_f32_16x16x32_bf16 v[20:23], v[194:197], v[226:229], v[20:23]
	v_mfma_f32_16x16x32_bf16 v[16:19], v[202:205], v[226:229], v[16:19]
	v_mfma_f32_16x16x32_bf16 v[4:7], v[194:197], v[234:237], v[4:7]
	v_mfma_f32_16x16x32_bf16 v[0:3], v[202:205], v[234:237], v[0:3]
	s_setprio 0
	s_barrier
	v_add_u32_e32 v165, 0x10000, v162
	ds_read_b128 v[206:209], v164 offset:0
	ds_read_b128 v[210:213], v164 offset:1024
	ds_read_b128 v[214:217], v164 offset:2048
	ds_read_b128 v[218:221], v164 offset:3072
	ds_read_b128 v[222:225], v164 offset:4096
	ds_read_b128 v[226:229], v164 offset:5120
	ds_read_b128 v[230:233], v164 offset:6144
	ds_read_b128 v[234:237], v164 offset:7168
	ds_read_b128 v[190:193], v165
	ds_read_b128 v[194:197], v165 offset:1024
	ds_read_b128 v[198:201], v165 offset:2048
	ds_read_b128 v[202:205], v165 offset:3072
	s_waitcnt vmcnt(0)
	s_waitcnt lgkmcnt(0)
	s_barrier
	s_setprio 1
	v_mfma_f32_16x16x32_bf16 v[52:55], v[190:193], v[206:209], v[52:55]
	v_mfma_f32_16x16x32_bf16 v[48:51], v[198:201], v[206:209], v[48:51]
	v_mfma_f32_16x16x32_bf16 v[36:39], v[190:193], v[214:217], v[36:39]
	v_mfma_f32_16x16x32_bf16 v[32:35], v[198:201], v[214:217], v[32:35]
	v_mfma_f32_16x16x32_bf16 v[20:23], v[190:193], v[222:225], v[20:23]
	v_mfma_f32_16x16x32_bf16 v[16:19], v[198:201], v[222:225], v[16:19]
	v_mfma_f32_16x16x32_bf16 v[4:7], v[190:193], v[230:233], v[4:7]
	v_mfma_f32_16x16x32_bf16 v[0:3], v[198:201], v[230:233], v[0:3]
	v_mfma_f32_16x16x32_bf16 v[52:55], v[194:197], v[210:213], v[52:55]
	v_mfma_f32_16x16x32_bf16 v[48:51], v[202:205], v[210:213], v[48:51]
	v_mfma_f32_16x16x32_bf16 v[36:39], v[194:197], v[218:221], v[36:39]
	v_mfma_f32_16x16x32_bf16 v[32:35], v[202:205], v[218:221], v[32:35]
	v_mfma_f32_16x16x32_bf16 v[20:23], v[194:197], v[226:229], v[20:23]
	v_mfma_f32_16x16x32_bf16 v[16:19], v[202:205], v[226:229], v[16:19]
	v_mfma_f32_16x16x32_bf16 v[4:7], v[194:197], v[234:237], v[4:7]
	v_mfma_f32_16x16x32_bf16 v[0:3], v[202:205], v[234:237], v[0:3]
	s_setprio 0
	s_barrier
	v_add_u32_e32 v165, 0x18000, v162
	ds_read_b128 v[206:209], v164 offset:32768
	ds_read_b128 v[210:213], v164 offset:33792
	ds_read_b128 v[214:217], v164 offset:34816
	ds_read_b128 v[218:221], v164 offset:35840
	ds_read_b128 v[222:225], v164 offset:36864
	ds_read_b128 v[226:229], v164 offset:37888
	ds_read_b128 v[230:233], v164 offset:38912
	ds_read_b128 v[234:237], v164 offset:39936
	ds_read_b128 v[190:193], v165
	ds_read_b128 v[194:197], v165 offset:1024
	ds_read_b128 v[198:201], v165 offset:2048
	ds_read_b128 v[202:205], v165 offset:3072
	s_waitcnt lgkmcnt(0)
	s_barrier
	s_setprio 1
	v_mfma_f32_16x16x32_bf16 v[52:55], v[190:193], v[206:209], v[52:55]
	v_mfma_f32_16x16x32_bf16 v[48:51], v[198:201], v[206:209], v[48:51]
	v_mfma_f32_16x16x32_bf16 v[36:39], v[190:193], v[214:217], v[36:39]
	v_mfma_f32_16x16x32_bf16 v[32:35], v[198:201], v[214:217], v[32:35]
	v_mfma_f32_16x16x32_bf16 v[20:23], v[190:193], v[222:225], v[20:23]
	v_mfma_f32_16x16x32_bf16 v[16:19], v[198:201], v[222:225], v[16:19]
	v_mfma_f32_16x16x32_bf16 v[4:7], v[190:193], v[230:233], v[4:7]
	v_mfma_f32_16x16x32_bf16 v[0:3], v[198:201], v[230:233], v[0:3]
	v_mfma_f32_16x16x32_bf16 v[52:55], v[194:197], v[210:213], v[52:55]
	v_mfma_f32_16x16x32_bf16 v[48:51], v[202:205], v[210:213], v[48:51]
	v_mfma_f32_16x16x32_bf16 v[36:39], v[194:197], v[218:221], v[36:39]
	v_mfma_f32_16x16x32_bf16 v[32:35], v[202:205], v[218:221], v[32:35]
	v_mfma_f32_16x16x32_bf16 v[20:23], v[194:197], v[226:229], v[20:23]
	v_mfma_f32_16x16x32_bf16 v[16:19], v[202:205], v[226:229], v[16:19]
	v_mfma_f32_16x16x32_bf16 v[4:7], v[194:197], v[234:237], v[4:7]
	v_mfma_f32_16x16x32_bf16 v[0:3], v[202:205], v[234:237], v[0:3]
	s_setprio 0
	s_barrier
	s_branch .Lq_lin_exit

.Lq_abi_0_loop:
	s_add_u32 s74, s74, 0x100
	s_addc_u32 s75, s75, 0
	s_add_u32 s2, s2, 0x100
	s_addc_u32 s3, s3, 0
	s_waitcnt vmcnt(0)
	s_barrier
	s_barrier
	v_lshl_add_u64 v[234:235], s[74:75], 0, v[128:129]
	s_add_i32 m0, s5, 0x4000
	v_lshl_add_u64 v[236:237], s[74:75], 0, v[130:131]
	global_load_lds_dwordx4 v[234:235], off
	s_add_i32 m0, s5, 0x6000
	v_lshl_add_u64 v[238:239], s[2:3], 0, v[144:145]
	global_load_lds_dwordx4 v[236:237], off
	s_add_i32 m0, s5, 0x14000
	v_lshl_add_u64 v[240:241], s[2:3], 0, v[132:133]
	global_load_lds_dwordx4 v[238:239], off
	s_add_i32 m0, s5, 0x16000
	s_add_u32 s74, s74, 0x80
	s_addc_u32 s75, s75, 0
	global_load_lds_dwordx4 v[240:241], off
	s_add_u32 s2, s2, 0x80
	s_addc_u32 s3, s3, 0
	s_mov_b32 s8, 0
.Lq_abi_0_k:
	v_lshl_add_u64 v[234:235], s[74:75], 0, v[128:129]
	s_add_i32 m0, s5, 0xc000
	v_lshl_add_u64 v[236:237], s[74:75], 0, v[130:131]
	global_load_lds_dwordx4 v[234:235], off
	s_add_i32 m0, s5, 0xe000
	v_lshl_add_u64 v[238:239], s[2:3], 0, v[144:145]
	global_load_lds_dwordx4 v[236:237], off
	s_add_i32 m0, s5, 0x1c000
	v_lshl_add_u64 v[240:241], s[2:3], 0, v[132:133]
	global_load_lds_dwordx4 v[238:239], off
	s_add_i32 m0, s5, 0x1e000
	s_add_u32 s74, s74, 0x80
	s_addc_u32 s75, s75, 0
	global_load_lds_dwordx4 v[240:241], off
	s_add_u32 s2, s2, 0x80
	s_addc_u32 s3, s3, 0
	v_add_u32_e32 v142, 0x10000, v160
	ds_read_b128 v[202:205], v162 offset:0
	ds_read_b128 v[206:209], v162 offset:1024
	ds_read_b128 v[210:213], v162 offset:2048
	ds_read_b128 v[214:217], v162 offset:3072
	ds_read_b128 v[218:221], v162 offset:4096
	ds_read_b128 v[222:225], v162 offset:5120
	ds_read_b128 v[226:229], v162 offset:6144
	ds_read_b128 v[230:233], v162 offset:7168
	ds_read_b128 v[138:141], v142
	ds_read_b128 v[164:167], v142 offset:1024
	ds_read_b128 v[168:171], v142 offset:2048
	ds_read_b128 v[172:175], v142 offset:3072
	s_waitcnt vmcnt(8)
	s_waitcnt lgkmcnt(0)
	s_barrier
	s_setprio 1
	v_mfma_f32_16x16x32_bf16 v[124:127], v[138:141], v[202:205], v[124:127]
	v_mfma_f32_16x16x32_bf16 v[120:123], v[168:171], v[202:205], v[120:123]
	v_mfma_f32_16x16x32_bf16 v[108:111], v[138:141], v[210:213], v[108:111]
	v_mfma_f32_16x16x32_bf16 v[104:107], v[168:171], v[210:213], v[104:107]
	v_mfma_f32_16x16x32_bf16 v[92:95], v[138:141], v[218:221], v[92:95]
	v_mfma_f32_16x16x32_bf16 v[88:91], v[168:171], v[218:221], v[88:91]
	v_mfma_f32_16x16x32_bf16 v[76:79], v[138:141], v[226:229], v[76:79]
	v_mfma_f32_16x16x32_bf16 v[72:75], v[168:171], v[226:229], v[72:75]
	v_mfma_f32_16x16x32_bf16 v[124:127], v[164:167], v[206:209], v[124:127]
	v_mfma_f32_16x16x32_bf16 v[120:123], v[172:175], v[206:209], v[120:123]
	v_mfma_f32_16x16x32_bf16 v[108:111], v[164:167], v[214:217], v[108:111]
	v_mfma_f32_16x16x32_bf16 v[104:107], v[172:175], v[214:217], v[104:107]
	v_mfma_f32_16x16x32_bf16 v[92:95], v[164:167], v[222:225], v[92:95]
	v_mfma_f32_16x16x32_bf16 v[88:91], v[172:175], v[222:225], v[88:91]
	v_mfma_f32_16x16x32_bf16 v[76:79], v[164:167], v[230:233], v[76:79]
	v_mfma_f32_16x16x32_bf16 v[72:75], v[172:175], v[230:233], v[72:75]
	s_setprio 0
	s_barrier
	v_lshl_add_u64 v[234:235], s[74:75], 0, v[128:129]
	s_add_i32 m0, s5, 0x0
	v_lshl_add_u64 v[236:237], s[74:75], 0, v[130:131]
	global_load_lds_dwordx4 v[234:235], off
	s_add_i32 m0, s5, 0x2000
	v_lshl_add_u64 v[238:239], s[2:3], 0, v[144:145]
	global_load_lds_dwordx4 v[236:237], off
	s_add_i32 m0, s5, 0x10000
	v_lshl_add_u64 v[240:241], s[2:3], 0, v[132:133]
	global_load_lds_dwordx4 v[238:239], off
	s_add_i32 m0, s5, 0x12000
	s_add_u32 s74, s74, 0x80
	s_addc_u32 s75, s75, 0
	global_load_lds_dwordx4 v[240:241], off
	s_add_u32 s2, s2, 0x80
	s_addc_u32 s3, s3, 0
	v_add_u32_e32 v142, 0x18000, v160
	ds_read_b128 v[202:205], v162 offset:32768
	ds_read_b128 v[206:209], v162 offset:33792
	ds_read_b128 v[210:213], v162 offset:34816
	ds_read_b128 v[214:217], v162 offset:35840
	ds_read_b128 v[218:221], v162 offset:36864
	ds_read_b128 v[222:225], v162 offset:37888
	ds_read_b128 v[226:229], v162 offset:38912
	ds_read_b128 v[230:233], v162 offset:39936
	ds_read_b128 v[138:141], v142
	ds_read_b128 v[164:167], v142 offset:1024
	ds_read_b128 v[168:171], v142 offset:2048
	ds_read_b128 v[172:175], v142 offset:3072
	s_waitcnt vmcnt(8)
	s_waitcnt lgkmcnt(0)
	s_barrier
	s_setprio 1
	v_mfma_f32_16x16x32_bf16 v[124:127], v[138:141], v[202:205], v[124:127]
	v_mfma_f32_16x16x32_bf16 v[120:123], v[168:171], v[202:205], v[120:123]
	v_mfma_f32_16x16x32_bf16 v[108:111], v[138:141], v[210:213], v[108:111]
	v_mfma_f32_16x16x32_bf16 v[104:107], v[168:171], v[210:213], v[104:107]
	v_mfma_f32_16x16x32_bf16 v[92:95], v[138:141], v[218:221], v[92:95]
	v_mfma_f32_16x16x32_bf16 v[88:91], v[168:171], v[218:221], v[88:91]
	v_mfma_f32_16x16x32_bf16 v[76:79], v[138:141], v[226:229], v[76:79]
	v_mfma_f32_16x16x32_bf16 v[72:75], v[168:171], v[226:229], v[72:75]
	v_mfma_f32_16x16x32_bf16 v[124:127], v[164:167], v[206:209], v[124:127]
	v_mfma_f32_16x16x32_bf16 v[120:123], v[172:175], v[206:209], v[120:123]
	v_mfma_f32_16x16x32_bf16 v[108:111], v[164:167], v[214:217], v[108:111]
	v_mfma_f32_16x16x32_bf16 v[104:107], v[172:175], v[214:217], v[104:107]
	v_mfma_f32_16x16x32_bf16 v[92:95], v[164:167], v[222:225], v[92:95]
	v_mfma_f32_16x16x32_bf16 v[88:91], v[172:175], v[222:225], v[88:91]
	v_mfma_f32_16x16x32_bf16 v[76:79], v[164:167], v[230:233], v[76:79]
	v_mfma_f32_16x16x32_bf16 v[72:75], v[172:175], v[230:233], v[72:75]
	s_setprio 0
	s_barrier
	v_lshl_add_u64 v[234:235], s[74:75], 0, v[128:129]
	s_add_i32 m0, s5, 0x8000
	v_lshl_add_u64 v[236:237], s[74:75], 0, v[130:131]
	global_load_lds_dwordx4 v[234:235], off
	s_add_i32 m0, s5, 0xa000
	v_lshl_add_u64 v[238:239], s[2:3], 0, v[144:145]
	global_load_lds_dwordx4 v[236:237], off
	s_add_i32 m0, s5, 0x18000
	v_lshl_add_u64 v[240:241], s[2:3], 0, v[132:133]
	global_load_lds_dwordx4 v[238:239], off
	s_add_i32 m0, s5, 0x1a000
	s_add_u32 s74, s74, 0x80
	s_addc_u32 s75, s75, 0
	global_load_lds_dwordx4 v[240:241], off
	s_add_u32 s2, s2, 0x80
	s_addc_u32 s3, s3, 0
	v_add_u32_e32 v142, 0x14000, v160
	ds_read_b128 v[202:205], v162 offset:16384
	ds_read_b128 v[206:209], v162 offset:17408
	ds_read_b128 v[210:213], v162 offset:18432
	ds_read_b128 v[214:217], v162 offset:19456
	ds_read_b128 v[218:221], v162 offset:20480
	ds_read_b128 v[222:225], v162 offset:21504
	ds_read_b128 v[226:229], v162 offset:22528
	ds_read_b128 v[230:233], v162 offset:23552
	ds_read_b128 v[138:141], v142
	ds_read_b128 v[164:167], v142 offset:1024
	ds_read_b128 v[168:171], v142 offset:2048
	ds_read_b128 v[172:175], v142 offset:3072
	s_waitcnt vmcnt(8)
	s_waitcnt lgkmcnt(0)
	s_barrier
	s_setprio 1
	v_mfma_f32_16x16x32_bf16 v[124:127], v[138:141], v[202:205], v[124:127]
	v_mfma_f32_16x16x32_bf16 v[120:123], v[168:171], v[202:205], v[120:123]
	v_mfma_f32_16x16x32_bf16 v[108:111], v[138:141], v[210:213], v[108:111]
	v_mfma_f32_16x16x32_bf16 v[104:107], v[168:171], v[210:213], v[104:107]
	v_mfma_f32_16x16x32_bf16 v[92:95], v[138:141], v[218:221], v[92:95]
	v_mfma_f32_16x16x32_bf16 v[88:91], v[168:171], v[218:221], v[88:91]
	v_mfma_f32_16x16x32_bf16 v[76:79], v[138:141], v[226:229], v[76:79]
	v_mfma_f32_16x16x32_bf16 v[72:75], v[168:171], v[226:229], v[72:75]
	v_mfma_f32_16x16x32_bf16 v[124:127], v[164:167], v[206:209], v[124:127]
	v_mfma_f32_16x16x32_bf16 v[120:123], v[172:175], v[206:209], v[120:123]
	v_mfma_f32_16x16x32_bf16 v[108:111], v[164:167], v[214:217], v[108:111]
	v_mfma_f32_16x16x32_bf16 v[104:107], v[172:175], v[214:217], v[104:107]
	v_mfma_f32_16x16x32_bf16 v[92:95], v[164:167], v[222:225], v[92:95]
	v_mfma_f32_16x16x32_bf16 v[88:91], v[172:175], v[222:225], v[88:91]
	v_mfma_f32_16x16x32_bf16 v[76:79], v[164:167], v[230:233], v[76:79]
	v_mfma_f32_16x16x32_bf16 v[72:75], v[172:175], v[230:233], v[72:75]
	s_setprio 0
	s_barrier
	v_lshl_add_u64 v[234:235], s[74:75], 0, v[128:129]
	s_add_i32 m0, s5, 0x4000
	v_lshl_add_u64 v[236:237], s[74:75], 0, v[130:131]
	global_load_lds_dwordx4 v[234:235], off
	s_add_i32 m0, s5, 0x6000
	v_lshl_add_u64 v[238:239], s[2:3], 0, v[144:145]
	global_load_lds_dwordx4 v[236:237], off
	s_add_i32 m0, s5, 0x14000
	v_lshl_add_u64 v[240:241], s[2:3], 0, v[132:133]
	global_load_lds_dwordx4 v[238:239], off
	s_add_i32 m0, s5, 0x16000
	s_add_u32 s74, s74, 0x80
	s_addc_u32 s75, s75, 0
	global_load_lds_dwordx4 v[240:241], off
	s_add_u32 s2, s2, 0x80
	s_addc_u32 s3, s3, 0
	v_add_u32_e32 v142, 0x1c000, v160
	ds_read_b128 v[202:205], v162 offset:49152
	ds_read_b128 v[206:209], v162 offset:50176
	ds_read_b128 v[210:213], v162 offset:51200
	ds_read_b128 v[214:217], v162 offset:52224
	ds_read_b128 v[218:221], v162 offset:53248
	ds_read_b128 v[222:225], v162 offset:54272
	ds_read_b128 v[226:229], v162 offset:55296
	ds_read_b128 v[230:233], v162 offset:56320
	ds_read_b128 v[138:141], v142
	ds_read_b128 v[164:167], v142 offset:1024
	ds_read_b128 v[168:171], v142 offset:2048
	ds_read_b128 v[172:175], v142 offset:3072
	s_waitcnt vmcnt(8)
	s_waitcnt lgkmcnt(0)
	s_barrier
	s_setprio 1
	v_mfma_f32_16x16x32_bf16 v[124:127], v[138:141], v[202:205], v[124:127]
	v_mfma_f32_16x16x32_bf16 v[120:123], v[168:171], v[202:205], v[120:123]
	v_mfma_f32_16x16x32_bf16 v[108:111], v[138:141], v[210:213], v[108:111]
	v_mfma_f32_16x16x32_bf16 v[104:107], v[168:171], v[210:213], v[104:107]
	v_mfma_f32_16x16x32_bf16 v[92:95], v[138:141], v[218:221], v[92:95]
	v_mfma_f32_16x16x32_bf16 v[88:91], v[168:171], v[218:221], v[88:91]
	v_mfma_f32_16x16x32_bf16 v[76:79], v[138:141], v[226:229], v[76:79]
	v_mfma_f32_16x16x32_bf16 v[72:75], v[168:171], v[226:229], v[72:75]
	v_mfma_f32_16x16x32_bf16 v[124:127], v[164:167], v[206:209], v[124:127]
	v_mfma_f32_16x16x32_bf16 v[120:123], v[172:175], v[206:209], v[120:123]
	v_mfma_f32_16x16x32_bf16 v[108:111], v[164:167], v[214:217], v[108:111]
	v_mfma_f32_16x16x32_bf16 v[104:107], v[172:175], v[214:217], v[104:107]
	v_mfma_f32_16x16x32_bf16 v[92:95], v[164:167], v[222:225], v[92:95]
	v_mfma_f32_16x16x32_bf16 v[88:91], v[172:175], v[222:225], v[88:91]
	v_mfma_f32_16x16x32_bf16 v[76:79], v[164:167], v[230:233], v[76:79]
	v_mfma_f32_16x16x32_bf16 v[72:75], v[172:175], v[230:233], v[72:75]
	s_setprio 0
	s_barrier
	s_add_i32 s8, s8, 1
	s_cmp_lt_u32 s8, 7
	s_cbranch_scc1 .Lq_abi_0_k
	v_lshl_add_u64 v[234:235], s[74:75], 0, v[128:129]
	s_add_i32 m0, s5, 0xc000
	v_lshl_add_u64 v[236:237], s[74:75], 0, v[130:131]
	global_load_lds_dwordx4 v[234:235], off
	s_add_i32 m0, s5, 0xe000
	v_lshl_add_u64 v[238:239], s[2:3], 0, v[144:145]
	global_load_lds_dwordx4 v[236:237], off
	s_add_i32 m0, s5, 0x1c000
	v_lshl_add_u64 v[240:241], s[2:3], 0, v[132:133]
	global_load_lds_dwordx4 v[238:239], off
	s_add_i32 m0, s5, 0x1e000
	s_add_u32 s74, s74, 0x80
	s_addc_u32 s75, s75, 0
	global_load_lds_dwordx4 v[240:241], off
	s_add_u32 s2, s2, 0x80
	s_addc_u32 s3, s3, 0
	v_add_u32_e32 v142, 0x10000, v160
	ds_read_b128 v[202:205], v162 offset:0
	ds_read_b128 v[206:209], v162 offset:1024
	ds_read_b128 v[210:213], v162 offset:2048
	ds_read_b128 v[214:217], v162 offset:3072
	ds_read_b128 v[218:221], v162 offset:4096
	ds_read_b128 v[222:225], v162 offset:5120
	ds_read_b128 v[226:229], v162 offset:6144
	ds_read_b128 v[230:233], v162 offset:7168
	ds_read_b128 v[138:141], v142
	ds_read_b128 v[164:167], v142 offset:1024
	ds_read_b128 v[168:171], v142 offset:2048
	ds_read_b128 v[172:175], v142 offset:3072
	s_waitcnt vmcnt(8)
	s_waitcnt lgkmcnt(0)
	s_barrier
	s_setprio 1
	v_mfma_f32_16x16x32_bf16 v[124:127], v[138:141], v[202:205], v[124:127]
	v_mfma_f32_16x16x32_bf16 v[120:123], v[168:171], v[202:205], v[120:123]
	v_mfma_f32_16x16x32_bf16 v[108:111], v[138:141], v[210:213], v[108:111]
	v_mfma_f32_16x16x32_bf16 v[104:107], v[168:171], v[210:213], v[104:107]
	v_mfma_f32_16x16x32_bf16 v[92:95], v[138:141], v[218:221], v[92:95]
	v_mfma_f32_16x16x32_bf16 v[88:91], v[168:171], v[218:221], v[88:91]
	v_mfma_f32_16x16x32_bf16 v[76:79], v[138:141], v[226:229], v[76:79]
	v_mfma_f32_16x16x32_bf16 v[72:75], v[168:171], v[226:229], v[72:75]
	v_mfma_f32_16x16x32_bf16 v[124:127], v[164:167], v[206:209], v[124:127]
	v_mfma_f32_16x16x32_bf16 v[120:123], v[172:175], v[206:209], v[120:123]
	v_mfma_f32_16x16x32_bf16 v[108:111], v[164:167], v[214:217], v[108:111]
	v_mfma_f32_16x16x32_bf16 v[104:107], v[172:175], v[214:217], v[104:107]
	v_mfma_f32_16x16x32_bf16 v[92:95], v[164:167], v[222:225], v[92:95]
	v_mfma_f32_16x16x32_bf16 v[88:91], v[172:175], v[222:225], v[88:91]
	v_mfma_f32_16x16x32_bf16 v[76:79], v[164:167], v[230:233], v[76:79]
	v_mfma_f32_16x16x32_bf16 v[72:75], v[172:175], v[230:233], v[72:75]
	s_setprio 0
	s_barrier
	v_add_u32_e32 v142, 0x18000, v160
	ds_read_b128 v[202:205], v162 offset:32768
	ds_read_b128 v[206:209], v162 offset:33792
	ds_read_b128 v[210:213], v162 offset:34816
	ds_read_b128 v[214:217], v162 offset:35840
	ds_read_b128 v[218:221], v162 offset:36864
	ds_read_b128 v[222:225], v162 offset:37888
	ds_read_b128 v[226:229], v162 offset:38912
	ds_read_b128 v[230:233], v162 offset:39936
	ds_read_b128 v[138:141], v142
	ds_read_b128 v[164:167], v142 offset:1024
	ds_read_b128 v[168:171], v142 offset:2048
	ds_read_b128 v[172:175], v142 offset:3072
	s_waitcnt vmcnt(4)
	s_waitcnt lgkmcnt(0)
	s_barrier
	s_setprio 1
	v_mfma_f32_16x16x32_bf16 v[124:127], v[138:141], v[202:205], v[124:127]
	v_mfma_f32_16x16x32_bf16 v[120:123], v[168:171], v[202:205], v[120:123]
	v_mfma_f32_16x16x32_bf16 v[108:111], v[138:141], v[210:213], v[108:111]
	v_mfma_f32_16x16x32_bf16 v[104:107], v[168:171], v[210:213], v[104:107]
	v_mfma_f32_16x16x32_bf16 v[92:95], v[138:141], v[218:221], v[92:95]
	v_mfma_f32_16x16x32_bf16 v[88:91], v[168:171], v[218:221], v[88:91]
	v_mfma_f32_16x16x32_bf16 v[76:79], v[138:141], v[226:229], v[76:79]
	v_mfma_f32_16x16x32_bf16 v[72:75], v[168:171], v[226:229], v[72:75]
	v_mfma_f32_16x16x32_bf16 v[124:127], v[164:167], v[206:209], v[124:127]
	v_mfma_f32_16x16x32_bf16 v[120:123], v[172:175], v[206:209], v[120:123]
	v_mfma_f32_16x16x32_bf16 v[108:111], v[164:167], v[214:217], v[108:111]
	v_mfma_f32_16x16x32_bf16 v[104:107], v[172:175], v[214:217], v[104:107]
	v_mfma_f32_16x16x32_bf16 v[92:95], v[164:167], v[222:225], v[92:95]
	v_mfma_f32_16x16x32_bf16 v[88:91], v[172:175], v[222:225], v[88:91]
	v_mfma_f32_16x16x32_bf16 v[76:79], v[164:167], v[230:233], v[76:79]
	v_mfma_f32_16x16x32_bf16 v[72:75], v[172:175], v[230:233], v[72:75]
	s_setprio 0
	s_barrier
	v_add_u32_e32 v142, 0x14000, v160
	ds_read_b128 v[202:205], v162 offset:16384
	ds_read_b128 v[206:209], v162 offset:17408
	ds_read_b128 v[210:213], v162 offset:18432
	ds_read_b128 v[214:217], v162 offset:19456
	ds_read_b128 v[218:221], v162 offset:20480
	ds_read_b128 v[222:225], v162 offset:21504
	ds_read_b128 v[226:229], v162 offset:22528
	ds_read_b128 v[230:233], v162 offset:23552
	ds_read_b128 v[138:141], v142
	ds_read_b128 v[164:167], v142 offset:1024
	ds_read_b128 v[168:171], v142 offset:2048
	ds_read_b128 v[172:175], v142 offset:3072
	s_waitcnt vmcnt(0)
	s_waitcnt lgkmcnt(0)
	s_barrier
	s_setprio 1
	v_mfma_f32_16x16x32_bf16 v[124:127], v[138:141], v[202:205], v[124:127]
	v_mfma_f32_16x16x32_bf16 v[120:123], v[168:171], v[202:205], v[120:123]
	v_mfma_f32_16x16x32_bf16 v[108:111], v[138:141], v[210:213], v[108:111]
	v_mfma_f32_16x16x32_bf16 v[104:107], v[168:171], v[210:213], v[104:107]
	v_mfma_f32_16x16x32_bf16 v[92:95], v[138:141], v[218:221], v[92:95]
	v_mfma_f32_16x16x32_bf16 v[88:91], v[168:171], v[218:221], v[88:91]
	v_mfma_f32_16x16x32_bf16 v[76:79], v[138:141], v[226:229], v[76:79]
	v_mfma_f32_16x16x32_bf16 v[72:75], v[168:171], v[226:229], v[72:75]
	v_mfma_f32_16x16x32_bf16 v[124:127], v[164:167], v[206:209], v[124:127]
	v_mfma_f32_16x16x32_bf16 v[120:123], v[172:175], v[206:209], v[120:123]
	v_mfma_f32_16x16x32_bf16 v[108:111], v[164:167], v[214:217], v[108:111]
	v_mfma_f32_16x16x32_bf16 v[104:107], v[172:175], v[214:217], v[104:107]
	v_mfma_f32_16x16x32_bf16 v[92:95], v[164:167], v[222:225], v[92:95]
	v_mfma_f32_16x16x32_bf16 v[88:91], v[172:175], v[222:225], v[88:91]
	v_mfma_f32_16x16x32_bf16 v[76:79], v[164:167], v[230:233], v[76:79]
	v_mfma_f32_16x16x32_bf16 v[72:75], v[172:175], v[230:233], v[72:75]
	s_setprio 0
	s_barrier
	v_add_u32_e32 v142, 0x1c000, v160
	ds_read_b128 v[202:205], v162 offset:49152
	ds_read_b128 v[206:209], v162 offset:50176
	ds_read_b128 v[210:213], v162 offset:51200
	ds_read_b128 v[214:217], v162 offset:52224
	ds_read_b128 v[218:221], v162 offset:53248
	ds_read_b128 v[222:225], v162 offset:54272
	ds_read_b128 v[226:229], v162 offset:55296
	ds_read_b128 v[230:233], v162 offset:56320
	ds_read_b128 v[138:141], v142
	ds_read_b128 v[164:167], v142 offset:1024
	ds_read_b128 v[168:171], v142 offset:2048
	ds_read_b128 v[172:175], v142 offset:3072
	s_waitcnt lgkmcnt(0)
	s_barrier
	s_setprio 1
	v_mfma_f32_16x16x32_bf16 v[124:127], v[138:141], v[202:205], v[124:127]
	v_mfma_f32_16x16x32_bf16 v[120:123], v[168:171], v[202:205], v[120:123]
	v_mfma_f32_16x16x32_bf16 v[108:111], v[138:141], v[210:213], v[108:111]
	v_mfma_f32_16x16x32_bf16 v[104:107], v[168:171], v[210:213], v[104:107]
	v_mfma_f32_16x16x32_bf16 v[92:95], v[138:141], v[218:221], v[92:95]
	v_mfma_f32_16x16x32_bf16 v[88:91], v[168:171], v[218:221], v[88:91]
	v_mfma_f32_16x16x32_bf16 v[76:79], v[138:141], v[226:229], v[76:79]
	v_mfma_f32_16x16x32_bf16 v[72:75], v[168:171], v[226:229], v[72:75]
	v_mfma_f32_16x16x32_bf16 v[124:127], v[164:167], v[206:209], v[124:127]
	v_mfma_f32_16x16x32_bf16 v[120:123], v[172:175], v[206:209], v[120:123]
	v_mfma_f32_16x16x32_bf16 v[108:111], v[164:167], v[214:217], v[108:111]
	v_mfma_f32_16x16x32_bf16 v[104:107], v[172:175], v[214:217], v[104:107]
	v_mfma_f32_16x16x32_bf16 v[92:95], v[164:167], v[222:225], v[92:95]
	v_mfma_f32_16x16x32_bf16 v[88:91], v[172:175], v[222:225], v[88:91]
	v_mfma_f32_16x16x32_bf16 v[76:79], v[164:167], v[230:233], v[76:79]
	v_mfma_f32_16x16x32_bf16 v[72:75], v[172:175], v[230:233], v[72:75]
	s_setprio 0
	s_barrier
	s_branch .Lq_abi_exit
.Lq_abi_1_loop:
	s_add_u32 s74, s74, 0x100
	s_addc_u32 s75, s75, 0
	s_add_u32 s2, s2, 0x80100
	s_addc_u32 s3, s3, 0
	s_waitcnt vmcnt(0)
	s_barrier
	s_barrier
	v_lshl_add_u64 v[234:235], s[74:75], 0, v[128:129]
	s_add_i32 m0, s5, 0x4000
	v_lshl_add_u64 v[236:237], s[74:75], 0, v[130:131]
	global_load_lds_dwordx4 v[234:235], off
	s_add_i32 m0, s5, 0x6000
	v_lshl_add_u64 v[238:239], s[2:3], 0, v[144:145]
	global_load_lds_dwordx4 v[236:237], off
	s_add_i32 m0, s5, 0x10000
	v_lshl_add_u64 v[240:241], s[2:3], 0, v[132:133]
	global_load_lds_dwordx4 v[238:239], off
	s_add_i32 m0, s5, 0x12000
	s_add_u32 s74, s74, 0x80
	s_addc_u32 s75, s75, 0
	global_load_lds_dwordx4 v[240:241], off
	s_add_u32 s2, s2, 0x80
	s_addc_u32 s3, s3, 0
	s_mov_b32 s8, 0
.Lq_abi_1_k:
	v_lshl_add_u64 v[234:235], s[74:75], 0, v[128:129]
	s_add_i32 m0, s5, 0xc000
	v_lshl_add_u64 v[236:237], s[74:75], 0, v[130:131]
	global_load_lds_dwordx4 v[234:235], off
	s_add_i32 m0, s5, 0xe000
	v_lshl_add_u64 v[238:239], s[2:3], 0, v[144:145]
	global_load_lds_dwordx4 v[236:237], off
	s_add_i32 m0, s5, 0x18000
	v_lshl_add_u64 v[240:241], s[2:3], 0, v[132:133]
	global_load_lds_dwordx4 v[238:239], off
	s_add_i32 m0, s5, 0x1a000
	s_add_u32 s74, s74, 0x80
	s_addc_u32 s75, s75, 0
	global_load_lds_dwordx4 v[240:241], off
	s_add_u32 s2, s2, 0x80
	s_addc_u32 s3, s3, 0
	v_add_u32_e32 v142, 0x14000, v160
	ds_read_b128 v[202:205], v162 offset:0
	ds_read_b128 v[206:209], v162 offset:1024
	ds_read_b128 v[210:213], v162 offset:2048
	ds_read_b128 v[214:217], v162 offset:3072
	ds_read_b128 v[218:221], v162 offset:4096
	ds_read_b128 v[222:225], v162 offset:5120
	ds_read_b128 v[226:229], v162 offset:6144
	ds_read_b128 v[230:233], v162 offset:7168
	ds_read_b128 v[176:179], v142
	ds_read_b128 v[190:193], v142 offset:1024
	ds_read_b128 v[194:197], v142 offset:2048
	ds_read_b128 v[198:201], v142 offset:3072
	s_waitcnt vmcnt(8)
	s_waitcnt lgkmcnt(0)
	s_barrier
	s_setprio 1
	v_mfma_f32_16x16x32_bf16 v[116:119], v[176:179], v[202:205], v[116:119]
	v_mfma_f32_16x16x32_bf16 v[112:115], v[194:197], v[202:205], v[112:115]
	v_mfma_f32_16x16x32_bf16 v[100:103], v[176:179], v[210:213], v[100:103]
	v_mfma_f32_16x16x32_bf16 v[96:99], v[194:197], v[210:213], v[96:99]
	v_mfma_f32_16x16x32_bf16 v[84:87], v[176:179], v[218:221], v[84:87]
	v_mfma_f32_16x16x32_bf16 v[80:83], v[194:197], v[218:221], v[80:83]
	v_mfma_f32_16x16x32_bf16 v[68:71], v[176:179], v[226:229], v[68:71]
	v_mfma_f32_16x16x32_bf16 v[64:67], v[194:197], v[226:229], v[64:67]
	v_mfma_f32_16x16x32_bf16 v[116:119], v[190:193], v[206:209], v[116:119]
	v_mfma_f32_16x16x32_bf16 v[112:115], v[198:201], v[206:209], v[112:115]
	v_mfma_f32_16x16x32_bf16 v[100:103], v[190:193], v[214:217], v[100:103]
	v_mfma_f32_16x16x32_bf16 v[96:99], v[198:201], v[214:217], v[96:99]
	v_mfma_f32_16x16x32_bf16 v[84:87], v[190:193], v[222:225], v[84:87]
	v_mfma_f32_16x16x32_bf16 v[80:83], v[198:201], v[222:225], v[80:83]
	v_mfma_f32_16x16x32_bf16 v[68:71], v[190:193], v[230:233], v[68:71]
	v_mfma_f32_16x16x32_bf16 v[64:67], v[198:201], v[230:233], v[64:67]
	s_setprio 0
	s_barrier
	v_lshl_add_u64 v[234:235], s[74:75], 0, v[128:129]
	s_add_i32 m0, s5, 0x0
	v_lshl_add_u64 v[236:237], s[74:75], 0, v[130:131]
	global_load_lds_dwordx4 v[234:235], off
	s_add_i32 m0, s5, 0x2000
	v_lshl_add_u64 v[238:239], s[2:3], 0, v[144:145]
	global_load_lds_dwordx4 v[236:237], off
	s_add_i32 m0, s5, 0x14000
	v_lshl_add_u64 v[240:241], s[2:3], 0, v[132:133]
	global_load_lds_dwordx4 v[238:239], off
	s_add_i32 m0, s5, 0x16000
	s_add_u32 s74, s74, 0x80
	s_addc_u32 s75, s75, 0
	global_load_lds_dwordx4 v[240:241], off
	s_add_u32 s2, s2, 0x80
	s_addc_u32 s3, s3, 0
	v_add_u32_e32 v142, 0x1c000, v160
	ds_read_b128 v[202:205], v162 offset:32768
	ds_read_b128 v[206:209], v162 offset:33792
	ds_read_b128 v[210:213], v162 offset:34816
	ds_read_b128 v[214:217], v162 offset:35840
	ds_read_b128 v[218:221], v162 offset:36864
	ds_read_b128 v[222:225], v162 offset:37888
	ds_read_b128 v[226:229], v162 offset:38912
	ds_read_b128 v[230:233], v162 offset:39936
	ds_read_b128 v[176:179], v142
	ds_read_b128 v[190:193], v142 offset:1024
	ds_read_b128 v[194:197], v142 offset:2048
	ds_read_b128 v[198:201], v142 offset:3072
	s_waitcnt vmcnt(8)
	s_waitcnt lgkmcnt(0)
	s_barrier
	s_setprio 1
	v_mfma_f32_16x16x32_bf16 v[116:119], v[176:179], v[202:205], v[116:119]
	v_mfma_f32_16x16x32_bf16 v[112:115], v[194:197], v[202:205], v[112:115]
	v_mfma_f32_16x16x32_bf16 v[100:103], v[176:179], v[210:213], v[100:103]
	v_mfma_f32_16x16x32_bf16 v[96:99], v[194:197], v[210:213], v[96:99]
	v_mfma_f32_16x16x32_bf16 v[84:87], v[176:179], v[218:221], v[84:87]
	v_mfma_f32_16x16x32_bf16 v[80:83], v[194:197], v[218:221], v[80:83]
	v_mfma_f32_16x16x32_bf16 v[68:71], v[176:179], v[226:229], v[68:71]
	v_mfma_f32_16x16x32_bf16 v[64:67], v[194:197], v[226:229], v[64:67]
	v_mfma_f32_16x16x32_bf16 v[116:119], v[190:193], v[206:209], v[116:119]
	v_mfma_f32_16x16x32_bf16 v[112:115], v[198:201], v[206:209], v[112:115]
	v_mfma_f32_16x16x32_bf16 v[100:103], v[190:193], v[214:217], v[100:103]
	v_mfma_f32_16x16x32_bf16 v[96:99], v[198:201], v[214:217], v[96:99]
	v_mfma_f32_16x16x32_bf16 v[84:87], v[190:193], v[222:225], v[84:87]
	v_mfma_f32_16x16x32_bf16 v[80:83], v[198:201], v[222:225], v[80:83]
	v_mfma_f32_16x16x32_bf16 v[68:71], v[190:193], v[230:233], v[68:71]
	v_mfma_f32_16x16x32_bf16 v[64:67], v[198:201], v[230:233], v[64:67]
	s_setprio 0
	s_barrier
	v_lshl_add_u64 v[234:235], s[74:75], 0, v[128:129]
	s_add_i32 m0, s5, 0x8000
	v_lshl_add_u64 v[236:237], s[74:75], 0, v[130:131]
	global_load_lds_dwordx4 v[234:235], off
	s_add_i32 m0, s5, 0xa000
	v_lshl_add_u64 v[238:239], s[2:3], 0, v[144:145]
	global_load_lds_dwordx4 v[236:237], off
	s_add_i32 m0, s5, 0x1c000
	v_lshl_add_u64 v[240:241], s[2:3], 0, v[132:133]
	global_load_lds_dwordx4 v[238:239], off
	s_add_i32 m0, s5, 0x1e000
	s_add_u32 s74, s74, 0x80
	s_addc_u32 s75, s75, 0
	global_load_lds_dwordx4 v[240:241], off
	s_add_u32 s2, s2, 0x80
	s_addc_u32 s3, s3, 0
	v_add_u32_e32 v142, 0x10000, v160
	ds_read_b128 v[202:205], v162 offset:16384
	ds_read_b128 v[206:209], v162 offset:17408
	ds_read_b128 v[210:213], v162 offset:18432
	ds_read_b128 v[214:217], v162 offset:19456
	ds_read_b128 v[218:221], v162 offset:20480
	ds_read_b128 v[222:225], v162 offset:21504
	ds_read_b128 v[226:229], v162 offset:22528
	ds_read_b128 v[230:233], v162 offset:23552
	ds_read_b128 v[176:179], v142
	ds_read_b128 v[190:193], v142 offset:1024
	ds_read_b128 v[194:197], v142 offset:2048
	ds_read_b128 v[198:201], v142 offset:3072
	s_waitcnt vmcnt(8)
	s_waitcnt lgkmcnt(0)
	s_barrier
	s_setprio 1
	v_mfma_f32_16x16x32_bf16 v[116:119], v[176:179], v[202:205], v[116:119]
	v_mfma_f32_16x16x32_bf16 v[112:115], v[194:197], v[202:205], v[112:115]
	v_mfma_f32_16x16x32_bf16 v[100:103], v[176:179], v[210:213], v[100:103]
	v_mfma_f32_16x16x32_bf16 v[96:99], v[194:197], v[210:213], v[96:99]
	v_mfma_f32_16x16x32_bf16 v[84:87], v[176:179], v[218:221], v[84:87]
	v_mfma_f32_16x16x32_bf16 v[80:83], v[194:197], v[218:221], v[80:83]
	v_mfma_f32_16x16x32_bf16 v[68:71], v[176:179], v[226:229], v[68:71]
	v_mfma_f32_16x16x32_bf16 v[64:67], v[194:197], v[226:229], v[64:67]
	v_mfma_f32_16x16x32_bf16 v[116:119], v[190:193], v[206:209], v[116:119]
	v_mfma_f32_16x16x32_bf16 v[112:115], v[198:201], v[206:209], v[112:115]
	v_mfma_f32_16x16x32_bf16 v[100:103], v[190:193], v[214:217], v[100:103]
	v_mfma_f32_16x16x32_bf16 v[96:99], v[198:201], v[214:217], v[96:99]
	v_mfma_f32_16x16x32_bf16 v[84:87], v[190:193], v[222:225], v[84:87]
	v_mfma_f32_16x16x32_bf16 v[80:83], v[198:201], v[222:225], v[80:83]
	v_mfma_f32_16x16x32_bf16 v[68:71], v[190:193], v[230:233], v[68:71]
	v_mfma_f32_16x16x32_bf16 v[64:67], v[198:201], v[230:233], v[64:67]
	s_setprio 0
	s_barrier
	v_lshl_add_u64 v[234:235], s[74:75], 0, v[128:129]
	s_add_i32 m0, s5, 0x4000
	v_lshl_add_u64 v[236:237], s[74:75], 0, v[130:131]
	global_load_lds_dwordx4 v[234:235], off
	s_add_i32 m0, s5, 0x6000
	v_lshl_add_u64 v[238:239], s[2:3], 0, v[144:145]
	global_load_lds_dwordx4 v[236:237], off
	s_add_i32 m0, s5, 0x10000
	v_lshl_add_u64 v[240:241], s[2:3], 0, v[132:133]
	global_load_lds_dwordx4 v[238:239], off
	s_add_i32 m0, s5, 0x12000
	s_add_u32 s74, s74, 0x80
	s_addc_u32 s75, s75, 0
	global_load_lds_dwordx4 v[240:241], off
	s_add_u32 s2, s2, 0x80
	s_addc_u32 s3, s3, 0
	v_add_u32_e32 v142, 0x18000, v160
	ds_read_b128 v[202:205], v162 offset:49152
	ds_read_b128 v[206:209], v162 offset:50176
	ds_read_b128 v[210:213], v162 offset:51200
	ds_read_b128 v[214:217], v162 offset:52224
	ds_read_b128 v[218:221], v162 offset:53248
	ds_read_b128 v[222:225], v162 offset:54272
	ds_read_b128 v[226:229], v162 offset:55296
	ds_read_b128 v[230:233], v162 offset:56320
	ds_read_b128 v[176:179], v142
	ds_read_b128 v[190:193], v142 offset:1024
	ds_read_b128 v[194:197], v142 offset:2048
	ds_read_b128 v[198:201], v142 offset:3072
	s_waitcnt vmcnt(8)
	s_waitcnt lgkmcnt(0)
	s_barrier
	s_setprio 1
	v_mfma_f32_16x16x32_bf16 v[116:119], v[176:179], v[202:205], v[116:119]
	v_mfma_f32_16x16x32_bf16 v[112:115], v[194:197], v[202:205], v[112:115]
	v_mfma_f32_16x16x32_bf16 v[100:103], v[176:179], v[210:213], v[100:103]
	v_mfma_f32_16x16x32_bf16 v[96:99], v[194:197], v[210:213], v[96:99]
	v_mfma_f32_16x16x32_bf16 v[84:87], v[176:179], v[218:221], v[84:87]
	v_mfma_f32_16x16x32_bf16 v[80:83], v[194:197], v[218:221], v[80:83]
	v_mfma_f32_16x16x32_bf16 v[68:71], v[176:179], v[226:229], v[68:71]
	v_mfma_f32_16x16x32_bf16 v[64:67], v[194:197], v[226:229], v[64:67]
	v_mfma_f32_16x16x32_bf16 v[116:119], v[190:193], v[206:209], v[116:119]
	v_mfma_f32_16x16x32_bf16 v[112:115], v[198:201], v[206:209], v[112:115]
	v_mfma_f32_16x16x32_bf16 v[100:103], v[190:193], v[214:217], v[100:103]
	v_mfma_f32_16x16x32_bf16 v[96:99], v[198:201], v[214:217], v[96:99]
	v_mfma_f32_16x16x32_bf16 v[84:87], v[190:193], v[222:225], v[84:87]
	v_mfma_f32_16x16x32_bf16 v[80:83], v[198:201], v[222:225], v[80:83]
	v_mfma_f32_16x16x32_bf16 v[68:71], v[190:193], v[230:233], v[68:71]
	v_mfma_f32_16x16x32_bf16 v[64:67], v[198:201], v[230:233], v[64:67]
	s_setprio 0
	s_barrier
	s_add_i32 s8, s8, 1
	s_cmp_lt_u32 s8, 7
	s_cbranch_scc1 .Lq_abi_1_k
	v_lshl_add_u64 v[234:235], s[74:75], 0, v[128:129]
	s_add_i32 m0, s5, 0xc000
	v_lshl_add_u64 v[236:237], s[74:75], 0, v[130:131]
	global_load_lds_dwordx4 v[234:235], off
	s_add_i32 m0, s5, 0xe000
	v_lshl_add_u64 v[238:239], s[2:3], 0, v[144:145]
	global_load_lds_dwordx4 v[236:237], off
	s_add_i32 m0, s5, 0x18000
	v_lshl_add_u64 v[240:241], s[2:3], 0, v[132:133]
	global_load_lds_dwordx4 v[238:239], off
	s_add_i32 m0, s5, 0x1a000
	s_add_u32 s74, s74, 0x80
	s_addc_u32 s75, s75, 0
	global_load_lds_dwordx4 v[240:241], off
	s_add_u32 s2, s2, 0x80
	s_addc_u32 s3, s3, 0
	v_add_u32_e32 v142, 0x14000, v160
	ds_read_b128 v[202:205], v162 offset:0
	ds_read_b128 v[206:209], v162 offset:1024
	ds_read_b128 v[210:213], v162 offset:2048
	ds_read_b128 v[214:217], v162 offset:3072
	ds_read_b128 v[218:221], v162 offset:4096
	ds_read_b128 v[222:225], v162 offset:5120
	ds_read_b128 v[226:229], v162 offset:6144
	ds_read_b128 v[230:233], v162 offset:7168
	ds_read_b128 v[176:179], v142
	ds_read_b128 v[190:193], v142 offset:1024
	ds_read_b128 v[194:197], v142 offset:2048
	ds_read_b128 v[198:201], v142 offset:3072
	s_waitcnt vmcnt(8)
	s_waitcnt lgkmcnt(0)
	s_barrier
	s_setprio 1
	v_mfma_f32_16x16x32_bf16 v[116:119], v[176:179], v[202:205], v[116:119]
	v_mfma_f32_16x16x32_bf16 v[112:115], v[194:197], v[202:205], v[112:115]
	v_mfma_f32_16x16x32_bf16 v[100:103], v[176:179], v[210:213], v[100:103]
	v_mfma_f32_16x16x32_bf16 v[96:99], v[194:197], v[210:213], v[96:99]
	v_mfma_f32_16x16x32_bf16 v[84:87], v[176:179], v[218:221], v[84:87]
	v_mfma_f32_16x16x32_bf16 v[80:83], v[194:197], v[218:221], v[80:83]
	v_mfma_f32_16x16x32_bf16 v[68:71], v[176:179], v[226:229], v[68:71]
	v_mfma_f32_16x16x32_bf16 v[64:67], v[194:197], v[226:229], v[64:67]
	v_mfma_f32_16x16x32_bf16 v[116:119], v[190:193], v[206:209], v[116:119]
	v_mfma_f32_16x16x32_bf16 v[112:115], v[198:201], v[206:209], v[112:115]
	v_mfma_f32_16x16x32_bf16 v[100:103], v[190:193], v[214:217], v[100:103]
	v_mfma_f32_16x16x32_bf16 v[96:99], v[198:201], v[214:217], v[96:99]
	v_mfma_f32_16x16x32_bf16 v[84:87], v[190:193], v[222:225], v[84:87]
	v_mfma_f32_16x16x32_bf16 v[80:83], v[198:201], v[222:225], v[80:83]
	v_mfma_f32_16x16x32_bf16 v[68:71], v[190:193], v[230:233], v[68:71]
	v_mfma_f32_16x16x32_bf16 v[64:67], v[198:201], v[230:233], v[64:67]
	s_setprio 0
	s_barrier
	v_add_u32_e32 v142, 0x1c000, v160
	ds_read_b128 v[202:205], v162 offset:32768
	ds_read_b128 v[206:209], v162 offset:33792
	ds_read_b128 v[210:213], v162 offset:34816
	ds_read_b128 v[214:217], v162 offset:35840
	ds_read_b128 v[218:221], v162 offset:36864
	ds_read_b128 v[222:225], v162 offset:37888
	ds_read_b128 v[226:229], v162 offset:38912
	ds_read_b128 v[230:233], v162 offset:39936
	ds_read_b128 v[176:179], v142
	ds_read_b128 v[190:193], v142 offset:1024
	ds_read_b128 v[194:197], v142 offset:2048
	ds_read_b128 v[198:201], v142 offset:3072
	s_waitcnt vmcnt(4)
	s_waitcnt lgkmcnt(0)
	s_barrier
	s_setprio 1
	v_mfma_f32_16x16x32_bf16 v[116:119], v[176:179], v[202:205], v[116:119]
	v_mfma_f32_16x16x32_bf16 v[112:115], v[194:197], v[202:205], v[112:115]
	v_mfma_f32_16x16x32_bf16 v[100:103], v[176:179], v[210:213], v[100:103]
	v_mfma_f32_16x16x32_bf16 v[96:99], v[194:197], v[210:213], v[96:99]
	v_mfma_f32_16x16x32_bf16 v[84:87], v[176:179], v[218:221], v[84:87]
	v_mfma_f32_16x16x32_bf16 v[80:83], v[194:197], v[218:221], v[80:83]
	v_mfma_f32_16x16x32_bf16 v[68:71], v[176:179], v[226:229], v[68:71]
	v_mfma_f32_16x16x32_bf16 v[64:67], v[194:197], v[226:229], v[64:67]
	v_mfma_f32_16x16x32_bf16 v[116:119], v[190:193], v[206:209], v[116:119]
	v_mfma_f32_16x16x32_bf16 v[112:115], v[198:201], v[206:209], v[112:115]
	v_mfma_f32_16x16x32_bf16 v[100:103], v[190:193], v[214:217], v[100:103]
	v_mfma_f32_16x16x32_bf16 v[96:99], v[198:201], v[214:217], v[96:99]
	v_mfma_f32_16x16x32_bf16 v[84:87], v[190:193], v[222:225], v[84:87]
	v_mfma_f32_16x16x32_bf16 v[80:83], v[198:201], v[222:225], v[80:83]
	v_mfma_f32_16x16x32_bf16 v[68:71], v[190:193], v[230:233], v[68:71]
	v_mfma_f32_16x16x32_bf16 v[64:67], v[198:201], v[230:233], v[64:67]
	s_setprio 0
	s_barrier
	v_add_u32_e32 v142, 0x10000, v160
	ds_read_b128 v[202:205], v162 offset:16384
	ds_read_b128 v[206:209], v162 offset:17408
	ds_read_b128 v[210:213], v162 offset:18432
	ds_read_b128 v[214:217], v162 offset:19456
	ds_read_b128 v[218:221], v162 offset:20480
	ds_read_b128 v[222:225], v162 offset:21504
	ds_read_b128 v[226:229], v162 offset:22528
	ds_read_b128 v[230:233], v162 offset:23552
	ds_read_b128 v[176:179], v142
	ds_read_b128 v[190:193], v142 offset:1024
	ds_read_b128 v[194:197], v142 offset:2048
	ds_read_b128 v[198:201], v142 offset:3072
	s_waitcnt vmcnt(0)
	s_waitcnt lgkmcnt(0)
	s_barrier
	s_setprio 1
	v_mfma_f32_16x16x32_bf16 v[116:119], v[176:179], v[202:205], v[116:119]
	v_mfma_f32_16x16x32_bf16 v[112:115], v[194:197], v[202:205], v[112:115]
	v_mfma_f32_16x16x32_bf16 v[100:103], v[176:179], v[210:213], v[100:103]
	v_mfma_f32_16x16x32_bf16 v[96:99], v[194:197], v[210:213], v[96:99]
	v_mfma_f32_16x16x32_bf16 v[84:87], v[176:179], v[218:221], v[84:87]
	v_mfma_f32_16x16x32_bf16 v[80:83], v[194:197], v[218:221], v[80:83]
	v_mfma_f32_16x16x32_bf16 v[68:71], v[176:179], v[226:229], v[68:71]
	v_mfma_f32_16x16x32_bf16 v[64:67], v[194:197], v[226:229], v[64:67]
	v_mfma_f32_16x16x32_bf16 v[116:119], v[190:193], v[206:209], v[116:119]
	v_mfma_f32_16x16x32_bf16 v[112:115], v[198:201], v[206:209], v[112:115]
	v_mfma_f32_16x16x32_bf16 v[100:103], v[190:193], v[214:217], v[100:103]
	v_mfma_f32_16x16x32_bf16 v[96:99], v[198:201], v[214:217], v[96:99]
	v_mfma_f32_16x16x32_bf16 v[84:87], v[190:193], v[222:225], v[84:87]
	v_mfma_f32_16x16x32_bf16 v[80:83], v[198:201], v[222:225], v[80:83]
	v_mfma_f32_16x16x32_bf16 v[68:71], v[190:193], v[230:233], v[68:71]
	v_mfma_f32_16x16x32_bf16 v[64:67], v[198:201], v[230:233], v[64:67]
	s_setprio 0
	s_barrier
	v_add_u32_e32 v142, 0x18000, v160
	ds_read_b128 v[202:205], v162 offset:49152
	ds_read_b128 v[206:209], v162 offset:50176
	ds_read_b128 v[210:213], v162 offset:51200
	ds_read_b128 v[214:217], v162 offset:52224
	ds_read_b128 v[218:221], v162 offset:53248
	ds_read_b128 v[222:225], v162 offset:54272
	ds_read_b128 v[226:229], v162 offset:55296
	ds_read_b128 v[230:233], v162 offset:56320
	ds_read_b128 v[176:179], v142
	ds_read_b128 v[190:193], v142 offset:1024
	ds_read_b128 v[194:197], v142 offset:2048
	ds_read_b128 v[198:201], v142 offset:3072
	s_waitcnt lgkmcnt(0)
	s_barrier
	s_setprio 1
	v_mfma_f32_16x16x32_bf16 v[116:119], v[176:179], v[202:205], v[116:119]
	v_mfma_f32_16x16x32_bf16 v[112:115], v[194:197], v[202:205], v[112:115]
	v_mfma_f32_16x16x32_bf16 v[100:103], v[176:179], v[210:213], v[100:103]
	v_mfma_f32_16x16x32_bf16 v[96:99], v[194:197], v[210:213], v[96:99]
	v_mfma_f32_16x16x32_bf16 v[84:87], v[176:179], v[218:221], v[84:87]
	v_mfma_f32_16x16x32_bf16 v[80:83], v[194:197], v[218:221], v[80:83]
	v_mfma_f32_16x16x32_bf16 v[68:71], v[176:179], v[226:229], v[68:71]
	v_mfma_f32_16x16x32_bf16 v[64:67], v[194:197], v[226:229], v[64:67]
	v_mfma_f32_16x16x32_bf16 v[116:119], v[190:193], v[206:209], v[116:119]
	v_mfma_f32_16x16x32_bf16 v[112:115], v[198:201], v[206:209], v[112:115]
	v_mfma_f32_16x16x32_bf16 v[100:103], v[190:193], v[214:217], v[100:103]
	v_mfma_f32_16x16x32_bf16 v[96:99], v[198:201], v[214:217], v[96:99]
	v_mfma_f32_16x16x32_bf16 v[84:87], v[190:193], v[222:225], v[84:87]
	v_mfma_f32_16x16x32_bf16 v[80:83], v[198:201], v[222:225], v[80:83]
	v_mfma_f32_16x16x32_bf16 v[68:71], v[190:193], v[230:233], v[68:71]
	v_mfma_f32_16x16x32_bf16 v[64:67], v[198:201], v[230:233], v[64:67]
	s_setprio 0
	s_barrier
	s_branch .Lq_abi_exit
.Lq_abi_2_loop:
	s_add_u32 s74, s74, 0x80080
	s_addc_u32 s75, s75, 0
	s_add_u32 s2, s2, 0x100
	s_addc_u32 s3, s3, 0
	s_waitcnt vmcnt(0)
	s_barrier
	s_barrier
	v_lshl_add_u64 v[234:235], s[74:75], 0, v[128:129]
	s_add_i32 m0, s5, 0xc000
	v_lshl_add_u64 v[236:237], s[74:75], 0, v[130:131]
	global_load_lds_dwordx4 v[234:235], off
	s_add_i32 m0, s5, 0xe000
	s_add_u32 s74, s74, 0x80
	s_addc_u32 s75, s75, 0
	global_load_lds_dwordx4 v[236:237], off
	v_lshl_add_u64 v[234:235], s[74:75], 0, v[128:129]
	s_add_i32 m0, s5, 0x0
	v_lshl_add_u64 v[236:237], s[74:75], 0, v[130:131]
	global_load_lds_dwordx4 v[234:235], off
	s_add_i32 m0, s5, 0x2000
	v_lshl_add_u64 v[238:239], s[2:3], 0, v[144:145]
	global_load_lds_dwordx4 v[236:237], off
	s_add_i32 m0, s5, 0x14000
	v_lshl_add_u64 v[240:241], s[2:3], 0, v[132:133]
	global_load_lds_dwordx4 v[238:239], off
	s_add_i32 m0, s5, 0x16000
	s_add_u32 s74, s74, 0x80
	s_addc_u32 s75, s75, 0
	global_load_lds_dwordx4 v[240:241], off
	s_add_u32 s2, s2, 0x80
	s_addc_u32 s3, s3, 0
	s_mov_b32 s8, 0
.Lq_abi_2_k:
	v_lshl_add_u64 v[234:235], s[74:75], 0, v[128:129]
	s_add_i32 m0, s5, 0x8000
	v_lshl_add_u64 v[236:237], s[74:75], 0, v[130:131]
	global_load_lds_dwordx4 v[234:235], off
	s_add_i32 m0, s5, 0xa000
	v_lshl_add_u64 v[238:239], s[2:3], 0, v[144:145]
	global_load_lds_dwordx4 v[236:237], off
	s_add_i32 m0, s5, 0x1c000
	v_lshl_add_u64 v[240:241], s[2:3], 0, v[132:133]
	global_load_lds_dwordx4 v[238:239], off
	s_add_i32 m0, s5, 0x1e000
	s_add_u32 s74, s74, 0x80
	s_addc_u32 s75, s75, 0
	global_load_lds_dwordx4 v[240:241], off
	s_add_u32 s2, s2, 0x80
	s_addc_u32 s3, s3, 0
	v_add_u32_e32 v142, 0x10000, v160
	ds_read_b128 v[202:205], v162 offset:16384
	ds_read_b128 v[206:209], v162 offset:17408
	ds_read_b128 v[210:213], v162 offset:18432
	ds_read_b128 v[214:217], v162 offset:19456
	ds_read_b128 v[218:221], v162 offset:20480
	ds_read_b128 v[222:225], v162 offset:21504
	ds_read_b128 v[226:229], v162 offset:22528
	ds_read_b128 v[230:233], v162 offset:23552
	ds_read_b128 v[138:141], v142
	ds_read_b128 v[164:167], v142 offset:1024
	ds_read_b128 v[168:171], v142 offset:2048
	ds_read_b128 v[172:175], v142 offset:3072
	s_waitcnt vmcnt(8)
	s_waitcnt lgkmcnt(0)
	s_barrier
	s_setprio 1
	v_mfma_f32_16x16x32_bf16 v[60:63], v[138:141], v[202:205], v[60:63]
	v_mfma_f32_16x16x32_bf16 v[56:59], v[168:171], v[202:205], v[56:59]
	v_mfma_f32_16x16x32_bf16 v[44:47], v[138:141], v[210:213], v[44:47]
	v_mfma_f32_16x16x32_bf16 v[40:43], v[168:171], v[210:213], v[40:43]
	v_mfma_f32_16x16x32_bf16 v[28:31], v[138:141], v[218:221], v[28:31]
	v_mfma_f32_16x16x32_bf16 v[24:27], v[168:171], v[218:221], v[24:27]
	v_mfma_f32_16x16x32_bf16 v[12:15], v[138:141], v[226:229], v[12:15]
	v_mfma_f32_16x16x32_bf16 v[8:11], v[168:171], v[226:229], v[8:11]
	v_mfma_f32_16x16x32_bf16 v[60:63], v[164:167], v[206:209], v[60:63]
	v_mfma_f32_16x16x32_bf16 v[56:59], v[172:175], v[206:209], v[56:59]
	v_mfma_f32_16x16x32_bf16 v[44:47], v[164:167], v[214:217], v[44:47]
	v_mfma_f32_16x16x32_bf16 v[40:43], v[172:175], v[214:217], v[40:43]
	v_mfma_f32_16x16x32_bf16 v[28:31], v[164:167], v[222:225], v[28:31]
	v_mfma_f32_16x16x32_bf16 v[24:27], v[172:175], v[222:225], v[24:27]
	v_mfma_f32_16x16x32_bf16 v[12:15], v[164:167], v[230:233], v[12:15]
	v_mfma_f32_16x16x32_bf16 v[8:11], v[172:175], v[230:233], v[8:11]
	s_setprio 0
	s_barrier
	v_lshl_add_u64 v[234:235], s[74:75], 0, v[128:129]
	s_add_i32 m0, s5, 0x4000
	v_lshl_add_u64 v[236:237], s[74:75], 0, v[130:131]
	global_load_lds_dwordx4 v[234:235], off
	s_add_i32 m0, s5, 0x6000
	v_lshl_add_u64 v[238:239], s[2:3], 0, v[144:145]
	global_load_lds_dwordx4 v[236:237], off
	s_add_i32 m0, s5, 0x10000
	v_lshl_add_u64 v[240:241], s[2:3], 0, v[132:133]
	global_load_lds_dwordx4 v[238:239], off
	s_add_i32 m0, s5, 0x12000
	s_add_u32 s74, s74, 0x80
	s_addc_u32 s75, s75, 0
	global_load_lds_dwordx4 v[240:241], off
	s_add_u32 s2, s2, 0x80
	s_addc_u32 s3, s3, 0
	v_add_u32_e32 v142, 0x18000, v160
	ds_read_b128 v[202:205], v162 offset:49152
	ds_read_b128 v[206:209], v162 offset:50176
	ds_read_b128 v[210:213], v162 offset:51200
	ds_read_b128 v[214:217], v162 offset:52224
	ds_read_b128 v[218:221], v162 offset:53248
	ds_read_b128 v[222:225], v162 offset:54272
	ds_read_b128 v[226:229], v162 offset:55296
	ds_read_b128 v[230:233], v162 offset:56320
	ds_read_b128 v[138:141], v142
	ds_read_b128 v[164:167], v142 offset:1024
	ds_read_b128 v[168:171], v142 offset:2048
	ds_read_b128 v[172:175], v142 offset:3072
	s_waitcnt vmcnt(8)
	s_waitcnt lgkmcnt(0)
	s_barrier
	s_setprio 1
	v_mfma_f32_16x16x32_bf16 v[60:63], v[138:141], v[202:205], v[60:63]
	v_mfma_f32_16x16x32_bf16 v[56:59], v[168:171], v[202:205], v[56:59]
	v_mfma_f32_16x16x32_bf16 v[44:47], v[138:141], v[210:213], v[44:47]
	v_mfma_f32_16x16x32_bf16 v[40:43], v[168:171], v[210:213], v[40:43]
	v_mfma_f32_16x16x32_bf16 v[28:31], v[138:141], v[218:221], v[28:31]
	v_mfma_f32_16x16x32_bf16 v[24:27], v[168:171], v[218:221], v[24:27]
	v_mfma_f32_16x16x32_bf16 v[12:15], v[138:141], v[226:229], v[12:15]
	v_mfma_f32_16x16x32_bf16 v[8:11], v[168:171], v[226:229], v[8:11]
	v_mfma_f32_16x16x32_bf16 v[60:63], v[164:167], v[206:209], v[60:63]
	v_mfma_f32_16x16x32_bf16 v[56:59], v[172:175], v[206:209], v[56:59]
	v_mfma_f32_16x16x32_bf16 v[44:47], v[164:167], v[214:217], v[44:47]
	v_mfma_f32_16x16x32_bf16 v[40:43], v[172:175], v[214:217], v[40:43]
	v_mfma_f32_16x16x32_bf16 v[28:31], v[164:167], v[222:225], v[28:31]
	v_mfma_f32_16x16x32_bf16 v[24:27], v[172:175], v[222:225], v[24:27]
	v_mfma_f32_16x16x32_bf16 v[12:15], v[164:167], v[230:233], v[12:15]
	v_mfma_f32_16x16x32_bf16 v[8:11], v[172:175], v[230:233], v[8:11]
	s_setprio 0
	s_barrier
	v_lshl_add_u64 v[234:235], s[74:75], 0, v[128:129]
	s_add_i32 m0, s5, 0xc000
	v_lshl_add_u64 v[236:237], s[74:75], 0, v[130:131]
	global_load_lds_dwordx4 v[234:235], off
	s_add_i32 m0, s5, 0xe000
	v_lshl_add_u64 v[238:239], s[2:3], 0, v[144:145]
	global_load_lds_dwordx4 v[236:237], off
	s_add_i32 m0, s5, 0x18000
	v_lshl_add_u64 v[240:241], s[2:3], 0, v[132:133]
	global_load_lds_dwordx4 v[238:239], off
	s_add_i32 m0, s5, 0x1a000
	s_add_u32 s74, s74, 0x80
	s_addc_u32 s75, s75, 0
	global_load_lds_dwordx4 v[240:241], off
	s_add_u32 s2, s2, 0x80
	s_addc_u32 s3, s3, 0
	v_add_u32_e32 v142, 0x14000, v160
	ds_read_b128 v[202:205], v162 offset:0
	ds_read_b128 v[206:209], v162 offset:1024
	ds_read_b128 v[210:213], v162 offset:2048
	ds_read_b128 v[214:217], v162 offset:3072
	ds_read_b128 v[218:221], v162 offset:4096
	ds_read_b128 v[222:225], v162 offset:5120
	ds_read_b128 v[226:229], v162 offset:6144
	ds_read_b128 v[230:233], v162 offset:7168
	ds_read_b128 v[138:141], v142
	ds_read_b128 v[164:167], v142 offset:1024
	ds_read_b128 v[168:171], v142 offset:2048
	ds_read_b128 v[172:175], v142 offset:3072
	s_waitcnt vmcnt(8)
	s_waitcnt lgkmcnt(0)
	s_barrier
	s_setprio 1
	v_mfma_f32_16x16x32_bf16 v[60:63], v[138:141], v[202:205], v[60:63]
	v_mfma_f32_16x16x32_bf16 v[56:59], v[168:171], v[202:205], v[56:59]
	v_mfma_f32_16x16x32_bf16 v[44:47], v[138:141], v[210:213], v[44:47]
	v_mfma_f32_16x16x32_bf16 v[40:43], v[168:171], v[210:213], v[40:43]
	v_mfma_f32_16x16x32_bf16 v[28:31], v[138:141], v[218:221], v[28:31]
	v_mfma_f32_16x16x32_bf16 v[24:27], v[168:171], v[218:221], v[24:27]
	v_mfma_f32_16x16x32_bf16 v[12:15], v[138:141], v[226:229], v[12:15]
	v_mfma_f32_16x16x32_bf16 v[8:11], v[168:171], v[226:229], v[8:11]
	v_mfma_f32_16x16x32_bf16 v[60:63], v[164:167], v[206:209], v[60:63]
	v_mfma_f32_16x16x32_bf16 v[56:59], v[172:175], v[206:209], v[56:59]
	v_mfma_f32_16x16x32_bf16 v[44:47], v[164:167], v[214:217], v[44:47]
	v_mfma_f32_16x16x32_bf16 v[40:43], v[172:175], v[214:217], v[40:43]
	v_mfma_f32_16x16x32_bf16 v[28:31], v[164:167], v[222:225], v[28:31]
	v_mfma_f32_16x16x32_bf16 v[24:27], v[172:175], v[222:225], v[24:27]
	v_mfma_f32_16x16x32_bf16 v[12:15], v[164:167], v[230:233], v[12:15]
	v_mfma_f32_16x16x32_bf16 v[8:11], v[172:175], v[230:233], v[8:11]
	s_setprio 0
	s_barrier
	v_lshl_add_u64 v[234:235], s[74:75], 0, v[128:129]
	s_add_i32 m0, s5, 0x0
	v_lshl_add_u64 v[236:237], s[74:75], 0, v[130:131]
	global_load_lds_dwordx4 v[234:235], off
	s_add_i32 m0, s5, 0x2000
	v_lshl_add_u64 v[238:239], s[2:3], 0, v[144:145]
	global_load_lds_dwordx4 v[236:237], off
	s_add_i32 m0, s5, 0x14000
	v_lshl_add_u64 v[240:241], s[2:3], 0, v[132:133]
	global_load_lds_dwordx4 v[238:239], off
	s_add_i32 m0, s5, 0x16000
	s_add_u32 s74, s74, 0x80
	s_addc_u32 s75, s75, 0
	global_load_lds_dwordx4 v[240:241], off
	s_add_u32 s2, s2, 0x80
	s_addc_u32 s3, s3, 0
	v_add_u32_e32 v142, 0x1c000, v160
	ds_read_b128 v[202:205], v162 offset:32768
	ds_read_b128 v[206:209], v162 offset:33792
	ds_read_b128 v[210:213], v162 offset:34816
	ds_read_b128 v[214:217], v162 offset:35840
	ds_read_b128 v[218:221], v162 offset:36864
	ds_read_b128 v[222:225], v162 offset:37888
	ds_read_b128 v[226:229], v162 offset:38912
	ds_read_b128 v[230:233], v162 offset:39936
	ds_read_b128 v[138:141], v142
	ds_read_b128 v[164:167], v142 offset:1024
	ds_read_b128 v[168:171], v142 offset:2048
	ds_read_b128 v[172:175], v142 offset:3072
	s_waitcnt vmcnt(8)
	s_waitcnt lgkmcnt(0)
	s_barrier
	s_setprio 1
	v_mfma_f32_16x16x32_bf16 v[60:63], v[138:141], v[202:205], v[60:63]
	v_mfma_f32_16x16x32_bf16 v[56:59], v[168:171], v[202:205], v[56:59]
	v_mfma_f32_16x16x32_bf16 v[44:47], v[138:141], v[210:213], v[44:47]
	v_mfma_f32_16x16x32_bf16 v[40:43], v[168:171], v[210:213], v[40:43]
	v_mfma_f32_16x16x32_bf16 v[28:31], v[138:141], v[218:221], v[28:31]
	v_mfma_f32_16x16x32_bf16 v[24:27], v[168:171], v[218:221], v[24:27]
	v_mfma_f32_16x16x32_bf16 v[12:15], v[138:141], v[226:229], v[12:15]
	v_mfma_f32_16x16x32_bf16 v[8:11], v[168:171], v[226:229], v[8:11]
	v_mfma_f32_16x16x32_bf16 v[60:63], v[164:167], v[206:209], v[60:63]
	v_mfma_f32_16x16x32_bf16 v[56:59], v[172:175], v[206:209], v[56:59]
	v_mfma_f32_16x16x32_bf16 v[44:47], v[164:167], v[214:217], v[44:47]
	v_mfma_f32_16x16x32_bf16 v[40:43], v[172:175], v[214:217], v[40:43]
	v_mfma_f32_16x16x32_bf16 v[28:31], v[164:167], v[222:225], v[28:31]
	v_mfma_f32_16x16x32_bf16 v[24:27], v[172:175], v[222:225], v[24:27]
	v_mfma_f32_16x16x32_bf16 v[12:15], v[164:167], v[230:233], v[12:15]
	v_mfma_f32_16x16x32_bf16 v[8:11], v[172:175], v[230:233], v[8:11]
	s_setprio 0
	s_barrier
	s_add_i32 s8, s8, 1
	s_cmp_lt_u32 s8, 7
	s_cbranch_scc1 .Lq_abi_2_k
	v_lshl_add_u64 v[234:235], s[74:75], 0, v[128:129]
	s_add_i32 m0, s5, 0x8000
	v_lshl_add_u64 v[236:237], s[74:75], 0, v[130:131]
	global_load_lds_dwordx4 v[234:235], off
	s_add_i32 m0, s5, 0xa000
	v_lshl_add_u64 v[238:239], s[2:3], 0, v[144:145]
	global_load_lds_dwordx4 v[236:237], off
	s_add_i32 m0, s5, 0x1c000
	v_lshl_add_u64 v[240:241], s[2:3], 0, v[132:133]
	global_load_lds_dwordx4 v[238:239], off
	s_add_i32 m0, s5, 0x1e000
	s_add_u32 s74, s74, 0x80
	s_addc_u32 s75, s75, 0
	global_load_lds_dwordx4 v[240:241], off
	s_add_u32 s2, s2, 0x80
	s_addc_u32 s3, s3, 0
	v_add_u32_e32 v142, 0x10000, v160
	ds_read_b128 v[202:205], v162 offset:16384
	ds_read_b128 v[206:209], v162 offset:17408
	ds_read_b128 v[210:213], v162 offset:18432
	ds_read_b128 v[214:217], v162 offset:19456
	ds_read_b128 v[218:221], v162 offset:20480
	ds_read_b128 v[222:225], v162 offset:21504
	ds_read_b128 v[226:229], v162 offset:22528
	ds_read_b128 v[230:233], v162 offset:23552
	ds_read_b128 v[138:141], v142
	ds_read_b128 v[164:167], v142 offset:1024
	ds_read_b128 v[168:171], v142 offset:2048
	ds_read_b128 v[172:175], v142 offset:3072
	s_waitcnt vmcnt(8)
	s_waitcnt lgkmcnt(0)
	s_barrier
	s_setprio 1
	v_mfma_f32_16x16x32_bf16 v[60:63], v[138:141], v[202:205], v[60:63]
	v_mfma_f32_16x16x32_bf16 v[56:59], v[168:171], v[202:205], v[56:59]
	v_mfma_f32_16x16x32_bf16 v[44:47], v[138:141], v[210:213], v[44:47]
	v_mfma_f32_16x16x32_bf16 v[40:43], v[168:171], v[210:213], v[40:43]
	v_mfma_f32_16x16x32_bf16 v[28:31], v[138:141], v[218:221], v[28:31]
	v_mfma_f32_16x16x32_bf16 v[24:27], v[168:171], v[218:221], v[24:27]
	v_mfma_f32_16x16x32_bf16 v[12:15], v[138:141], v[226:229], v[12:15]
	v_mfma_f32_16x16x32_bf16 v[8:11], v[168:171], v[226:229], v[8:11]
	v_mfma_f32_16x16x32_bf16 v[60:63], v[164:167], v[206:209], v[60:63]
	v_mfma_f32_16x16x32_bf16 v[56:59], v[172:175], v[206:209], v[56:59]
	v_mfma_f32_16x16x32_bf16 v[44:47], v[164:167], v[214:217], v[44:47]
	v_mfma_f32_16x16x32_bf16 v[40:43], v[172:175], v[214:217], v[40:43]
	v_mfma_f32_16x16x32_bf16 v[28:31], v[164:167], v[222:225], v[28:31]
	v_mfma_f32_16x16x32_bf16 v[24:27], v[172:175], v[222:225], v[24:27]
	v_mfma_f32_16x16x32_bf16 v[12:15], v[164:167], v[230:233], v[12:15]
	v_mfma_f32_16x16x32_bf16 v[8:11], v[172:175], v[230:233], v[8:11]
	s_setprio 0
	s_barrier
	v_add_u32_e32 v142, 0x18000, v160
	ds_read_b128 v[202:205], v162 offset:49152
	ds_read_b128 v[206:209], v162 offset:50176
	ds_read_b128 v[210:213], v162 offset:51200
	ds_read_b128 v[214:217], v162 offset:52224
	ds_read_b128 v[218:221], v162 offset:53248
	ds_read_b128 v[222:225], v162 offset:54272
	ds_read_b128 v[226:229], v162 offset:55296
	ds_read_b128 v[230:233], v162 offset:56320
	ds_read_b128 v[138:141], v142
	ds_read_b128 v[164:167], v142 offset:1024
	ds_read_b128 v[168:171], v142 offset:2048
	ds_read_b128 v[172:175], v142 offset:3072
	s_waitcnt vmcnt(4)
	s_waitcnt lgkmcnt(0)
	s_barrier
	s_setprio 1
	v_mfma_f32_16x16x32_bf16 v[60:63], v[138:141], v[202:205], v[60:63]
	v_mfma_f32_16x16x32_bf16 v[56:59], v[168:171], v[202:205], v[56:59]
	v_mfma_f32_16x16x32_bf16 v[44:47], v[138:141], v[210:213], v[44:47]
	v_mfma_f32_16x16x32_bf16 v[40:43], v[168:171], v[210:213], v[40:43]
	v_mfma_f32_16x16x32_bf16 v[28:31], v[138:141], v[218:221], v[28:31]
	v_mfma_f32_16x16x32_bf16 v[24:27], v[168:171], v[218:221], v[24:27]
	v_mfma_f32_16x16x32_bf16 v[12:15], v[138:141], v[226:229], v[12:15]
	v_mfma_f32_16x16x32_bf16 v[8:11], v[168:171], v[226:229], v[8:11]
	v_mfma_f32_16x16x32_bf16 v[60:63], v[164:167], v[206:209], v[60:63]
	v_mfma_f32_16x16x32_bf16 v[56:59], v[172:175], v[206:209], v[56:59]
	v_mfma_f32_16x16x32_bf16 v[44:47], v[164:167], v[214:217], v[44:47]
	v_mfma_f32_16x16x32_bf16 v[40:43], v[172:175], v[214:217], v[40:43]
	v_mfma_f32_16x16x32_bf16 v[28:31], v[164:167], v[222:225], v[28:31]
	v_mfma_f32_16x16x32_bf16 v[24:27], v[172:175], v[222:225], v[24:27]
	v_mfma_f32_16x16x32_bf16 v[12:15], v[164:167], v[230:233], v[12:15]
	v_mfma_f32_16x16x32_bf16 v[8:11], v[172:175], v[230:233], v[8:11]
	s_setprio 0
	s_barrier
	v_add_u32_e32 v142, 0x14000, v160
	ds_read_b128 v[202:205], v162 offset:0
	ds_read_b128 v[206:209], v162 offset:1024
	ds_read_b128 v[210:213], v162 offset:2048
	ds_read_b128 v[214:217], v162 offset:3072
	ds_read_b128 v[218:221], v162 offset:4096
	ds_read_b128 v[222:225], v162 offset:5120
	ds_read_b128 v[226:229], v162 offset:6144
	ds_read_b128 v[230:233], v162 offset:7168
	ds_read_b128 v[138:141], v142
	ds_read_b128 v[164:167], v142 offset:1024
	ds_read_b128 v[168:171], v142 offset:2048
	ds_read_b128 v[172:175], v142 offset:3072
	s_waitcnt vmcnt(0)
	s_waitcnt lgkmcnt(0)
	s_barrier
	s_setprio 1
	v_mfma_f32_16x16x32_bf16 v[60:63], v[138:141], v[202:205], v[60:63]
	v_mfma_f32_16x16x32_bf16 v[56:59], v[168:171], v[202:205], v[56:59]
	v_mfma_f32_16x16x32_bf16 v[44:47], v[138:141], v[210:213], v[44:47]
	v_mfma_f32_16x16x32_bf16 v[40:43], v[168:171], v[210:213], v[40:43]
	v_mfma_f32_16x16x32_bf16 v[28:31], v[138:141], v[218:221], v[28:31]
	v_mfma_f32_16x16x32_bf16 v[24:27], v[168:171], v[218:221], v[24:27]
	v_mfma_f32_16x16x32_bf16 v[12:15], v[138:141], v[226:229], v[12:15]
	v_mfma_f32_16x16x32_bf16 v[8:11], v[168:171], v[226:229], v[8:11]
	v_mfma_f32_16x16x32_bf16 v[60:63], v[164:167], v[206:209], v[60:63]
	v_mfma_f32_16x16x32_bf16 v[56:59], v[172:175], v[206:209], v[56:59]
	v_mfma_f32_16x16x32_bf16 v[44:47], v[164:167], v[214:217], v[44:47]
	v_mfma_f32_16x16x32_bf16 v[40:43], v[172:175], v[214:217], v[40:43]
	v_mfma_f32_16x16x32_bf16 v[28:31], v[164:167], v[222:225], v[28:31]
	v_mfma_f32_16x16x32_bf16 v[24:27], v[172:175], v[222:225], v[24:27]
	v_mfma_f32_16x16x32_bf16 v[12:15], v[164:167], v[230:233], v[12:15]
	v_mfma_f32_16x16x32_bf16 v[8:11], v[172:175], v[230:233], v[8:11]
	s_setprio 0
	s_barrier
	v_add_u32_e32 v142, 0x1c000, v160
	ds_read_b128 v[202:205], v162 offset:32768
	ds_read_b128 v[206:209], v162 offset:33792
	ds_read_b128 v[210:213], v162 offset:34816
	ds_read_b128 v[214:217], v162 offset:35840
	ds_read_b128 v[218:221], v162 offset:36864
	ds_read_b128 v[222:225], v162 offset:37888
	ds_read_b128 v[226:229], v162 offset:38912
	ds_read_b128 v[230:233], v162 offset:39936
	ds_read_b128 v[138:141], v142
	ds_read_b128 v[164:167], v142 offset:1024
	ds_read_b128 v[168:171], v142 offset:2048
	ds_read_b128 v[172:175], v142 offset:3072
	s_waitcnt lgkmcnt(0)
	s_barrier
	s_setprio 1
	v_mfma_f32_16x16x32_bf16 v[60:63], v[138:141], v[202:205], v[60:63]
	v_mfma_f32_16x16x32_bf16 v[56:59], v[168:171], v[202:205], v[56:59]
	v_mfma_f32_16x16x32_bf16 v[44:47], v[138:141], v[210:213], v[44:47]
	v_mfma_f32_16x16x32_bf16 v[40:43], v[168:171], v[210:213], v[40:43]
	v_mfma_f32_16x16x32_bf16 v[28:31], v[138:141], v[218:221], v[28:31]
	v_mfma_f32_16x16x32_bf16 v[24:27], v[168:171], v[218:221], v[24:27]
	v_mfma_f32_16x16x32_bf16 v[12:15], v[138:141], v[226:229], v[12:15]
	v_mfma_f32_16x16x32_bf16 v[8:11], v[168:171], v[226:229], v[8:11]
	v_mfma_f32_16x16x32_bf16 v[60:63], v[164:167], v[206:209], v[60:63]
	v_mfma_f32_16x16x32_bf16 v[56:59], v[172:175], v[206:209], v[56:59]
	v_mfma_f32_16x16x32_bf16 v[44:47], v[164:167], v[214:217], v[44:47]
	v_mfma_f32_16x16x32_bf16 v[40:43], v[172:175], v[214:217], v[40:43]
	v_mfma_f32_16x16x32_bf16 v[28:31], v[164:167], v[222:225], v[28:31]
	v_mfma_f32_16x16x32_bf16 v[24:27], v[172:175], v[222:225], v[24:27]
	v_mfma_f32_16x16x32_bf16 v[12:15], v[164:167], v[230:233], v[12:15]
	v_mfma_f32_16x16x32_bf16 v[8:11], v[172:175], v[230:233], v[8:11]
	s_setprio 0
	s_barrier
	s_branch .Lq_abi_exit
.Lq_abi_3_loop:
	s_add_u32 s74, s74, 0x80080
	s_addc_u32 s75, s75, 0
	s_add_u32 s2, s2, 0x80100
	s_addc_u32 s3, s3, 0
	s_waitcnt vmcnt(0)
	s_barrier
	s_barrier
	v_lshl_add_u64 v[234:235], s[74:75], 0, v[128:129]
	s_add_i32 m0, s5, 0xc000
	v_lshl_add_u64 v[236:237], s[74:75], 0, v[130:131]
	global_load_lds_dwordx4 v[234:235], off
	s_add_i32 m0, s5, 0xe000
	s_add_u32 s74, s74, 0x80
	s_addc_u32 s75, s75, 0
	global_load_lds_dwordx4 v[236:237], off
	v_lshl_add_u64 v[234:235], s[74:75], 0, v[128:129]
	s_add_i32 m0, s5, 0x0
	v_lshl_add_u64 v[236:237], s[74:75], 0, v[130:131]
	global_load_lds_dwordx4 v[234:235], off
	s_add_i32 m0, s5, 0x2000
	v_lshl_add_u64 v[238:239], s[2:3], 0, v[144:145]
	global_load_lds_dwordx4 v[236:237], off
	s_add_i32 m0, s5, 0x10000
	v_lshl_add_u64 v[240:241], s[2:3], 0, v[132:133]
	global_load_lds_dwordx4 v[238:239], off
	s_add_i32 m0, s5, 0x12000
	s_add_u32 s74, s74, 0x80
	s_addc_u32 s75, s75, 0
	global_load_lds_dwordx4 v[240:241], off
	s_add_u32 s2, s2, 0x80
	s_addc_u32 s3, s3, 0
	s_mov_b32 s8, 0
.Lq_abi_3_k:
	v_lshl_add_u64 v[234:235], s[74:75], 0, v[128:129]
	s_add_i32 m0, s5, 0x8000
	v_lshl_add_u64 v[236:237], s[74:75], 0, v[130:131]
	global_load_lds_dwordx4 v[234:235], off
	s_add_i32 m0, s5, 0xa000
	v_lshl_add_u64 v[238:239], s[2:3], 0, v[144:145]
	global_load_lds_dwordx4 v[236:237], off
	s_add_i32 m0, s5, 0x18000
	v_lshl_add_u64 v[240:241], s[2:3], 0, v[132:133]
	global_load_lds_dwordx4 v[238:239], off
	s_add_i32 m0, s5, 0x1a000
	s_add_u32 s74, s74, 0x80
	s_addc_u32 s75, s75, 0
	global_load_lds_dwordx4 v[240:241], off
	s_add_u32 s2, s2, 0x80
	s_addc_u32 s3, s3, 0
	v_add_u32_e32 v142, 0x14000, v160
	ds_read_b128 v[202:205], v162 offset:16384
	ds_read_b128 v[206:209], v162 offset:17408
	ds_read_b128 v[210:213], v162 offset:18432
	ds_read_b128 v[214:217], v162 offset:19456
	ds_read_b128 v[218:221], v162 offset:20480
	ds_read_b128 v[222:225], v162 offset:21504
	ds_read_b128 v[226:229], v162 offset:22528
	ds_read_b128 v[230:233], v162 offset:23552
	ds_read_b128 v[176:179], v142
	ds_read_b128 v[190:193], v142 offset:1024
	ds_read_b128 v[194:197], v142 offset:2048
	ds_read_b128 v[198:201], v142 offset:3072
	s_waitcnt vmcnt(8)
	s_waitcnt lgkmcnt(0)
	s_barrier
	s_setprio 1
	v_mfma_f32_16x16x32_bf16 v[52:55], v[176:179], v[202:205], v[52:55]
	v_mfma_f32_16x16x32_bf16 v[48:51], v[194:197], v[202:205], v[48:51]
	v_mfma_f32_16x16x32_bf16 v[36:39], v[176:179], v[210:213], v[36:39]
	v_mfma_f32_16x16x32_bf16 v[32:35], v[194:197], v[210:213], v[32:35]
	v_mfma_f32_16x16x32_bf16 v[20:23], v[176:179], v[218:221], v[20:23]
	v_mfma_f32_16x16x32_bf16 v[16:19], v[194:197], v[218:221], v[16:19]
	v_mfma_f32_16x16x32_bf16 v[4:7], v[176:179], v[226:229], v[4:7]
	v_mfma_f32_16x16x32_bf16 v[0:3], v[194:197], v[226:229], v[0:3]
	v_mfma_f32_16x16x32_bf16 v[52:55], v[190:193], v[206:209], v[52:55]
	v_mfma_f32_16x16x32_bf16 v[48:51], v[198:201], v[206:209], v[48:51]
	v_mfma_f32_16x16x32_bf16 v[36:39], v[190:193], v[214:217], v[36:39]
	v_mfma_f32_16x16x32_bf16 v[32:35], v[198:201], v[214:217], v[32:35]
	v_mfma_f32_16x16x32_bf16 v[20:23], v[190:193], v[222:225], v[20:23]
	v_mfma_f32_16x16x32_bf16 v[16:19], v[198:201], v[222:225], v[16:19]
	v_mfma_f32_16x16x32_bf16 v[4:7], v[190:193], v[230:233], v[4:7]
	v_mfma_f32_16x16x32_bf16 v[0:3], v[198:201], v[230:233], v[0:3]
	s_setprio 0
	s_barrier
	v_lshl_add_u64 v[234:235], s[74:75], 0, v[128:129]
	s_add_i32 m0, s5, 0x4000
	v_lshl_add_u64 v[236:237], s[74:75], 0, v[130:131]
	global_load_lds_dwordx4 v[234:235], off
	s_add_i32 m0, s5, 0x6000
	v_lshl_add_u64 v[238:239], s[2:3], 0, v[144:145]
	global_load_lds_dwordx4 v[236:237], off
	s_add_i32 m0, s5, 0x14000
	v_lshl_add_u64 v[240:241], s[2:3], 0, v[132:133]
	global_load_lds_dwordx4 v[238:239], off
	s_add_i32 m0, s5, 0x16000
	s_add_u32 s74, s74, 0x80
	s_addc_u32 s75, s75, 0
	global_load_lds_dwordx4 v[240:241], off
	s_add_u32 s2, s2, 0x80
	s_addc_u32 s3, s3, 0
	v_add_u32_e32 v142, 0x1c000, v160
	ds_read_b128 v[202:205], v162 offset:49152
	ds_read_b128 v[206:209], v162 offset:50176
	ds_read_b128 v[210:213], v162 offset:51200
	ds_read_b128 v[214:217], v162 offset:52224
	ds_read_b128 v[218:221], v162 offset:53248
	ds_read_b128 v[222:225], v162 offset:54272
	ds_read_b128 v[226:229], v162 offset:55296
	ds_read_b128 v[230:233], v162 offset:56320
	ds_read_b128 v[176:179], v142
	ds_read_b128 v[190:193], v142 offset:1024
	ds_read_b128 v[194:197], v142 offset:2048
	ds_read_b128 v[198:201], v142 offset:3072
	s_waitcnt vmcnt(8)
	s_waitcnt lgkmcnt(0)
	s_barrier
	s_setprio 1
	v_mfma_f32_16x16x32_bf16 v[52:55], v[176:179], v[202:205], v[52:55]
	v_mfma_f32_16x16x32_bf16 v[48:51], v[194:197], v[202:205], v[48:51]
	v_mfma_f32_16x16x32_bf16 v[36:39], v[176:179], v[210:213], v[36:39]
	v_mfma_f32_16x16x32_bf16 v[32:35], v[194:197], v[210:213], v[32:35]
	v_mfma_f32_16x16x32_bf16 v[20:23], v[176:179], v[218:221], v[20:23]
	v_mfma_f32_16x16x32_bf16 v[16:19], v[194:197], v[218:221], v[16:19]
	v_mfma_f32_16x16x32_bf16 v[4:7], v[176:179], v[226:229], v[4:7]
	v_mfma_f32_16x16x32_bf16 v[0:3], v[194:197], v[226:229], v[0:3]
	v_mfma_f32_16x16x32_bf16 v[52:55], v[190:193], v[206:209], v[52:55]
	v_mfma_f32_16x16x32_bf16 v[48:51], v[198:201], v[206:209], v[48:51]
	v_mfma_f32_16x16x32_bf16 v[36:39], v[190:193], v[214:217], v[36:39]
	v_mfma_f32_16x16x32_bf16 v[32:35], v[198:201], v[214:217], v[32:35]
	v_mfma_f32_16x16x32_bf16 v[20:23], v[190:193], v[222:225], v[20:23]
	v_mfma_f32_16x16x32_bf16 v[16:19], v[198:201], v[222:225], v[16:19]
	v_mfma_f32_16x16x32_bf16 v[4:7], v[190:193], v[230:233], v[4:7]
	v_mfma_f32_16x16x32_bf16 v[0:3], v[198:201], v[230:233], v[0:3]
	s_setprio 0
	s_barrier
	v_lshl_add_u64 v[234:235], s[74:75], 0, v[128:129]
	s_add_i32 m0, s5, 0xc000
	v_lshl_add_u64 v[236:237], s[74:75], 0, v[130:131]
	global_load_lds_dwordx4 v[234:235], off
	s_add_i32 m0, s5, 0xe000
	v_lshl_add_u64 v[238:239], s[2:3], 0, v[144:145]
	global_load_lds_dwordx4 v[236:237], off
	s_add_i32 m0, s5, 0x1c000
	v_lshl_add_u64 v[240:241], s[2:3], 0, v[132:133]
	global_load_lds_dwordx4 v[238:239], off
	s_add_i32 m0, s5, 0x1e000
	s_add_u32 s74, s74, 0x80
	s_addc_u32 s75, s75, 0
	global_load_lds_dwordx4 v[240:241], off
	s_add_u32 s2, s2, 0x80
	s_addc_u32 s3, s3, 0
	v_add_u32_e32 v142, 0x10000, v160
	ds_read_b128 v[202:205], v162 offset:0
	ds_read_b128 v[206:209], v162 offset:1024
	ds_read_b128 v[210:213], v162 offset:2048
	ds_read_b128 v[214:217], v162 offset:3072
	ds_read_b128 v[218:221], v162 offset:4096
	ds_read_b128 v[222:225], v162 offset:5120
	ds_read_b128 v[226:229], v162 offset:6144
	ds_read_b128 v[230:233], v162 offset:7168
	ds_read_b128 v[176:179], v142
	ds_read_b128 v[190:193], v142 offset:1024
	ds_read_b128 v[194:197], v142 offset:2048
	ds_read_b128 v[198:201], v142 offset:3072
	s_waitcnt vmcnt(8)
	s_waitcnt lgkmcnt(0)
	s_barrier
	s_setprio 1
	v_mfma_f32_16x16x32_bf16 v[52:55], v[176:179], v[202:205], v[52:55]
	v_mfma_f32_16x16x32_bf16 v[48:51], v[194:197], v[202:205], v[48:51]
	v_mfma_f32_16x16x32_bf16 v[36:39], v[176:179], v[210:213], v[36:39]
	v_mfma_f32_16x16x32_bf16 v[32:35], v[194:197], v[210:213], v[32:35]
	v_mfma_f32_16x16x32_bf16 v[20:23], v[176:179], v[218:221], v[20:23]
	v_mfma_f32_16x16x32_bf16 v[16:19], v[194:197], v[218:221], v[16:19]
	v_mfma_f32_16x16x32_bf16 v[4:7], v[176:179], v[226:229], v[4:7]
	v_mfma_f32_16x16x32_bf16 v[0:3], v[194:197], v[226:229], v[0:3]
	v_mfma_f32_16x16x32_bf16 v[52:55], v[190:193], v[206:209], v[52:55]
	v_mfma_f32_16x16x32_bf16 v[48:51], v[198:201], v[206:209], v[48:51]
	v_mfma_f32_16x16x32_bf16 v[36:39], v[190:193], v[214:217], v[36:39]
	v_mfma_f32_16x16x32_bf16 v[32:35], v[198:201], v[214:217], v[32:35]
	v_mfma_f32_16x16x32_bf16 v[20:23], v[190:193], v[222:225], v[20:23]
	v_mfma_f32_16x16x32_bf16 v[16:19], v[198:201], v[222:225], v[16:19]
	v_mfma_f32_16x16x32_bf16 v[4:7], v[190:193], v[230:233], v[4:7]
	v_mfma_f32_16x16x32_bf16 v[0:3], v[198:201], v[230:233], v[0:3]
	s_setprio 0
	s_barrier
	v_lshl_add_u64 v[234:235], s[74:75], 0, v[128:129]
	s_add_i32 m0, s5, 0x0
	v_lshl_add_u64 v[236:237], s[74:75], 0, v[130:131]
	global_load_lds_dwordx4 v[234:235], off
	s_add_i32 m0, s5, 0x2000
	v_lshl_add_u64 v[238:239], s[2:3], 0, v[144:145]
	global_load_lds_dwordx4 v[236:237], off
	s_add_i32 m0, s5, 0x10000
	v_lshl_add_u64 v[240:241], s[2:3], 0, v[132:133]
	global_load_lds_dwordx4 v[238:239], off
	s_add_i32 m0, s5, 0x12000
	s_add_u32 s74, s74, 0x80
	s_addc_u32 s75, s75, 0
	global_load_lds_dwordx4 v[240:241], off
	s_add_u32 s2, s2, 0x80
	s_addc_u32 s3, s3, 0
	v_add_u32_e32 v142, 0x18000, v160
	ds_read_b128 v[202:205], v162 offset:32768
	ds_read_b128 v[206:209], v162 offset:33792
	ds_read_b128 v[210:213], v162 offset:34816
	ds_read_b128 v[214:217], v162 offset:35840
	ds_read_b128 v[218:221], v162 offset:36864
	ds_read_b128 v[222:225], v162 offset:37888
	ds_read_b128 v[226:229], v162 offset:38912
	ds_read_b128 v[230:233], v162 offset:39936
	ds_read_b128 v[176:179], v142
	ds_read_b128 v[190:193], v142 offset:1024
	ds_read_b128 v[194:197], v142 offset:2048
	ds_read_b128 v[198:201], v142 offset:3072
	s_waitcnt vmcnt(8)
	s_waitcnt lgkmcnt(0)
	s_barrier
	s_setprio 1
	v_mfma_f32_16x16x32_bf16 v[52:55], v[176:179], v[202:205], v[52:55]
	v_mfma_f32_16x16x32_bf16 v[48:51], v[194:197], v[202:205], v[48:51]
	v_mfma_f32_16x16x32_bf16 v[36:39], v[176:179], v[210:213], v[36:39]
	v_mfma_f32_16x16x32_bf16 v[32:35], v[194:197], v[210:213], v[32:35]
	v_mfma_f32_16x16x32_bf16 v[20:23], v[176:179], v[218:221], v[20:23]
	v_mfma_f32_16x16x32_bf16 v[16:19], v[194:197], v[218:221], v[16:19]
	v_mfma_f32_16x16x32_bf16 v[4:7], v[176:179], v[226:229], v[4:7]
	v_mfma_f32_16x16x32_bf16 v[0:3], v[194:197], v[226:229], v[0:3]
	v_mfma_f32_16x16x32_bf16 v[52:55], v[190:193], v[206:209], v[52:55]
	v_mfma_f32_16x16x32_bf16 v[48:51], v[198:201], v[206:209], v[48:51]
	v_mfma_f32_16x16x32_bf16 v[36:39], v[190:193], v[214:217], v[36:39]
	v_mfma_f32_16x16x32_bf16 v[32:35], v[198:201], v[214:217], v[32:35]
	v_mfma_f32_16x16x32_bf16 v[20:23], v[190:193], v[222:225], v[20:23]
	v_mfma_f32_16x16x32_bf16 v[16:19], v[198:201], v[222:225], v[16:19]
	v_mfma_f32_16x16x32_bf16 v[4:7], v[190:193], v[230:233], v[4:7]
	v_mfma_f32_16x16x32_bf16 v[0:3], v[198:201], v[230:233], v[0:3]
	s_setprio 0
	s_barrier
	s_add_i32 s8, s8, 1
	s_cmp_lt_u32 s8, 7
	s_cbranch_scc1 .Lq_abi_3_k
	v_lshl_add_u64 v[234:235], s[74:75], 0, v[128:129]
	s_add_i32 m0, s5, 0x8000
	v_lshl_add_u64 v[236:237], s[74:75], 0, v[130:131]
	global_load_lds_dwordx4 v[234:235], off
	s_add_i32 m0, s5, 0xa000
	v_lshl_add_u64 v[238:239], s[2:3], 0, v[144:145]
	global_load_lds_dwordx4 v[236:237], off
	s_add_i32 m0, s5, 0x18000
	v_lshl_add_u64 v[240:241], s[2:3], 0, v[132:133]
	global_load_lds_dwordx4 v[238:239], off
	s_add_i32 m0, s5, 0x1a000
	s_add_u32 s74, s74, 0x80
	s_addc_u32 s75, s75, 0
	global_load_lds_dwordx4 v[240:241], off
	s_add_u32 s2, s2, 0x80
	s_addc_u32 s3, s3, 0
	v_add_u32_e32 v142, 0x14000, v160
	ds_read_b128 v[202:205], v162 offset:16384
	ds_read_b128 v[206:209], v162 offset:17408
	ds_read_b128 v[210:213], v162 offset:18432
	ds_read_b128 v[214:217], v162 offset:19456
	ds_read_b128 v[218:221], v162 offset:20480
	ds_read_b128 v[222:225], v162 offset:21504
	ds_read_b128 v[226:229], v162 offset:22528
	ds_read_b128 v[230:233], v162 offset:23552
	ds_read_b128 v[176:179], v142
	ds_read_b128 v[190:193], v142 offset:1024
	ds_read_b128 v[194:197], v142 offset:2048
	ds_read_b128 v[198:201], v142 offset:3072
	s_waitcnt vmcnt(8)
	s_waitcnt lgkmcnt(0)
	s_barrier
	s_setprio 1
	v_mfma_f32_16x16x32_bf16 v[52:55], v[176:179], v[202:205], v[52:55]
	v_mfma_f32_16x16x32_bf16 v[48:51], v[194:197], v[202:205], v[48:51]
	v_mfma_f32_16x16x32_bf16 v[36:39], v[176:179], v[210:213], v[36:39]
	v_mfma_f32_16x16x32_bf16 v[32:35], v[194:197], v[210:213], v[32:35]
	v_mfma_f32_16x16x32_bf16 v[20:23], v[176:179], v[218:221], v[20:23]
	v_mfma_f32_16x16x32_bf16 v[16:19], v[194:197], v[218:221], v[16:19]
	v_mfma_f32_16x16x32_bf16 v[4:7], v[176:179], v[226:229], v[4:7]
	v_mfma_f32_16x16x32_bf16 v[0:3], v[194:197], v[226:229], v[0:3]
	v_mfma_f32_16x16x32_bf16 v[52:55], v[190:193], v[206:209], v[52:55]
	v_mfma_f32_16x16x32_bf16 v[48:51], v[198:201], v[206:209], v[48:51]
	v_mfma_f32_16x16x32_bf16 v[36:39], v[190:193], v[214:217], v[36:39]
	v_mfma_f32_16x16x32_bf16 v[32:35], v[198:201], v[214:217], v[32:35]
	v_mfma_f32_16x16x32_bf16 v[20:23], v[190:193], v[222:225], v[20:23]
	v_mfma_f32_16x16x32_bf16 v[16:19], v[198:201], v[222:225], v[16:19]
	v_mfma_f32_16x16x32_bf16 v[4:7], v[190:193], v[230:233], v[4:7]
	v_mfma_f32_16x16x32_bf16 v[0:3], v[198:201], v[230:233], v[0:3]
	s_setprio 0
	s_barrier
	v_add_u32_e32 v142, 0x1c000, v160
	ds_read_b128 v[202:205], v162 offset:49152
	ds_read_b128 v[206:209], v162 offset:50176
	ds_read_b128 v[210:213], v162 offset:51200
	ds_read_b128 v[214:217], v162 offset:52224
	ds_read_b128 v[218:221], v162 offset:53248
	ds_read_b128 v[222:225], v162 offset:54272
	ds_read_b128 v[226:229], v162 offset:55296
	ds_read_b128 v[230:233], v162 offset:56320
	ds_read_b128 v[176:179], v142
	ds_read_b128 v[190:193], v142 offset:1024
	ds_read_b128 v[194:197], v142 offset:2048
	ds_read_b128 v[198:201], v142 offset:3072
	s_waitcnt vmcnt(4)
	s_waitcnt lgkmcnt(0)
	s_barrier
	s_setprio 1
	v_mfma_f32_16x16x32_bf16 v[52:55], v[176:179], v[202:205], v[52:55]
	v_mfma_f32_16x16x32_bf16 v[48:51], v[194:197], v[202:205], v[48:51]
	v_mfma_f32_16x16x32_bf16 v[36:39], v[176:179], v[210:213], v[36:39]
	v_mfma_f32_16x16x32_bf16 v[32:35], v[194:197], v[210:213], v[32:35]
	v_mfma_f32_16x16x32_bf16 v[20:23], v[176:179], v[218:221], v[20:23]
	v_mfma_f32_16x16x32_bf16 v[16:19], v[194:197], v[218:221], v[16:19]
	v_mfma_f32_16x16x32_bf16 v[4:7], v[176:179], v[226:229], v[4:7]
	v_mfma_f32_16x16x32_bf16 v[0:3], v[194:197], v[226:229], v[0:3]
	v_mfma_f32_16x16x32_bf16 v[52:55], v[190:193], v[206:209], v[52:55]
	v_mfma_f32_16x16x32_bf16 v[48:51], v[198:201], v[206:209], v[48:51]
	v_mfma_f32_16x16x32_bf16 v[36:39], v[190:193], v[214:217], v[36:39]
	v_mfma_f32_16x16x32_bf16 v[32:35], v[198:201], v[214:217], v[32:35]
	v_mfma_f32_16x16x32_bf16 v[20:23], v[190:193], v[222:225], v[20:23]
	v_mfma_f32_16x16x32_bf16 v[16:19], v[198:201], v[222:225], v[16:19]
	v_mfma_f32_16x16x32_bf16 v[4:7], v[190:193], v[230:233], v[4:7]
	v_mfma_f32_16x16x32_bf16 v[0:3], v[198:201], v[230:233], v[0:3]
	s_setprio 0
	s_barrier
	v_add_u32_e32 v142, 0x10000, v160
	ds_read_b128 v[202:205], v162 offset:0
	ds_read_b128 v[206:209], v162 offset:1024
	ds_read_b128 v[210:213], v162 offset:2048
	ds_read_b128 v[214:217], v162 offset:3072
	ds_read_b128 v[218:221], v162 offset:4096
	ds_read_b128 v[222:225], v162 offset:5120
	ds_read_b128 v[226:229], v162 offset:6144
	ds_read_b128 v[230:233], v162 offset:7168
	ds_read_b128 v[176:179], v142
	ds_read_b128 v[190:193], v142 offset:1024
	ds_read_b128 v[194:197], v142 offset:2048
	ds_read_b128 v[198:201], v142 offset:3072
	s_waitcnt vmcnt(0)
	s_waitcnt lgkmcnt(0)
	s_barrier
	s_setprio 1
	v_mfma_f32_16x16x32_bf16 v[52:55], v[176:179], v[202:205], v[52:55]
	v_mfma_f32_16x16x32_bf16 v[48:51], v[194:197], v[202:205], v[48:51]
	v_mfma_f32_16x16x32_bf16 v[36:39], v[176:179], v[210:213], v[36:39]
	v_mfma_f32_16x16x32_bf16 v[32:35], v[194:197], v[210:213], v[32:35]
	v_mfma_f32_16x16x32_bf16 v[20:23], v[176:179], v[218:221], v[20:23]
	v_mfma_f32_16x16x32_bf16 v[16:19], v[194:197], v[218:221], v[16:19]
	v_mfma_f32_16x16x32_bf16 v[4:7], v[176:179], v[226:229], v[4:7]
	v_mfma_f32_16x16x32_bf16 v[0:3], v[194:197], v[226:229], v[0:3]
	v_mfma_f32_16x16x32_bf16 v[52:55], v[190:193], v[206:209], v[52:55]
	v_mfma_f32_16x16x32_bf16 v[48:51], v[198:201], v[206:209], v[48:51]
	v_mfma_f32_16x16x32_bf16 v[36:39], v[190:193], v[214:217], v[36:39]
	v_mfma_f32_16x16x32_bf16 v[32:35], v[198:201], v[214:217], v[32:35]
	v_mfma_f32_16x16x32_bf16 v[20:23], v[190:193], v[222:225], v[20:23]
	v_mfma_f32_16x16x32_bf16 v[16:19], v[198:201], v[222:225], v[16:19]
	v_mfma_f32_16x16x32_bf16 v[4:7], v[190:193], v[230:233], v[4:7]
	v_mfma_f32_16x16x32_bf16 v[0:3], v[198:201], v[230:233], v[0:3]
	s_setprio 0
	s_barrier
	v_add_u32_e32 v142, 0x18000, v160
	ds_read_b128 v[202:205], v162 offset:32768
	ds_read_b128 v[206:209], v162 offset:33792
	ds_read_b128 v[210:213], v162 offset:34816
	ds_read_b128 v[214:217], v162 offset:35840
	ds_read_b128 v[218:221], v162 offset:36864
	ds_read_b128 v[222:225], v162 offset:37888
	ds_read_b128 v[226:229], v162 offset:38912
	ds_read_b128 v[230:233], v162 offset:39936
	ds_read_b128 v[176:179], v142
	ds_read_b128 v[190:193], v142 offset:1024
	ds_read_b128 v[194:197], v142 offset:2048
	ds_read_b128 v[198:201], v142 offset:3072
	s_waitcnt lgkmcnt(0)
	s_barrier
	s_setprio 1
	v_mfma_f32_16x16x32_bf16 v[52:55], v[176:179], v[202:205], v[52:55]
	v_mfma_f32_16x16x32_bf16 v[48:51], v[194:197], v[202:205], v[48:51]
	v_mfma_f32_16x16x32_bf16 v[36:39], v[176:179], v[210:213], v[36:39]
	v_mfma_f32_16x16x32_bf16 v[32:35], v[194:197], v[210:213], v[32:35]
	v_mfma_f32_16x16x32_bf16 v[20:23], v[176:179], v[218:221], v[20:23]
	v_mfma_f32_16x16x32_bf16 v[16:19], v[194:197], v[218:221], v[16:19]
	v_mfma_f32_16x16x32_bf16 v[4:7], v[176:179], v[226:229], v[4:7]
	v_mfma_f32_16x16x32_bf16 v[0:3], v[194:197], v[226:229], v[0:3]
	v_mfma_f32_16x16x32_bf16 v[52:55], v[190:193], v[206:209], v[52:55]
	v_mfma_f32_16x16x32_bf16 v[48:51], v[198:201], v[206:209], v[48:51]
	v_mfma_f32_16x16x32_bf16 v[36:39], v[190:193], v[214:217], v[36:39]
	v_mfma_f32_16x16x32_bf16 v[32:35], v[198:201], v[214:217], v[32:35]
	v_mfma_f32_16x16x32_bf16 v[20:23], v[190:193], v[222:225], v[20:23]
	v_mfma_f32_16x16x32_bf16 v[16:19], v[198:201], v[222:225], v[16:19]
	v_mfma_f32_16x16x32_bf16 v[4:7], v[190:193], v[230:233], v[4:7]
	v_mfma_f32_16x16x32_bf16 v[0:3], v[198:201], v[230:233], v[0:3]
	s_setprio 0
	s_barrier
	s_branch .Lq_abi_exit
